# MFMA-VALU interleave in gdn_prep stage C: the f32 MFMAs of the off-diagonal block are issued k-step by k-step inside the first 32 substitution rows (operand copies + permlane32_swap), so the matrix pi
# speedup vs baseline: 1.0027x; 1.0027x over previous
; __device__ __forceinline__ float bf2f(bf16 v) { return __uint_as_float(((unsigned)v) << 16); }
; #define GDN_LOADROW(buf, rr_, i_) do { _Pragma("unroll") for (int j4 = 0; j4 < ((i_) + 3) / 4; ++j4) buf[j4] = *(const f32x4*)(Lm + (i_) * GP_LSTR + 4 * j4); rr_ = bf2f(*(const bf16*)(xsrc + (i_) * GP_STR * 2)) * scl[i_]; } while (0)
; template <int STRIP> __device__ __forceinline__ void ph_gdn_prep_fast(const bf16* __restrict__ proj, const float* __restrict__ small, const float* __restrict__ conv_w, const float* __restrict__ a_log, const float* __restrict__ dt_bias, ...
;     ...
;             const int cs = wave >> 2, ci = 2 * pair + cs;
;             unsigned char* L = lds_dyn + cs * GP_CHUNK; const float* sgc = (const float*)(L + GP_SC); const float* sbeta = sgc + 64; const float* segc = sgc + 128; const float* sekd = sgc + 192;
;             const int c = (wave & 3) * 64 + lane; const bool isw = c >= 128; const int cc = c & 127;
;             const unsigned char* xsrc = L + (isw ? GP_K : GP_V) + cc * 2;
;             const float* Lm = (const float*)(L + GP_L);
;             float U[64];
;             const float* scl = isw ? (sgc + 256) : sbeta;
;             f32x4 bA[16], bB[16]; float rA, rB = 0.f;
;             rA = bf2f(*(const bf16*)xsrc) * scl[0];
;     ...
; #pragma unroll
;             for (int i = 0; i < 64; i += 2) {
;                 GDN_LOADROW(bB, rB, i + 1);
;                 GDN_ROW(bA, rA, i);
;                 if (i + 2 < 64) GDN_LOADROW(bA, rA, i + 2);
;                 GDN_ROW(bB, rB, i + 1);
.LBB0_1303:
	s_or_b64 exec, exec, s[8:9]
	v_ashrrev_i32_e32 v8, 8, v78
	s_mov_b32 s0, 0x11500
	v_and_b32_e32 v4, 0x80, v78
	v_and_b32_e32 v2, 0x80, v78
	v_mad_i32_i24 v10, v8, s0, 0
	v_cmp_ne_u32_e32 vcc, 0, v2
	v_and_b32_e32 v2, 0x7f, v78
	v_cmp_eq_u32_e64 s[0:1], 0, v4
	v_mov_b32_e32 v4, 0x8800
	v_lshlrev_b32_e32 v18, 1, v2
	v_cndmask_b32_e64 v4, v236, v4, s[0:1]
	s_waitcnt lgkmcnt(0)
	s_barrier
	v_add3_u32 v123, v10, v4, v18
	v_mov_b32_e32 v126, 0x11400
	v_mov_b32_e32 v127, 0x11100
	v_and_b32_e32 v125, 3, v78
	v_cndmask_b32_e64 v126, v126, v127, s[0:1]
	v_lshlrev_b32_e32 v125, 3, v125
	v_add_u32_e32 v124, v10, v126
	v_add_u32_e32 v125, 0xcc00, v125
	v_add_u32_e32 v125, v10, v125
	v_and_b32_e32 v130, 31, v78
	v_bfe_u32 v127, v78, 5, 1
	v_add_u32_e32 v130, 32, v130
	v_mul_u32_u24_e32 v130, 0x110, v130
	v_lshl_add_u32 v130, v127, 2, v130
	v_add_u32_e32 v130, 0xcc00, v130
	v_add_u32_e32 v130, v10, v130
	ds_read_b32 v172, v130 offset:0
	ds_read_b32 v173, v130 offset:8
	ds_read_b32 v174, v130 offset:16
	ds_read_b32 v175, v130 offset:24
	ds_read_b32 v176, v130 offset:32
	ds_read_b32 v177, v130 offset:40
	ds_read_b32 v178, v130 offset:48
	ds_read_b32 v179, v130 offset:56
	ds_read_b32 v222, v130 offset:64
	ds_read_b32 v223, v130 offset:72
	ds_read_b32 v224, v130 offset:80
	ds_read_b32 v225, v130 offset:88
	ds_read_b32 v226, v130 offset:96
	ds_read_b32 v227, v130 offset:104
	ds_read_b32 v228, v130 offset:112
	ds_read_b32 v229, v130 offset:120
	v_mov_b32_e32 v244, 0
	v_mov_b32_e32 v245, 0
	v_mov_b32_e32 v246, 0
	v_mov_b32_e32 v247, 0
	v_mov_b32_e32 v248, 0
	v_mov_b32_e32 v249, 0
	v_mov_b32_e32 v250, 0
	v_mov_b32_e32 v251, 0
	v_mov_b32_e32 v252, 0
	v_mov_b32_e32 v253, 0
	v_mov_b32_e32 v126, 0
	v_mov_b32_e32 v127, 0
	ds_read_b32 v208, v124 offset:0
	ds_read_u16_d16_hi v244, v123 offset:0
	ds_read_b64 v[186:187], v125 offset:272
	ds_read_b32 v209, v124 offset:4
	ds_read_u16_d16_hi v245, v123 offset:272
	ds_read_b64 v[188:189], v125 offset:544
	ds_read_b32 v210, v124 offset:8
	ds_read_u16_d16_hi v246, v123 offset:544
	ds_read_b64 v[190:191], v125 offset:816
	ds_read_b32 v211, v124 offset:12
	ds_read_u16_d16_hi v247, v123 offset:816
	ds_read_b64 v[192:193], v125 offset:1088
	ds_read_b32 v212, v124 offset:16
	ds_read_u16_d16_hi v248, v123 offset:1088
	ds_read_b64 v[194:195], v125 offset:1360
	ds_read_b32 v213, v124 offset:20
	ds_read_u16_d16_hi v249, v123 offset:1360
	ds_read_b64 v[196:197], v125 offset:1632
	ds_read_b32 v214, v124 offset:24
	ds_read_u16_d16_hi v250, v123 offset:1632
	ds_read_b64 v[198:199], v125 offset:1904
	ds_read_b32 v215, v124 offset:28
	ds_read_u16_d16_hi v251, v123 offset:1904
	ds_read_b64 v[200:201], v125 offset:2176
	ds_read_b32 v216, v124 offset:32
	ds_read_u16_d16_hi v252, v123 offset:2176
	ds_read_b64 v[202:203], v125 offset:2448
	ds_read_b64 v[204:205], v125 offset:2480
	ds_read_b32 v217, v124 offset:36
	ds_read_u16_d16_hi v253, v123 offset:2448
	ds_read_b64 v[206:207], v125 offset:2720
	ds_read_b64 v[164:165], v125 offset:2752
	ds_read_b32 v218, v124 offset:40
	ds_read_u16_d16_hi v126, v123 offset:2720
	s_waitcnt lgkmcnt(15)
	v_fma_f32 v4, v208, v244, 0
	s_waitcnt lgkmcnt(15)
	v_mul_f32_dpp v120, v186, v4 quad_perm:[0,0,0,0] row_mask:0xf bank_mask:0xf
	v_fma_f32 v116, v209, v245, -v120
	v_add_f32_e32 v5, 0, v116
	v_mov_b32_e32 v128, v4
	v_mov_b32_e32 v129, v5
	s_waitcnt lgkmcnt(15)
	v_mul_f32_dpp v120, v188, v4 quad_perm:[0,0,0,0] row_mask:0xf bank_mask:0xf
	v_fma_f32 v116, v210, v246, -v120
	v_permlane32_swap_b32_e32 v128, v129
	v_mul_f32_dpp v117, -v189, v5 quad_perm:[0,0,0,0] row_mask:0xf bank_mask:0xf
	v_add_f32_e32 v6, v117, v116
	v_mfma_f32_32x32x2_f32 v[132:147], v172, v128, 0
	s_waitcnt lgkmcnt(15)
	v_mul_f32_dpp v120, v190, v4 quad_perm:[0,0,0,0] row_mask:0xf bank_mask:0xf
	v_fma_f32 v116, v211, v247, -v120
	v_mul_f32_dpp v117, -v191, v5 quad_perm:[0,0,0,0] row_mask:0xf bank_mask:0xf
	v_mul_f32_dpp v118, -v190, v6 quad_perm:[1,1,1,1] row_mask:0xf bank_mask:0xf
	ds_read_b64 v[166:167], v125 offset:2992
	v_add_f32_e32 v121, v117, v116
	v_add_f32_e32 v12, v118, v121
	v_mov_b32_e32 v220, v6
	v_mov_b32_e32 v221, v12
	s_waitcnt lgkmcnt(15)
	v_mul_f32_dpp v120, v192, v4 quad_perm:[0,0,0,0] row_mask:0xf bank_mask:0xf
	v_fma_f32 v116, v212, v248, -v120
	v_permlane32_swap_b32_e32 v220, v221
	v_mul_f32_dpp v117, -v193, v5 quad_perm:[0,0,0,0] row_mask:0xf bank_mask:0xf
	v_mul_f32_dpp v118, -v192, v6 quad_perm:[1,1,1,1] row_mask:0xf bank_mask:0xf
	v_mfma_f32_32x32x2_f32 v[132:147], v173, v220, v[132:147]
	v_mul_f32_dpp v119, -v193, v12 quad_perm:[1,1,1,1] row_mask:0xf bank_mask:0xf
	ds_read_b64 v[168:169], v125 offset:3024
	v_add_f32_e32 v121, v117, v116
	v_add_f32_e32 v122, v118, v119
	v_add_f32_e32 v7, v122, v121
	s_waitcnt lgkmcnt(15)
	v_mul_f32_dpp v120, v194, v4 quad_perm:[0,0,0,0] row_mask:0xf bank_mask:0xf
	v_fma_f32 v116, v213, v249, -v120
	v_mfma_f32_32x32x2_f32 v[148:163], v172, v129, 0
	v_mul_f32_dpp v117, -v195, v5 quad_perm:[0,0,0,0] row_mask:0xf bank_mask:0xf
	v_mul_f32_dpp v118, -v194, v6 quad_perm:[1,1,1,1] row_mask:0xf bank_mask:0xf
	v_mul_f32_dpp v119, -v195, v12 quad_perm:[1,1,1,1] row_mask:0xf bank_mask:0xf
	ds_read_b32 v219, v124 offset:44
	v_fmac_f32_dpp v116, -v194, v7 quad_perm:[2,2,2,2] row_mask:0xf bank_mask:0xf
	v_add_f32_e32 v121, v117, v116
	v_add_f32_e32 v122, v118, v119
	v_add_f32_e32 v13, v122, v121
	v_mov_b32_e32 v128, v7
	v_mov_b32_e32 v129, v13
	s_waitcnt lgkmcnt(15)
; #define GDN_LOADROW(buf, rr_, i_) do { _Pragma("unroll") for (int j4 = 0; j4 < ((i_) + 3) / 4; ++j4) buf[j4] = *(const f32x4*)(Lm + (i_) * GP_LSTR + 4 * j4); rr_ = bf2f(*(const bf16*)(xsrc + (i_) * GP_STR * 2)) * scl[i_]; } while (0)
; template <int STRIP> __device__ __forceinline__ void ph_gdn_prep_fast(const bf16* __restrict__ proj, const float* __restrict__ small, const float* __restrict__ conv_w, const float* __restrict__ a_log, const float* __restrict__ dt_bias, ...
;     ...
; #pragma unroll
;             for (int i = 0; i < 64; i += 2) {
;                 GDN_LOADROW(bB, rB, i + 1);
;                 GDN_ROW(bA, rA, i);
;                 if (i + 2 < 64) GDN_LOADROW(bA, rA, i + 2);
;                 GDN_ROW(bB, rB, i + 1);
;             }
	v_mul_f32_dpp v120, v196, v4 quad_perm:[0,0,0,0] row_mask:0xf bank_mask:0xf
	v_fma_f32 v116, v214, v250, -v120
	v_permlane32_swap_b32_e32 v128, v129
	v_mul_f32_dpp v117, -v197, v5 quad_perm:[0,0,0,0] row_mask:0xf bank_mask:0xf
	v_mfma_f32_32x32x2_f32 v[148:163], v173, v221, v[148:163]
	v_mul_f32_dpp v118, -v196, v6 quad_perm:[1,1,1,1] row_mask:0xf bank_mask:0xf
	v_mfma_f32_32x32x2_f32 v[132:147], v174, v128, v[132:147]
	ds_read_u16_d16_hi v127, v123 offset:2992
	v_mul_f32_dpp v119, -v197, v12 quad_perm:[1,1,1,1] row_mask:0xf bank_mask:0xf
	v_fmac_f32_dpp v116, -v196, v7 quad_perm:[2,2,2,2] row_mask:0xf bank_mask:0xf
	v_fmac_f32_dpp v117, -v197, v13 quad_perm:[2,2,2,2] row_mask:0xf bank_mask:0xf
	ds_read_b64 v[170:171], v125 offset:3264
	v_add_f32_e32 v121, v117, v116
	v_add_f32_e32 v122, v118, v119
	v_add_f32_e32 v14, v122, v121
	s_waitcnt lgkmcnt(15)
	v_mul_f32_dpp v120, v198, v4 quad_perm:[0,0,0,0] row_mask:0xf bank_mask:0xf
	v_fma_f32 v116, v215, v251, -v120
	v_mul_f32_dpp v117, -v199, v5 quad_perm:[0,0,0,0] row_mask:0xf bank_mask:0xf
	v_mul_f32_dpp v118, -v198, v6 quad_perm:[1,1,1,1] row_mask:0xf bank_mask:0xf
	v_mul_f32_dpp v119, -v199, v12 quad_perm:[1,1,1,1] row_mask:0xf bank_mask:0xf
	ds_read_b64 v[84:85], v125 offset:3296
	v_fmac_f32_dpp v116, -v198, v7 quad_perm:[2,2,2,2] row_mask:0xf bank_mask:0xf
	v_fmac_f32_dpp v117, -v199, v13 quad_perm:[2,2,2,2] row_mask:0xf bank_mask:0xf
	v_fmac_f32_dpp v118, -v198, v14 quad_perm:[3,3,3,3] row_mask:0xf bank_mask:0xf
	ds_read_b32 v181, v124 offset:48
	v_add_f32_e32 v121, v117, v116
	v_add_f32_e32 v122, v118, v119
	v_mfma_f32_32x32x2_f32 v[148:163], v174, v129, v[148:163]
	v_add_f32_e32 v15, v122, v121
	v_mov_b32_e32 v220, v14
	v_mov_b32_e32 v221, v15
	s_waitcnt lgkmcnt(15)
	v_mul_f32_dpp v120, v200, v4 quad_perm:[0,0,0,0] row_mask:0xf bank_mask:0xf
	v_fma_f32 v116, v216, v252, -v120
	v_permlane32_swap_b32_e32 v220, v221
	v_mul_f32_dpp v117, -v201, v5 quad_perm:[0,0,0,0] row_mask:0xf bank_mask:0xf
	v_mul_f32_dpp v118, -v200, v6 quad_perm:[1,1,1,1] row_mask:0xf bank_mask:0xf
	v_mfma_f32_32x32x2_f32 v[132:147], v175, v220, v[132:147]
	v_mul_f32_dpp v119, -v201, v12 quad_perm:[1,1,1,1] row_mask:0xf bank_mask:0xf
	ds_read_u16_d16_hi v244, v123 offset:3264
	v_fmac_f32_dpp v116, -v200, v7 quad_perm:[2,2,2,2] row_mask:0xf bank_mask:0xf
	v_fmac_f32_dpp v117, -v201, v13 quad_perm:[2,2,2,2] row_mask:0xf bank_mask:0xf
	v_fmac_f32_dpp v118, -v200, v14 quad_perm:[3,3,3,3] row_mask:0xf bank_mask:0xf
	ds_read_b64 v[86:87], v125 offset:3536
	v_fmac_f32_dpp v119, -v201, v15 quad_perm:[3,3,3,3] row_mask:0xf bank_mask:0xf
	v_add_f32_e32 v121, v117, v116
	v_add_f32_e32 v122, v118, v119
	v_add_f32_e32 v16, v122, v121
	s_waitcnt lgkmcnt(13)
	v_mul_f32_dpp v120, v202, v4 quad_perm:[0,0,0,0] row_mask:0xf bank_mask:0xf
	v_fma_f32 v116, v217, v253, -v120
	v_mul_f32_dpp v117, -v203, v5 quad_perm:[0,0,0,0] row_mask:0xf bank_mask:0xf
	v_mul_f32_dpp v118, -v202, v6 quad_perm:[1,1,1,1] row_mask:0xf bank_mask:0xf
	ds_read_b64 v[88:89], v125 offset:3568
	v_mul_f32_dpp v119, -v203, v12 quad_perm:[1,1,1,1] row_mask:0xf bank_mask:0xf
	v_fmac_f32_dpp v116, -v202, v7 quad_perm:[2,2,2,2] row_mask:0xf bank_mask:0xf
	v_fmac_f32_dpp v117, -v203, v13 quad_perm:[2,2,2,2] row_mask:0xf bank_mask:0xf
	ds_read_b32 v182, v124 offset:52
	v_fmac_f32_dpp v118, -v202, v14 quad_perm:[3,3,3,3] row_mask:0xf bank_mask:0xf
	v_mfma_f32_32x32x2_f32 v[148:163], v175, v221, v[148:163]
	v_fmac_f32_dpp v119, -v203, v15 quad_perm:[3,3,3,3] row_mask:0xf bank_mask:0xf
	v_fmac_f32_dpp v116, -v204, v16 quad_perm:[0,0,0,0] row_mask:0xf bank_mask:0xf
	ds_read_u16_d16_hi v245, v123 offset:3536
	v_add_f32_e32 v121, v117, v116
	v_add_f32_e32 v122, v118, v119
	v_add_f32_e32 v17, v122, v121
	v_mov_b32_e32 v128, v16
	v_mov_b32_e32 v129, v17
	s_waitcnt lgkmcnt(12)
	v_mul_f32_dpp v120, v206, v4 quad_perm:[0,0,0,0] row_mask:0xf bank_mask:0xf
	v_fma_f32 v116, v218, v126, -v120
	v_permlane32_swap_b32_e32 v128, v129
	v_mul_f32_dpp v117, -v207, v5 quad_perm:[0,0,0,0] row_mask:0xf bank_mask:0xf
	v_mul_f32_dpp v118, -v206, v6 quad_perm:[1,1,1,1] row_mask:0xf bank_mask:0xf
	v_mfma_f32_32x32x2_f32 v[132:147], v176, v128, v[132:147]
	v_mul_f32_dpp v119, -v207, v12 quad_perm:[1,1,1,1] row_mask:0xf bank_mask:0xf
	ds_read_b64 v[90:91], v125 offset:3808
	v_fmac_f32_dpp v116, -v206, v7 quad_perm:[2,2,2,2] row_mask:0xf bank_mask:0xf
	v_fmac_f32_dpp v117, -v207, v13 quad_perm:[2,2,2,2] row_mask:0xf bank_mask:0xf
	v_fmac_f32_dpp v118, -v206, v14 quad_perm:[3,3,3,3] row_mask:0xf bank_mask:0xf
	ds_read_b64 v[92:93], v125 offset:3840
	v_fmac_f32_dpp v119, -v207, v15 quad_perm:[3,3,3,3] row_mask:0xf bank_mask:0xf
	v_fmac_f32_dpp v116, -v164, v16 quad_perm:[0,0,0,0] row_mask:0xf bank_mask:0xf
	v_fmac_f32_dpp v117, -v165, v17 quad_perm:[0,0,0,0] row_mask:0xf bank_mask:0xf
	ds_read_b32 v183, v124 offset:56
	v_add_f32_e32 v121, v117, v116
	v_add_f32_e32 v122, v118, v119
	v_add_f32_e32 v19, v122, v121
	s_waitcnt lgkmcnt(11)
	v_mul_f32_dpp v120, v166, v4 quad_perm:[0,0,0,0] row_mask:0xf bank_mask:0xf
	v_fma_f32 v116, v219, v127, -v120
	v_mul_f32_dpp v117, -v167, v5 quad_perm:[0,0,0,0] row_mask:0xf bank_mask:0xf
	v_mul_f32_dpp v118, -v166, v6 quad_perm:[1,1,1,1] row_mask:0xf bank_mask:0xf
	v_mul_f32_dpp v119, -v167, v12 quad_perm:[1,1,1,1] row_mask:0xf bank_mask:0xf
	ds_read_u16_d16_hi v246, v123 offset:3808
	v_fmac_f32_dpp v116, -v166, v7 quad_perm:[2,2,2,2] row_mask:0xf bank_mask:0xf
	v_mfma_f32_32x32x2_f32 v[148:163], v176, v129, v[148:163]
	v_fmac_f32_dpp v117, -v167, v13 quad_perm:[2,2,2,2] row_mask:0xf bank_mask:0xf
	v_fmac_f32_dpp v118, -v166, v14 quad_perm:[3,3,3,3] row_mask:0xf bank_mask:0xf
	ds_read_b64 v[186:187], v125 offset:4080
	v_fmac_f32_dpp v119, -v167, v15 quad_perm:[3,3,3,3] row_mask:0xf bank_mask:0xf
	v_fmac_f32_dpp v116, -v168, v16 quad_perm:[0,0,0,0] row_mask:0xf bank_mask:0xf
	v_fmac_f32_dpp v117, -v169, v17 quad_perm:[0,0,0,0] row_mask:0xf bank_mask:0xf
	ds_read_b64 v[188:189], v125 offset:4112
	v_fmac_f32_dpp v118, -v168, v19 quad_perm:[1,1,1,1] row_mask:0xf bank_mask:0xf
	v_add_f32_e32 v121, v117, v116
	v_add_f32_e32 v122, v118, v119
	v_add_f32_e32 v20, v122, v121
	v_mov_b32_e32 v220, v19
	v_mov_b32_e32 v221, v20
	s_waitcnt lgkmcnt(10)
; #define GDN_LOADROW(buf, rr_, i_) do { _Pragma("unroll") for (int j4 = 0; j4 < ((i_) + 3) / 4; ++j4) buf[j4] = *(const f32x4*)(Lm + (i_) * GP_LSTR + 4 * j4); rr_ = bf2f(*(const bf16*)(xsrc + (i_) * GP_STR * 2)) * scl[i_]; } while (0)
; template <int STRIP> __device__ __forceinline__ void ph_gdn_prep_fast(const bf16* __restrict__ proj, const float* __restrict__ small, const float* __restrict__ conv_w, const float* __restrict__ a_log, const float* __restrict__ dt_bias, ...
;     ...
; #pragma unroll
;             for (int i = 0; i < 64; i += 2) {
;                 GDN_LOADROW(bB, rB, i + 1);
;                 GDN_ROW(bA, rA, i);
;                 if (i + 2 < 64) GDN_LOADROW(bA, rA, i + 2);
;                 GDN_ROW(bB, rB, i + 1);
;             }
	v_mul_f32_dpp v120, v170, v4 quad_perm:[0,0,0,0] row_mask:0xf bank_mask:0xf
	v_fma_f32 v116, v181, v244, -v120
	v_permlane32_swap_b32_e32 v220, v221
	v_mul_f32_dpp v117, -v171, v5 quad_perm:[0,0,0,0] row_mask:0xf bank_mask:0xf
	v_mul_f32_dpp v118, -v170, v6 quad_perm:[1,1,1,1] row_mask:0xf bank_mask:0xf
	v_mfma_f32_32x32x2_f32 v[132:147], v177, v220, v[132:147]
	ds_read_b32 v185, v124 offset:60
	v_mul_f32_dpp v119, -v171, v12 quad_perm:[1,1,1,1] row_mask:0xf bank_mask:0xf
	v_fmac_f32_dpp v116, -v170, v7 quad_perm:[2,2,2,2] row_mask:0xf bank_mask:0xf
	v_fmac_f32_dpp v117, -v171, v13 quad_perm:[2,2,2,2] row_mask:0xf bank_mask:0xf
	ds_read_u16_d16_hi v247, v123 offset:4080
	v_fmac_f32_dpp v118, -v170, v14 quad_perm:[3,3,3,3] row_mask:0xf bank_mask:0xf
	v_fmac_f32_dpp v119, -v171, v15 quad_perm:[3,3,3,3] row_mask:0xf bank_mask:0xf
	v_fmac_f32_dpp v116, -v84, v16 quad_perm:[0,0,0,0] row_mask:0xf bank_mask:0xf
	ds_read_b64 v[190:191], v125 offset:4352
	v_fmac_f32_dpp v117, -v85, v17 quad_perm:[0,0,0,0] row_mask:0xf bank_mask:0xf
	v_fmac_f32_dpp v118, -v84, v19 quad_perm:[1,1,1,1] row_mask:0xf bank_mask:0xf
	v_fmac_f32_dpp v119, -v85, v20 quad_perm:[1,1,1,1] row_mask:0xf bank_mask:0xf
	ds_read_b64 v[192:193], v125 offset:4384
	v_add_f32_e32 v121, v117, v116
	v_add_f32_e32 v122, v118, v119
	v_add_f32_e32 v21, v122, v121
	s_waitcnt lgkmcnt(10)
	v_mul_f32_dpp v120, v86, v4 quad_perm:[0,0,0,0] row_mask:0xf bank_mask:0xf
	v_fma_f32 v116, v182, v245, -v120
	v_mul_f32_dpp v117, -v87, v5 quad_perm:[0,0,0,0] row_mask:0xf bank_mask:0xf
	v_mul_f32_dpp v118, -v86, v6 quad_perm:[1,1,1,1] row_mask:0xf bank_mask:0xf
	v_mfma_f32_32x32x2_f32 v[148:163], v177, v221, v[148:163]
	v_mul_f32_dpp v119, -v87, v12 quad_perm:[1,1,1,1] row_mask:0xf bank_mask:0xf
	ds_read_b32 v208, v124 offset:64
	v_fmac_f32_dpp v116, -v86, v7 quad_perm:[2,2,2,2] row_mask:0xf bank_mask:0xf
	v_fmac_f32_dpp v117, -v87, v13 quad_perm:[2,2,2,2] row_mask:0xf bank_mask:0xf
	v_fmac_f32_dpp v118, -v86, v14 quad_perm:[3,3,3,3] row_mask:0xf bank_mask:0xf
	ds_read_u16_d16_hi v248, v123 offset:4352
	v_fmac_f32_dpp v119, -v87, v15 quad_perm:[3,3,3,3] row_mask:0xf bank_mask:0xf
	v_fmac_f32_dpp v116, -v88, v16 quad_perm:[0,0,0,0] row_mask:0xf bank_mask:0xf
	v_fmac_f32_dpp v117, -v89, v17 quad_perm:[0,0,0,0] row_mask:0xf bank_mask:0xf
	ds_read_b64 v[194:195], v125 offset:4624
	v_fmac_f32_dpp v118, -v88, v19 quad_perm:[1,1,1,1] row_mask:0xf bank_mask:0xf
	v_fmac_f32_dpp v119, -v89, v20 quad_perm:[1,1,1,1] row_mask:0xf bank_mask:0xf
	v_fmac_f32_dpp v116, -v88, v21 quad_perm:[2,2,2,2] row_mask:0xf bank_mask:0xf
	ds_read_b64 v[196:197], v125 offset:4656
	v_add_f32_e32 v121, v117, v116
	v_add_f32_e32 v122, v118, v119
	v_add_f32_e32 v22, v122, v121
	v_mov_b32_e32 v128, v21
	v_mov_b32_e32 v129, v22
	s_waitcnt lgkmcnt(10)
	v_mul_f32_dpp v120, v90, v4 quad_perm:[0,0,0,0] row_mask:0xf bank_mask:0xf
	v_fma_f32 v116, v183, v246, -v120
	v_permlane32_swap_b32_e32 v128, v129
	v_mul_f32_dpp v117, -v91, v5 quad_perm:[0,0,0,0] row_mask:0xf bank_mask:0xf
	v_mul_f32_dpp v118, -v90, v6 quad_perm:[1,1,1,1] row_mask:0xf bank_mask:0xf
	v_mfma_f32_32x32x2_f32 v[132:147], v178, v128, v[132:147]
	v_mul_f32_dpp v119, -v91, v12 quad_perm:[1,1,1,1] row_mask:0xf bank_mask:0xf
	ds_read_b64 v[198:199], v125 offset:4688
	v_fmac_f32_dpp v116, -v90, v7 quad_perm:[2,2,2,2] row_mask:0xf bank_mask:0xf
	v_fmac_f32_dpp v117, -v91, v13 quad_perm:[2,2,2,2] row_mask:0xf bank_mask:0xf
	v_fmac_f32_dpp v118, -v90, v14 quad_perm:[3,3,3,3] row_mask:0xf bank_mask:0xf
	ds_read_b32 v209, v124 offset:68
	v_fmac_f32_dpp v119, -v91, v15 quad_perm:[3,3,3,3] row_mask:0xf bank_mask:0xf
	v_fmac_f32_dpp v116, -v92, v16 quad_perm:[0,0,0,0] row_mask:0xf bank_mask:0xf
	v_fmac_f32_dpp v117, -v93, v17 quad_perm:[0,0,0,0] row_mask:0xf bank_mask:0xf
	ds_read_u16_d16_hi v249, v123 offset:4624
	v_fmac_f32_dpp v118, -v92, v19 quad_perm:[1,1,1,1] row_mask:0xf bank_mask:0xf
	v_fmac_f32_dpp v119, -v93, v20 quad_perm:[1,1,1,1] row_mask:0xf bank_mask:0xf
	v_fmac_f32_dpp v116, -v92, v21 quad_perm:[2,2,2,2] row_mask:0xf bank_mask:0xf
	ds_read_b64 v[200:201], v125 offset:4896
	v_fmac_f32_dpp v117, -v93, v22 quad_perm:[2,2,2,2] row_mask:0xf bank_mask:0xf
	v_add_f32_e32 v121, v117, v116
	v_add_f32_e32 v122, v118, v119
	v_add_f32_e32 v23, v122, v121
	s_waitcnt lgkmcnt(10)
	v_mul_f32_dpp v120, v186, v4 quad_perm:[0,0,0,0] row_mask:0xf bank_mask:0xf
	v_fma_f32 v116, v185, v247, -v120
	v_mfma_f32_32x32x2_f32 v[148:163], v178, v129, v[148:163]
	v_mul_f32_dpp v117, -v187, v5 quad_perm:[0,0,0,0] row_mask:0xf bank_mask:0xf
	v_mul_f32_dpp v118, -v186, v6 quad_perm:[1,1,1,1] row_mask:0xf bank_mask:0xf
	ds_read_b64 v[202:203], v125 offset:4928
	v_mul_f32_dpp v119, -v187, v12 quad_perm:[1,1,1,1] row_mask:0xf bank_mask:0xf
	v_fmac_f32_dpp v116, -v186, v7 quad_perm:[2,2,2,2] row_mask:0xf bank_mask:0xf
	v_fmac_f32_dpp v117, -v187, v13 quad_perm:[2,2,2,2] row_mask:0xf bank_mask:0xf
	ds_read_b64 v[204:205], v125 offset:4960
	v_fmac_f32_dpp v118, -v186, v14 quad_perm:[3,3,3,3] row_mask:0xf bank_mask:0xf
	v_fmac_f32_dpp v119, -v187, v15 quad_perm:[3,3,3,3] row_mask:0xf bank_mask:0xf
	v_fmac_f32_dpp v116, -v188, v16 quad_perm:[0,0,0,0] row_mask:0xf bank_mask:0xf
	ds_read_b32 v210, v124 offset:72
	v_fmac_f32_dpp v117, -v189, v17 quad_perm:[0,0,0,0] row_mask:0xf bank_mask:0xf
	v_fmac_f32_dpp v118, -v188, v19 quad_perm:[1,1,1,1] row_mask:0xf bank_mask:0xf
	v_fmac_f32_dpp v119, -v189, v20 quad_perm:[1,1,1,1] row_mask:0xf bank_mask:0xf
	ds_read_u16_d16_hi v250, v123 offset:4896
	v_fmac_f32_dpp v116, -v188, v21 quad_perm:[2,2,2,2] row_mask:0xf bank_mask:0xf
	v_fmac_f32_dpp v117, -v189, v22 quad_perm:[2,2,2,2] row_mask:0xf bank_mask:0xf
	v_fmac_f32_dpp v118, -v188, v23 quad_perm:[3,3,3,3] row_mask:0xf bank_mask:0xf
	ds_read_b64 v[206:207], v125 offset:5168
	v_add_f32_e32 v121, v117, v116
	v_add_f32_e32 v122, v118, v119
	v_add_f32_e32 v24, v122, v121
	v_mov_b32_e32 v220, v23
	v_mov_b32_e32 v221, v24
	s_waitcnt lgkmcnt(11)
; #define GDN_LOADROW(buf, rr_, i_) do { _Pragma("unroll") for (int j4 = 0; j4 < ((i_) + 3) / 4; ++j4) buf[j4] = *(const f32x4*)(Lm + (i_) * GP_LSTR + 4 * j4); rr_ = bf2f(*(const bf16*)(xsrc + (i_) * GP_STR * 2)) * scl[i_]; } while (0)
; template <int STRIP> __device__ __forceinline__ void ph_gdn_prep_fast(const bf16* __restrict__ proj, const float* __restrict__ small, const float* __restrict__ conv_w, const float* __restrict__ a_log, const float* __restrict__ dt_bias, ...
;     ...
; #pragma unroll
;             for (int i = 0; i < 64; i += 2) {
;                 GDN_LOADROW(bB, rB, i + 1);
;                 GDN_ROW(bA, rA, i);
;                 if (i + 2 < 64) GDN_LOADROW(bA, rA, i + 2);
;                 GDN_ROW(bB, rB, i + 1);
;             }
	v_mul_f32_dpp v120, v190, v4 quad_perm:[0,0,0,0] row_mask:0xf bank_mask:0xf
	v_fma_f32 v116, v208, v248, -v120
	v_permlane32_swap_b32_e32 v220, v221
	v_mul_f32_dpp v117, -v191, v5 quad_perm:[0,0,0,0] row_mask:0xf bank_mask:0xf
	v_mul_f32_dpp v118, -v190, v6 quad_perm:[1,1,1,1] row_mask:0xf bank_mask:0xf
	v_mfma_f32_32x32x2_f32 v[132:147], v179, v220, v[132:147]
	v_mul_f32_dpp v119, -v191, v12 quad_perm:[1,1,1,1] row_mask:0xf bank_mask:0xf
	ds_read_b64 v[164:165], v125 offset:5200
	v_fmac_f32_dpp v116, -v190, v7 quad_perm:[2,2,2,2] row_mask:0xf bank_mask:0xf
	v_fmac_f32_dpp v117, -v191, v13 quad_perm:[2,2,2,2] row_mask:0xf bank_mask:0xf
	v_fmac_f32_dpp v118, -v190, v14 quad_perm:[3,3,3,3] row_mask:0xf bank_mask:0xf
	ds_read_b64 v[166:167], v125 offset:5232
	v_fmac_f32_dpp v119, -v191, v15 quad_perm:[3,3,3,3] row_mask:0xf bank_mask:0xf
	v_fmac_f32_dpp v116, -v192, v16 quad_perm:[0,0,0,0] row_mask:0xf bank_mask:0xf
	v_fmac_f32_dpp v117, -v193, v17 quad_perm:[0,0,0,0] row_mask:0xf bank_mask:0xf
	ds_read_b32 v211, v124 offset:76
	v_fmac_f32_dpp v118, -v192, v19 quad_perm:[1,1,1,1] row_mask:0xf bank_mask:0xf
	v_fmac_f32_dpp v119, -v193, v20 quad_perm:[1,1,1,1] row_mask:0xf bank_mask:0xf
	v_fmac_f32_dpp v116, -v192, v21 quad_perm:[2,2,2,2] row_mask:0xf bank_mask:0xf
	ds_read_u16_d16_hi v251, v123 offset:5168
	v_fmac_f32_dpp v117, -v193, v22 quad_perm:[2,2,2,2] row_mask:0xf bank_mask:0xf
	v_fmac_f32_dpp v118, -v192, v23 quad_perm:[3,3,3,3] row_mask:0xf bank_mask:0xf
	v_fmac_f32_dpp v119, -v193, v24 quad_perm:[3,3,3,3] row_mask:0xf bank_mask:0xf
	ds_read_b64 v[168:169], v125 offset:5440
	v_add_f32_e32 v121, v117, v116
	v_add_f32_e32 v122, v118, v119
	v_add_f32_e32 v25, v122, v121
	v_mfma_f32_32x32x2_f32 v[148:163], v179, v221, v[148:163]
	s_waitcnt lgkmcnt(11)
	v_mul_f32_dpp v120, v194, v4 quad_perm:[0,0,0,0] row_mask:0xf bank_mask:0xf
	v_fma_f32 v116, v209, v249, -v120
	v_mul_f32_dpp v117, -v195, v5 quad_perm:[0,0,0,0] row_mask:0xf bank_mask:0xf
	v_mul_f32_dpp v118, -v194, v6 quad_perm:[1,1,1,1] row_mask:0xf bank_mask:0xf
	v_mul_f32_dpp v119, -v195, v12 quad_perm:[1,1,1,1] row_mask:0xf bank_mask:0xf
	ds_read_b64 v[170:171], v125 offset:5472
	v_fmac_f32_dpp v116, -v194, v7 quad_perm:[2,2,2,2] row_mask:0xf bank_mask:0xf
	v_fmac_f32_dpp v117, -v195, v13 quad_perm:[2,2,2,2] row_mask:0xf bank_mask:0xf
	v_fmac_f32_dpp v118, -v194, v14 quad_perm:[3,3,3,3] row_mask:0xf bank_mask:0xf
	ds_read_b64 v[84:85], v125 offset:5504
	v_fmac_f32_dpp v119, -v195, v15 quad_perm:[3,3,3,3] row_mask:0xf bank_mask:0xf
	v_fmac_f32_dpp v116, -v196, v16 quad_perm:[0,0,0,0] row_mask:0xf bank_mask:0xf
	v_fmac_f32_dpp v117, -v197, v17 quad_perm:[0,0,0,0] row_mask:0xf bank_mask:0xf
	ds_read_b32 v212, v124 offset:80
	v_fmac_f32_dpp v118, -v196, v19 quad_perm:[1,1,1,1] row_mask:0xf bank_mask:0xf
	v_fmac_f32_dpp v119, -v197, v20 quad_perm:[1,1,1,1] row_mask:0xf bank_mask:0xf
	v_fmac_f32_dpp v116, -v196, v21 quad_perm:[2,2,2,2] row_mask:0xf bank_mask:0xf
	ds_read_u16_d16_hi v252, v123 offset:5440
	v_fmac_f32_dpp v117, -v197, v22 quad_perm:[2,2,2,2] row_mask:0xf bank_mask:0xf
	v_fmac_f32_dpp v118, -v196, v23 quad_perm:[3,3,3,3] row_mask:0xf bank_mask:0xf
	v_fmac_f32_dpp v119, -v197, v24 quad_perm:[3,3,3,3] row_mask:0xf bank_mask:0xf
	ds_read_b64 v[86:87], v125 offset:5712
	v_fmac_f32_dpp v116, -v198, v25 quad_perm:[0,0,0,0] row_mask:0xf bank_mask:0xf
	v_add_f32_e32 v121, v117, v116
	v_add_f32_e32 v122, v118, v119
	v_add_f32_e32 v27, v122, v121
	v_mov_b32_e32 v128, v25
	v_mov_b32_e32 v129, v27
	s_waitcnt lgkmcnt(11)
	v_mul_f32_dpp v120, v200, v4 quad_perm:[0,0,0,0] row_mask:0xf bank_mask:0xf
	v_fma_f32 v116, v210, v250, -v120
	v_permlane32_swap_b32_e32 v128, v129
	v_mul_f32_dpp v117, -v201, v5 quad_perm:[0,0,0,0] row_mask:0xf bank_mask:0xf
	v_mul_f32_dpp v118, -v200, v6 quad_perm:[1,1,1,1] row_mask:0xf bank_mask:0xf
	v_mfma_f32_32x32x2_f32 v[132:147], v222, v128, v[132:147]
	ds_read_b64 v[88:89], v125 offset:5744
	v_mul_f32_dpp v119, -v201, v12 quad_perm:[1,1,1,1] row_mask:0xf bank_mask:0xf
	v_fmac_f32_dpp v116, -v200, v7 quad_perm:[2,2,2,2] row_mask:0xf bank_mask:0xf
	v_fmac_f32_dpp v117, -v201, v13 quad_perm:[2,2,2,2] row_mask:0xf bank_mask:0xf
	ds_read_b64 v[90:91], v125 offset:5776
	v_fmac_f32_dpp v118, -v200, v14 quad_perm:[3,3,3,3] row_mask:0xf bank_mask:0xf
	v_fmac_f32_dpp v119, -v201, v15 quad_perm:[3,3,3,3] row_mask:0xf bank_mask:0xf
	v_fmac_f32_dpp v116, -v202, v16 quad_perm:[0,0,0,0] row_mask:0xf bank_mask:0xf
	ds_read_b32 v213, v124 offset:84
	v_fmac_f32_dpp v117, -v203, v17 quad_perm:[0,0,0,0] row_mask:0xf bank_mask:0xf
	v_fmac_f32_dpp v118, -v202, v19 quad_perm:[1,1,1,1] row_mask:0xf bank_mask:0xf
	v_fmac_f32_dpp v119, -v203, v20 quad_perm:[1,1,1,1] row_mask:0xf bank_mask:0xf
	ds_read_u16_d16_hi v253, v123 offset:5712
	v_fmac_f32_dpp v116, -v202, v21 quad_perm:[2,2,2,2] row_mask:0xf bank_mask:0xf
	v_fmac_f32_dpp v117, -v203, v22 quad_perm:[2,2,2,2] row_mask:0xf bank_mask:0xf
	v_fmac_f32_dpp v118, -v202, v23 quad_perm:[3,3,3,3] row_mask:0xf bank_mask:0xf
	ds_read_b64 v[92:93], v125 offset:5984
	v_fmac_f32_dpp v119, -v203, v24 quad_perm:[3,3,3,3] row_mask:0xf bank_mask:0xf
	v_fmac_f32_dpp v116, -v204, v25 quad_perm:[0,0,0,0] row_mask:0xf bank_mask:0xf
	v_fmac_f32_dpp v117, -v205, v27 quad_perm:[0,0,0,0] row_mask:0xf bank_mask:0xf
	ds_read_b64 v[186:187], v125 offset:6016
	v_add_f32_e32 v121, v117, v116
	v_mfma_f32_32x32x2_f32 v[148:163], v222, v129, v[148:163]
	v_add_f32_e32 v122, v118, v119
	v_add_f32_e32 v28, v122, v121
	s_waitcnt lgkmcnt(12)
; #define GDN_LOADROW(buf, rr_, i_) do { _Pragma("unroll") for (int j4 = 0; j4 < ((i_) + 3) / 4; ++j4) buf[j4] = *(const f32x4*)(Lm + (i_) * GP_LSTR + 4 * j4); rr_ = bf2f(*(const bf16*)(xsrc + (i_) * GP_STR * 2)) * scl[i_]; } while (0)
; template <int STRIP> __device__ __forceinline__ void ph_gdn_prep_fast(const bf16* __restrict__ proj, const float* __restrict__ small, const float* __restrict__ conv_w, const float* __restrict__ a_log, const float* __restrict__ dt_bias, ...
;     ...
; #pragma unroll
;             for (int i = 0; i < 64; i += 2) {
;                 GDN_LOADROW(bB, rB, i + 1);
;                 GDN_ROW(bA, rA, i);
;                 if (i + 2 < 64) GDN_LOADROW(bA, rA, i + 2);
;                 GDN_ROW(bB, rB, i + 1);
;             }
	v_mul_f32_dpp v120, v206, v4 quad_perm:[0,0,0,0] row_mask:0xf bank_mask:0xf
	v_fma_f32 v116, v211, v251, -v120
	v_mul_f32_dpp v117, -v207, v5 quad_perm:[0,0,0,0] row_mask:0xf bank_mask:0xf
	v_mul_f32_dpp v118, -v206, v6 quad_perm:[1,1,1,1] row_mask:0xf bank_mask:0xf
	v_mul_f32_dpp v119, -v207, v12 quad_perm:[1,1,1,1] row_mask:0xf bank_mask:0xf
	ds_read_b64 v[188:189], v125 offset:6048
	v_fmac_f32_dpp v116, -v206, v7 quad_perm:[2,2,2,2] row_mask:0xf bank_mask:0xf
	v_fmac_f32_dpp v117, -v207, v13 quad_perm:[2,2,2,2] row_mask:0xf bank_mask:0xf
	v_fmac_f32_dpp v118, -v206, v14 quad_perm:[3,3,3,3] row_mask:0xf bank_mask:0xf
	ds_read_b32 v214, v124 offset:88
	v_fmac_f32_dpp v119, -v207, v15 quad_perm:[3,3,3,3] row_mask:0xf bank_mask:0xf
	v_fmac_f32_dpp v116, -v164, v16 quad_perm:[0,0,0,0] row_mask:0xf bank_mask:0xf
	v_fmac_f32_dpp v117, -v165, v17 quad_perm:[0,0,0,0] row_mask:0xf bank_mask:0xf
	ds_read_u16_d16_hi v126, v123 offset:5984
	v_fmac_f32_dpp v118, -v164, v19 quad_perm:[1,1,1,1] row_mask:0xf bank_mask:0xf
	v_fmac_f32_dpp v119, -v165, v20 quad_perm:[1,1,1,1] row_mask:0xf bank_mask:0xf
	v_fmac_f32_dpp v116, -v164, v21 quad_perm:[2,2,2,2] row_mask:0xf bank_mask:0xf
	ds_read_b64 v[190:191], v125 offset:6256
	v_fmac_f32_dpp v117, -v165, v22 quad_perm:[2,2,2,2] row_mask:0xf bank_mask:0xf
	v_fmac_f32_dpp v118, -v164, v23 quad_perm:[3,3,3,3] row_mask:0xf bank_mask:0xf
	v_fmac_f32_dpp v119, -v165, v24 quad_perm:[3,3,3,3] row_mask:0xf bank_mask:0xf
	ds_read_b64 v[192:193], v125 offset:6288
	v_fmac_f32_dpp v116, -v166, v25 quad_perm:[0,0,0,0] row_mask:0xf bank_mask:0xf
	v_fmac_f32_dpp v117, -v167, v27 quad_perm:[0,0,0,0] row_mask:0xf bank_mask:0xf
	v_fmac_f32_dpp v118, -v166, v28 quad_perm:[1,1,1,1] row_mask:0xf bank_mask:0xf
	ds_read_b64 v[194:195], v125 offset:6320
	v_add_f32_e32 v121, v117, v116
	v_add_f32_e32 v122, v118, v119
	v_add_f32_e32 v29, v122, v121
	v_mov_b32_e32 v220, v28
	v_mov_b32_e32 v221, v29
	s_waitcnt lgkmcnt(13)
	v_mul_f32_dpp v120, v168, v4 quad_perm:[0,0,0,0] row_mask:0xf bank_mask:0xf
	v_fma_f32 v116, v212, v252, -v120
	v_permlane32_swap_b32_e32 v220, v221
	v_mul_f32_dpp v117, -v169, v5 quad_perm:[0,0,0,0] row_mask:0xf bank_mask:0xf
	v_mul_f32_dpp v118, -v168, v6 quad_perm:[1,1,1,1] row_mask:0xf bank_mask:0xf
	v_mfma_f32_32x32x2_f32 v[132:147], v223, v220, v[132:147]
	v_mul_f32_dpp v119, -v169, v12 quad_perm:[1,1,1,1] row_mask:0xf bank_mask:0xf
	ds_read_b32 v215, v124 offset:92
	v_fmac_f32_dpp v116, -v168, v7 quad_perm:[2,2,2,2] row_mask:0xf bank_mask:0xf
	v_fmac_f32_dpp v117, -v169, v13 quad_perm:[2,2,2,2] row_mask:0xf bank_mask:0xf
	v_fmac_f32_dpp v118, -v168, v14 quad_perm:[3,3,3,3] row_mask:0xf bank_mask:0xf
	ds_read_u16_d16_hi v127, v123 offset:6256
	v_fmac_f32_dpp v119, -v169, v15 quad_perm:[3,3,3,3] row_mask:0xf bank_mask:0xf
	v_fmac_f32_dpp v116, -v170, v16 quad_perm:[0,0,0,0] row_mask:0xf bank_mask:0xf
	v_fmac_f32_dpp v117, -v171, v17 quad_perm:[0,0,0,0] row_mask:0xf bank_mask:0xf
	ds_read_b64 v[196:197], v125 offset:6528
	v_fmac_f32_dpp v118, -v170, v19 quad_perm:[1,1,1,1] row_mask:0xf bank_mask:0xf
	v_fmac_f32_dpp v119, -v171, v20 quad_perm:[1,1,1,1] row_mask:0xf bank_mask:0xf
	v_fmac_f32_dpp v116, -v170, v21 quad_perm:[2,2,2,2] row_mask:0xf bank_mask:0xf
	ds_read_b64 v[198:199], v125 offset:6560
	v_fmac_f32_dpp v117, -v171, v22 quad_perm:[2,2,2,2] row_mask:0xf bank_mask:0xf
	v_fmac_f32_dpp v118, -v170, v23 quad_perm:[3,3,3,3] row_mask:0xf bank_mask:0xf
	v_fmac_f32_dpp v119, -v171, v24 quad_perm:[3,3,3,3] row_mask:0xf bank_mask:0xf
	ds_read_b64 v[200:201], v125 offset:6592
	v_fmac_f32_dpp v116, -v84, v25 quad_perm:[0,0,0,0] row_mask:0xf bank_mask:0xf
	v_fmac_f32_dpp v117, -v85, v27 quad_perm:[0,0,0,0] row_mask:0xf bank_mask:0xf
	v_fmac_f32_dpp v118, -v84, v28 quad_perm:[1,1,1,1] row_mask:0xf bank_mask:0xf
	v_mfma_f32_32x32x2_f32 v[148:163], v223, v221, v[148:163]
	ds_read_b32 v216, v124 offset:96
	v_fmac_f32_dpp v119, -v85, v29 quad_perm:[1,1,1,1] row_mask:0xf bank_mask:0xf
	v_add_f32_e32 v121, v117, v116
	v_add_f32_e32 v122, v118, v119
	v_add_f32_e32 v30, v122, v121
	s_waitcnt lgkmcnt(14)
	v_mul_f32_dpp v120, v86, v4 quad_perm:[0,0,0,0] row_mask:0xf bank_mask:0xf
	v_fma_f32 v116, v213, v253, -v120
	v_mul_f32_dpp v117, -v87, v5 quad_perm:[0,0,0,0] row_mask:0xf bank_mask:0xf
	v_mul_f32_dpp v118, -v86, v6 quad_perm:[1,1,1,1] row_mask:0xf bank_mask:0xf
	ds_read_u16_d16_hi v244, v123 offset:6528
	v_mul_f32_dpp v119, -v87, v12 quad_perm:[1,1,1,1] row_mask:0xf bank_mask:0xf
	v_fmac_f32_dpp v116, -v86, v7 quad_perm:[2,2,2,2] row_mask:0xf bank_mask:0xf
	v_fmac_f32_dpp v117, -v87, v13 quad_perm:[2,2,2,2] row_mask:0xf bank_mask:0xf
	v_fmac_f32_dpp v118, -v86, v14 quad_perm:[3,3,3,3] row_mask:0xf bank_mask:0xf
	v_fmac_f32_dpp v119, -v87, v15 quad_perm:[3,3,3,3] row_mask:0xf bank_mask:0xf
	v_fmac_f32_dpp v116, -v88, v16 quad_perm:[0,0,0,0] row_mask:0xf bank_mask:0xf
	v_fmac_f32_dpp v117, -v89, v17 quad_perm:[0,0,0,0] row_mask:0xf bank_mask:0xf
	v_fmac_f32_dpp v118, -v88, v19 quad_perm:[1,1,1,1] row_mask:0xf bank_mask:0xf
	v_fmac_f32_dpp v119, -v89, v20 quad_perm:[1,1,1,1] row_mask:0xf bank_mask:0xf
	v_fmac_f32_dpp v116, -v88, v21 quad_perm:[2,2,2,2] row_mask:0xf bank_mask:0xf
	v_fmac_f32_dpp v117, -v89, v22 quad_perm:[2,2,2,2] row_mask:0xf bank_mask:0xf
	v_fmac_f32_dpp v118, -v88, v23 quad_perm:[3,3,3,3] row_mask:0xf bank_mask:0xf
	v_fmac_f32_dpp v119, -v89, v24 quad_perm:[3,3,3,3] row_mask:0xf bank_mask:0xf
	v_fmac_f32_dpp v116, -v90, v25 quad_perm:[0,0,0,0] row_mask:0xf bank_mask:0xf
	v_fmac_f32_dpp v117, -v91, v27 quad_perm:[0,0,0,0] row_mask:0xf bank_mask:0xf
	v_fmac_f32_dpp v118, -v90, v28 quad_perm:[1,1,1,1] row_mask:0xf bank_mask:0xf
	v_fmac_f32_dpp v119, -v91, v29 quad_perm:[1,1,1,1] row_mask:0xf bank_mask:0xf
	v_fmac_f32_dpp v116, -v90, v30 quad_perm:[2,2,2,2] row_mask:0xf bank_mask:0xf
	v_add_f32_e32 v121, v117, v116
	v_add_f32_e32 v122, v118, v119
	v_add_f32_e32 v31, v122, v121
	v_mov_b32_e32 v128, v30
	v_mov_b32_e32 v129, v31
	s_waitcnt lgkmcnt(10)
; #define GDN_LOADROW(buf, rr_, i_) do { _Pragma("unroll") for (int j4 = 0; j4 < ((i_) + 3) / 4; ++j4) buf[j4] = *(const f32x4*)(Lm + (i_) * GP_LSTR + 4 * j4); rr_ = bf2f(*(const bf16*)(xsrc + (i_) * GP_STR * 2)) * scl[i_]; } while (0)
; template <int STRIP> __device__ __forceinline__ void ph_gdn_prep_fast(const bf16* __restrict__ proj, const float* __restrict__ small, const float* __restrict__ conv_w, const float* __restrict__ a_log, const float* __restrict__ dt_bias, ...
;     ...
; #pragma unroll
;             for (int i = 0; i < 64; i += 2) {
;                 GDN_LOADROW(bB, rB, i + 1);
;                 GDN_ROW(bA, rA, i);
;                 if (i + 2 < 64) GDN_LOADROW(bA, rA, i + 2);
;                 GDN_ROW(bB, rB, i + 1);
;             }
	v_mul_f32_dpp v120, v92, v4 quad_perm:[0,0,0,0] row_mask:0xf bank_mask:0xf
	v_fma_f32 v116, v214, v126, -v120
	v_permlane32_swap_b32_e32 v128, v129
	v_mul_f32_dpp v117, -v93, v5 quad_perm:[0,0,0,0] row_mask:0xf bank_mask:0xf
	v_mul_f32_dpp v118, -v92, v6 quad_perm:[1,1,1,1] row_mask:0xf bank_mask:0xf
	v_mfma_f32_32x32x2_f32 v[132:147], v224, v128, v[132:147]
	v_mul_f32_dpp v119, -v93, v12 quad_perm:[1,1,1,1] row_mask:0xf bank_mask:0xf
	ds_read_b64 v[202:203], v125 offset:6800
	v_fmac_f32_dpp v116, -v92, v7 quad_perm:[2,2,2,2] row_mask:0xf bank_mask:0xf
	v_fmac_f32_dpp v117, -v93, v13 quad_perm:[2,2,2,2] row_mask:0xf bank_mask:0xf
	v_fmac_f32_dpp v118, -v92, v14 quad_perm:[3,3,3,3] row_mask:0xf bank_mask:0xf
	ds_read_b64 v[204:205], v125 offset:6832
	v_fmac_f32_dpp v119, -v93, v15 quad_perm:[3,3,3,3] row_mask:0xf bank_mask:0xf
	v_fmac_f32_dpp v116, -v186, v16 quad_perm:[0,0,0,0] row_mask:0xf bank_mask:0xf
	v_fmac_f32_dpp v117, -v187, v17 quad_perm:[0,0,0,0] row_mask:0xf bank_mask:0xf
	ds_read_b64 v[206:207], v125 offset:6864
	v_fmac_f32_dpp v118, -v186, v19 quad_perm:[1,1,1,1] row_mask:0xf bank_mask:0xf
	v_fmac_f32_dpp v119, -v187, v20 quad_perm:[1,1,1,1] row_mask:0xf bank_mask:0xf
	v_fmac_f32_dpp v116, -v186, v21 quad_perm:[2,2,2,2] row_mask:0xf bank_mask:0xf
	ds_read_b64 v[164:165], v125 offset:6896
	v_fmac_f32_dpp v117, -v187, v22 quad_perm:[2,2,2,2] row_mask:0xf bank_mask:0xf
	v_fmac_f32_dpp v118, -v186, v23 quad_perm:[3,3,3,3] row_mask:0xf bank_mask:0xf
	v_fmac_f32_dpp v119, -v187, v24 quad_perm:[3,3,3,3] row_mask:0xf bank_mask:0xf
	ds_read_b32 v217, v124 offset:100
	v_fmac_f32_dpp v116, -v188, v25 quad_perm:[0,0,0,0] row_mask:0xf bank_mask:0xf
	v_fmac_f32_dpp v117, -v189, v27 quad_perm:[0,0,0,0] row_mask:0xf bank_mask:0xf
	v_fmac_f32_dpp v118, -v188, v28 quad_perm:[1,1,1,1] row_mask:0xf bank_mask:0xf
	v_mfma_f32_32x32x2_f32 v[148:163], v224, v129, v[148:163]
	ds_read_u16_d16_hi v245, v123 offset:6800
	v_fmac_f32_dpp v119, -v189, v29 quad_perm:[1,1,1,1] row_mask:0xf bank_mask:0xf
	v_fmac_f32_dpp v116, -v188, v30 quad_perm:[2,2,2,2] row_mask:0xf bank_mask:0xf
	v_fmac_f32_dpp v117, -v189, v31 quad_perm:[2,2,2,2] row_mask:0xf bank_mask:0xf
	v_add_f32_e32 v121, v117, v116
	v_add_f32_e32 v122, v118, v119
	v_add_f32_e32 v32, v122, v121
	s_waitcnt lgkmcnt(11)
	v_mul_f32_dpp v120, v190, v4 quad_perm:[0,0,0,0] row_mask:0xf bank_mask:0xf
	v_fma_f32 v116, v215, v127, -v120
	v_mul_f32_dpp v117, -v191, v5 quad_perm:[0,0,0,0] row_mask:0xf bank_mask:0xf
	v_mul_f32_dpp v118, -v190, v6 quad_perm:[1,1,1,1] row_mask:0xf bank_mask:0xf
	v_mul_f32_dpp v119, -v191, v12 quad_perm:[1,1,1,1] row_mask:0xf bank_mask:0xf
	ds_read_b64 v[166:167], v125 offset:7072
	v_fmac_f32_dpp v116, -v190, v7 quad_perm:[2,2,2,2] row_mask:0xf bank_mask:0xf
	v_fmac_f32_dpp v117, -v191, v13 quad_perm:[2,2,2,2] row_mask:0xf bank_mask:0xf
	v_fmac_f32_dpp v118, -v190, v14 quad_perm:[3,3,3,3] row_mask:0xf bank_mask:0xf
	ds_read_b64 v[168:169], v125 offset:7104
	v_fmac_f32_dpp v119, -v191, v15 quad_perm:[3,3,3,3] row_mask:0xf bank_mask:0xf
	v_fmac_f32_dpp v116, -v192, v16 quad_perm:[0,0,0,0] row_mask:0xf bank_mask:0xf
	v_fmac_f32_dpp v117, -v193, v17 quad_perm:[0,0,0,0] row_mask:0xf bank_mask:0xf
	ds_read_b64 v[170:171], v125 offset:7136
	v_fmac_f32_dpp v118, -v192, v19 quad_perm:[1,1,1,1] row_mask:0xf bank_mask:0xf
	v_fmac_f32_dpp v119, -v193, v20 quad_perm:[1,1,1,1] row_mask:0xf bank_mask:0xf
	v_fmac_f32_dpp v116, -v192, v21 quad_perm:[2,2,2,2] row_mask:0xf bank_mask:0xf
	ds_read_b64 v[84:85], v125 offset:7168
	v_fmac_f32_dpp v117, -v193, v22 quad_perm:[2,2,2,2] row_mask:0xf bank_mask:0xf
	v_fmac_f32_dpp v118, -v192, v23 quad_perm:[3,3,3,3] row_mask:0xf bank_mask:0xf
	v_fmac_f32_dpp v119, -v193, v24 quad_perm:[3,3,3,3] row_mask:0xf bank_mask:0xf
	ds_read_b32 v218, v124 offset:104
	v_fmac_f32_dpp v116, -v194, v25 quad_perm:[0,0,0,0] row_mask:0xf bank_mask:0xf
	v_fmac_f32_dpp v117, -v195, v27 quad_perm:[0,0,0,0] row_mask:0xf bank_mask:0xf
	v_fmac_f32_dpp v118, -v194, v28 quad_perm:[1,1,1,1] row_mask:0xf bank_mask:0xf
	ds_read_u16_d16_hi v246, v123 offset:7072
	v_fmac_f32_dpp v119, -v195, v29 quad_perm:[1,1,1,1] row_mask:0xf bank_mask:0xf
	v_fmac_f32_dpp v116, -v194, v30 quad_perm:[2,2,2,2] row_mask:0xf bank_mask:0xf
	v_fmac_f32_dpp v117, -v195, v31 quad_perm:[2,2,2,2] row_mask:0xf bank_mask:0xf
	v_fmac_f32_dpp v118, -v194, v32 quad_perm:[3,3,3,3] row_mask:0xf bank_mask:0xf
	v_add_f32_e32 v121, v117, v116
	v_add_f32_e32 v122, v118, v119
	v_add_f32_e32 v33, v122, v121
	v_mov_b32_e32 v220, v32
	v_mov_b32_e32 v221, v33
	s_waitcnt lgkmcnt(12)
; #define GDN_LOADROW(buf, rr_, i_) do { _Pragma("unroll") for (int j4 = 0; j4 < ((i_) + 3) / 4; ++j4) buf[j4] = *(const f32x4*)(Lm + (i_) * GP_LSTR + 4 * j4); rr_ = bf2f(*(const bf16*)(xsrc + (i_) * GP_STR * 2)) * scl[i_]; } while (0)
; template <int STRIP> __device__ __forceinline__ void ph_gdn_prep_fast(const bf16* __restrict__ proj, const float* __restrict__ small, const float* __restrict__ conv_w, const float* __restrict__ a_log, const float* __restrict__ dt_bias, ...
;     ...
; #pragma unroll
;             for (int i = 0; i < 64; i += 2) {
;                 GDN_LOADROW(bB, rB, i + 1);
;                 GDN_ROW(bA, rA, i);
;                 if (i + 2 < 64) GDN_LOADROW(bA, rA, i + 2);
;                 GDN_ROW(bB, rB, i + 1);
;             }
	v_mul_f32_dpp v120, v196, v4 quad_perm:[0,0,0,0] row_mask:0xf bank_mask:0xf
	v_fma_f32 v116, v216, v244, -v120
	v_permlane32_swap_b32_e32 v220, v221
	v_mul_f32_dpp v117, -v197, v5 quad_perm:[0,0,0,0] row_mask:0xf bank_mask:0xf
	v_mul_f32_dpp v118, -v196, v6 quad_perm:[1,1,1,1] row_mask:0xf bank_mask:0xf
	v_mfma_f32_32x32x2_f32 v[132:147], v225, v220, v[132:147]
	ds_read_b64 v[86:87], v125 offset:7344
	v_mul_f32_dpp v119, -v197, v12 quad_perm:[1,1,1,1] row_mask:0xf bank_mask:0xf
	v_fmac_f32_dpp v116, -v196, v7 quad_perm:[2,2,2,2] row_mask:0xf bank_mask:0xf
	v_fmac_f32_dpp v117, -v197, v13 quad_perm:[2,2,2,2] row_mask:0xf bank_mask:0xf
	ds_read_b64 v[88:89], v125 offset:7376
	v_fmac_f32_dpp v118, -v196, v14 quad_perm:[3,3,3,3] row_mask:0xf bank_mask:0xf
	v_fmac_f32_dpp v119, -v197, v15 quad_perm:[3,3,3,3] row_mask:0xf bank_mask:0xf
	v_fmac_f32_dpp v116, -v198, v16 quad_perm:[0,0,0,0] row_mask:0xf bank_mask:0xf
	ds_read_b64 v[90:91], v125 offset:7408
	v_fmac_f32_dpp v117, -v199, v17 quad_perm:[0,0,0,0] row_mask:0xf bank_mask:0xf
	v_fmac_f32_dpp v118, -v198, v19 quad_perm:[1,1,1,1] row_mask:0xf bank_mask:0xf
	v_fmac_f32_dpp v119, -v199, v20 quad_perm:[1,1,1,1] row_mask:0xf bank_mask:0xf
	ds_read_b64 v[92:93], v125 offset:7440
	v_fmac_f32_dpp v116, -v198, v21 quad_perm:[2,2,2,2] row_mask:0xf bank_mask:0xf
	v_fmac_f32_dpp v117, -v199, v22 quad_perm:[2,2,2,2] row_mask:0xf bank_mask:0xf
	v_fmac_f32_dpp v118, -v198, v23 quad_perm:[3,3,3,3] row_mask:0xf bank_mask:0xf
	ds_read_b32 v219, v124 offset:108
	v_fmac_f32_dpp v119, -v199, v24 quad_perm:[3,3,3,3] row_mask:0xf bank_mask:0xf
	v_fmac_f32_dpp v116, -v200, v25 quad_perm:[0,0,0,0] row_mask:0xf bank_mask:0xf
	v_fmac_f32_dpp v117, -v201, v27 quad_perm:[0,0,0,0] row_mask:0xf bank_mask:0xf
	ds_read_u16_d16_hi v247, v123 offset:7344
	v_fmac_f32_dpp v118, -v200, v28 quad_perm:[1,1,1,1] row_mask:0xf bank_mask:0xf
	v_mfma_f32_32x32x2_f32 v[148:163], v225, v221, v[148:163]
	v_fmac_f32_dpp v119, -v201, v29 quad_perm:[1,1,1,1] row_mask:0xf bank_mask:0xf
	v_fmac_f32_dpp v116, -v200, v30 quad_perm:[2,2,2,2] row_mask:0xf bank_mask:0xf
	v_fmac_f32_dpp v117, -v201, v31 quad_perm:[2,2,2,2] row_mask:0xf bank_mask:0xf
	v_fmac_f32_dpp v118, -v200, v32 quad_perm:[3,3,3,3] row_mask:0xf bank_mask:0xf
	v_fmac_f32_dpp v119, -v201, v33 quad_perm:[3,3,3,3] row_mask:0xf bank_mask:0xf
	v_add_f32_e32 v121, v117, v116
	v_add_f32_e32 v122, v118, v119
	v_add_f32_e32 v34, v122, v121
	s_waitcnt lgkmcnt(12)
	v_mul_f32_dpp v120, v202, v4 quad_perm:[0,0,0,0] row_mask:0xf bank_mask:0xf
	v_fma_f32 v116, v217, v245, -v120
	v_mul_f32_dpp v117, -v203, v5 quad_perm:[0,0,0,0] row_mask:0xf bank_mask:0xf
	v_mul_f32_dpp v118, -v202, v6 quad_perm:[1,1,1,1] row_mask:0xf bank_mask:0xf
	v_mul_f32_dpp v119, -v203, v12 quad_perm:[1,1,1,1] row_mask:0xf bank_mask:0xf
	ds_read_b64 v[186:187], v125 offset:7616
	v_fmac_f32_dpp v116, -v202, v7 quad_perm:[2,2,2,2] row_mask:0xf bank_mask:0xf
	v_fmac_f32_dpp v117, -v203, v13 quad_perm:[2,2,2,2] row_mask:0xf bank_mask:0xf
	v_fmac_f32_dpp v118, -v202, v14 quad_perm:[3,3,3,3] row_mask:0xf bank_mask:0xf
	ds_read_b64 v[188:189], v125 offset:7648
	v_fmac_f32_dpp v119, -v203, v15 quad_perm:[3,3,3,3] row_mask:0xf bank_mask:0xf
	v_fmac_f32_dpp v116, -v204, v16 quad_perm:[0,0,0,0] row_mask:0xf bank_mask:0xf
	v_fmac_f32_dpp v117, -v205, v17 quad_perm:[0,0,0,0] row_mask:0xf bank_mask:0xf
	ds_read_b64 v[190:191], v125 offset:7680
	v_fmac_f32_dpp v118, -v204, v19 quad_perm:[1,1,1,1] row_mask:0xf bank_mask:0xf
	v_fmac_f32_dpp v119, -v205, v20 quad_perm:[1,1,1,1] row_mask:0xf bank_mask:0xf
	v_fmac_f32_dpp v116, -v204, v21 quad_perm:[2,2,2,2] row_mask:0xf bank_mask:0xf
	ds_read_b64 v[192:193], v125 offset:7712
	v_fmac_f32_dpp v117, -v205, v22 quad_perm:[2,2,2,2] row_mask:0xf bank_mask:0xf
	v_fmac_f32_dpp v118, -v204, v23 quad_perm:[3,3,3,3] row_mask:0xf bank_mask:0xf
	v_fmac_f32_dpp v119, -v205, v24 quad_perm:[3,3,3,3] row_mask:0xf bank_mask:0xf
	ds_read_b32 v181, v124 offset:112
	v_fmac_f32_dpp v116, -v206, v25 quad_perm:[0,0,0,0] row_mask:0xf bank_mask:0xf
	v_fmac_f32_dpp v117, -v207, v27 quad_perm:[0,0,0,0] row_mask:0xf bank_mask:0xf
	v_fmac_f32_dpp v118, -v206, v28 quad_perm:[1,1,1,1] row_mask:0xf bank_mask:0xf
	ds_read_u16_d16_hi v248, v123 offset:7616
	v_fmac_f32_dpp v119, -v207, v29 quad_perm:[1,1,1,1] row_mask:0xf bank_mask:0xf
	v_fmac_f32_dpp v116, -v206, v30 quad_perm:[2,2,2,2] row_mask:0xf bank_mask:0xf
	v_fmac_f32_dpp v117, -v207, v31 quad_perm:[2,2,2,2] row_mask:0xf bank_mask:0xf
	v_fmac_f32_dpp v118, -v206, v32 quad_perm:[3,3,3,3] row_mask:0xf bank_mask:0xf
	v_fmac_f32_dpp v119, -v207, v33 quad_perm:[3,3,3,3] row_mask:0xf bank_mask:0xf
	v_fmac_f32_dpp v116, -v164, v34 quad_perm:[0,0,0,0] row_mask:0xf bank_mask:0xf
	v_add_f32_e32 v121, v117, v116
	v_add_f32_e32 v122, v118, v119
	v_add_f32_e32 v35, v122, v121
	v_mov_b32_e32 v128, v34
	v_mov_b32_e32 v129, v35
	s_waitcnt lgkmcnt(12)
; __device__ __forceinline__ float bf2f(bf16 v) { return __uint_as_float(((unsigned)v) << 16); }
; #define GDN_LOADROW(buf, rr_, i_) do { _Pragma("unroll") for (int j4 = 0; j4 < ((i_) + 3) / 4; ++j4) buf[j4] = *(const f32x4*)(Lm + (i_) * GP_LSTR + 4 * j4); rr_ = bf2f(*(const bf16*)(xsrc + (i_) * GP_STR * 2)) * scl[i_]; } while (0)
; template <int STRIP> __device__ __forceinline__ void ph_gdn_prep_fast(const bf16* __restrict__ proj, const float* __restrict__ small, const float* __restrict__ conv_w, const float* __restrict__ a_log, const float* __restrict__ dt_bias, ...
;     ...
;             f32x4 bA[16], bB[16]; float rA, rB = 0.f;
;             rA = bf2f(*(const bf16*)xsrc) * scl[0];
;     ...
; #pragma unroll
;             for (int i = 0; i < 64; i += 2) {
;                 GDN_LOADROW(bB, rB, i + 1);
;                 GDN_ROW(bA, rA, i);
;                 if (i + 2 < 64) GDN_LOADROW(bA, rA, i + 2);
;                 GDN_ROW(bB, rB, i + 1);
;             }
	v_mul_f32_dpp v120, v166, v4 quad_perm:[0,0,0,0] row_mask:0xf bank_mask:0xf
	v_fma_f32 v116, v218, v246, -v120
	v_permlane32_swap_b32_e32 v128, v129
	v_mul_f32_dpp v117, -v167, v5 quad_perm:[0,0,0,0] row_mask:0xf bank_mask:0xf
	v_mul_f32_dpp v118, -v166, v6 quad_perm:[1,1,1,1] row_mask:0xf bank_mask:0xf
	v_mfma_f32_32x32x2_f32 v[132:147], v226, v128, v[132:147]
	v_mul_f32_dpp v119, -v167, v12 quad_perm:[1,1,1,1] row_mask:0xf bank_mask:0xf
	ds_read_b64 v[194:195], v125 offset:7888
	v_fmac_f32_dpp v116, -v166, v7 quad_perm:[2,2,2,2] row_mask:0xf bank_mask:0xf
	v_fmac_f32_dpp v117, -v167, v13 quad_perm:[2,2,2,2] row_mask:0xf bank_mask:0xf
	v_fmac_f32_dpp v118, -v166, v14 quad_perm:[3,3,3,3] row_mask:0xf bank_mask:0xf
	ds_read_b64 v[196:197], v125 offset:7920
	v_fmac_f32_dpp v119, -v167, v15 quad_perm:[3,3,3,3] row_mask:0xf bank_mask:0xf
	v_fmac_f32_dpp v116, -v168, v16 quad_perm:[0,0,0,0] row_mask:0xf bank_mask:0xf
	v_fmac_f32_dpp v117, -v169, v17 quad_perm:[0,0,0,0] row_mask:0xf bank_mask:0xf
	ds_read_b64 v[198:199], v125 offset:7952
	v_fmac_f32_dpp v118, -v168, v19 quad_perm:[1,1,1,1] row_mask:0xf bank_mask:0xf
	v_fmac_f32_dpp v119, -v169, v20 quad_perm:[1,1,1,1] row_mask:0xf bank_mask:0xf
	v_fmac_f32_dpp v116, -v168, v21 quad_perm:[2,2,2,2] row_mask:0xf bank_mask:0xf
	ds_read_b64 v[200:201], v125 offset:7984
	v_fmac_f32_dpp v117, -v169, v22 quad_perm:[2,2,2,2] row_mask:0xf bank_mask:0xf
	v_fmac_f32_dpp v118, -v168, v23 quad_perm:[3,3,3,3] row_mask:0xf bank_mask:0xf
	v_fmac_f32_dpp v119, -v169, v24 quad_perm:[3,3,3,3] row_mask:0xf bank_mask:0xf
	ds_read_b32 v182, v124 offset:116
	v_fmac_f32_dpp v116, -v170, v25 quad_perm:[0,0,0,0] row_mask:0xf bank_mask:0xf
	v_fmac_f32_dpp v117, -v171, v27 quad_perm:[0,0,0,0] row_mask:0xf bank_mask:0xf
	v_fmac_f32_dpp v118, -v170, v28 quad_perm:[1,1,1,1] row_mask:0xf bank_mask:0xf
	v_mfma_f32_32x32x2_f32 v[148:163], v226, v129, v[148:163]
	ds_read_u16_d16_hi v249, v123 offset:7888
	v_fmac_f32_dpp v119, -v171, v29 quad_perm:[1,1,1,1] row_mask:0xf bank_mask:0xf
	v_fmac_f32_dpp v116, -v170, v30 quad_perm:[2,2,2,2] row_mask:0xf bank_mask:0xf
	v_fmac_f32_dpp v117, -v171, v31 quad_perm:[2,2,2,2] row_mask:0xf bank_mask:0xf
	v_fmac_f32_dpp v118, -v170, v32 quad_perm:[3,3,3,3] row_mask:0xf bank_mask:0xf
	v_fmac_f32_dpp v119, -v171, v33 quad_perm:[3,3,3,3] row_mask:0xf bank_mask:0xf
	v_fmac_f32_dpp v116, -v84, v34 quad_perm:[0,0,0,0] row_mask:0xf bank_mask:0xf
	v_fmac_f32_dpp v117, -v85, v35 quad_perm:[0,0,0,0] row_mask:0xf bank_mask:0xf
	v_add_f32_e32 v121, v117, v116
	v_add_f32_e32 v122, v118, v119
	v_add_f32_e32 v36, v122, v121
	s_waitcnt lgkmcnt(12)
	v_mul_f32_dpp v120, v86, v4 quad_perm:[0,0,0,0] row_mask:0xf bank_mask:0xf
	v_fma_f32 v116, v219, v247, -v120
	v_mul_f32_dpp v117, -v87, v5 quad_perm:[0,0,0,0] row_mask:0xf bank_mask:0xf
	v_mul_f32_dpp v118, -v86, v6 quad_perm:[1,1,1,1] row_mask:0xf bank_mask:0xf
	ds_read_b64 v[202:203], v125 offset:8160
	v_mul_f32_dpp v119, -v87, v12 quad_perm:[1,1,1,1] row_mask:0xf bank_mask:0xf
	v_fmac_f32_dpp v116, -v86, v7 quad_perm:[2,2,2,2] row_mask:0xf bank_mask:0xf
	v_fmac_f32_dpp v117, -v87, v13 quad_perm:[2,2,2,2] row_mask:0xf bank_mask:0xf
	ds_read_b64 v[204:205], v125 offset:8192
	v_fmac_f32_dpp v118, -v86, v14 quad_perm:[3,3,3,3] row_mask:0xf bank_mask:0xf
	v_fmac_f32_dpp v119, -v87, v15 quad_perm:[3,3,3,3] row_mask:0xf bank_mask:0xf
	v_fmac_f32_dpp v116, -v88, v16 quad_perm:[0,0,0,0] row_mask:0xf bank_mask:0xf
	ds_read_b64 v[206:207], v125 offset:8224
	v_fmac_f32_dpp v117, -v89, v17 quad_perm:[0,0,0,0] row_mask:0xf bank_mask:0xf
	v_fmac_f32_dpp v118, -v88, v19 quad_perm:[1,1,1,1] row_mask:0xf bank_mask:0xf
	v_fmac_f32_dpp v119, -v89, v20 quad_perm:[1,1,1,1] row_mask:0xf bank_mask:0xf
	ds_read_b64 v[164:165], v125 offset:8256
	v_fmac_f32_dpp v116, -v88, v21 quad_perm:[2,2,2,2] row_mask:0xf bank_mask:0xf
	v_fmac_f32_dpp v117, -v89, v22 quad_perm:[2,2,2,2] row_mask:0xf bank_mask:0xf
	v_fmac_f32_dpp v118, -v88, v23 quad_perm:[3,3,3,3] row_mask:0xf bank_mask:0xf
	ds_read_b32 v183, v124 offset:120
	v_fmac_f32_dpp v119, -v89, v24 quad_perm:[3,3,3,3] row_mask:0xf bank_mask:0xf
	v_fmac_f32_dpp v116, -v90, v25 quad_perm:[0,0,0,0] row_mask:0xf bank_mask:0xf
	v_fmac_f32_dpp v117, -v91, v27 quad_perm:[0,0,0,0] row_mask:0xf bank_mask:0xf
	ds_read_u16_d16_hi v250, v123 offset:8160
	v_fmac_f32_dpp v118, -v90, v28 quad_perm:[1,1,1,1] row_mask:0xf bank_mask:0xf
	v_fmac_f32_dpp v119, -v91, v29 quad_perm:[1,1,1,1] row_mask:0xf bank_mask:0xf
	v_fmac_f32_dpp v116, -v90, v30 quad_perm:[2,2,2,2] row_mask:0xf bank_mask:0xf
	v_fmac_f32_dpp v117, -v91, v31 quad_perm:[2,2,2,2] row_mask:0xf bank_mask:0xf
	v_fmac_f32_dpp v118, -v90, v32 quad_perm:[3,3,3,3] row_mask:0xf bank_mask:0xf
	v_fmac_f32_dpp v119, -v91, v33 quad_perm:[3,3,3,3] row_mask:0xf bank_mask:0xf
	v_fmac_f32_dpp v116, -v92, v34 quad_perm:[0,0,0,0] row_mask:0xf bank_mask:0xf
	v_fmac_f32_dpp v117, -v93, v35 quad_perm:[0,0,0,0] row_mask:0xf bank_mask:0xf
	v_fmac_f32_dpp v118, -v92, v36 quad_perm:[1,1,1,1] row_mask:0xf bank_mask:0xf
	v_add_f32_e32 v121, v117, v116
	v_add_f32_e32 v122, v118, v119
	v_add_f32_e32 v37, v122, v121
	v_mov_b32_e32 v220, v36
	v_mov_b32_e32 v221, v37
	s_waitcnt lgkmcnt(12)
; __device__ __forceinline__ float bf2f(bf16 v) { return __uint_as_float(((unsigned)v) << 16); }
; #define GDN_LOADROW(buf, rr_, i_) do { _Pragma("unroll") for (int j4 = 0; j4 < ((i_) + 3) / 4; ++j4) buf[j4] = *(const f32x4*)(Lm + (i_) * GP_LSTR + 4 * j4); rr_ = bf2f(*(const bf16*)(xsrc + (i_) * GP_STR * 2)) * scl[i_]; } while (0)
; template <int STRIP> __device__ __forceinline__ void ph_gdn_prep_fast(const bf16* __restrict__ proj, const float* __restrict__ small, const float* __restrict__ conv_w, const float* __restrict__ a_log, const float* __restrict__ dt_bias, ...
;     ...
;             f32x4 bA[16], bB[16]; float rA, rB = 0.f;
;             rA = bf2f(*(const bf16*)xsrc) * scl[0];
;     ...
; #pragma unroll
;             for (int i = 0; i < 64; i += 2) {
;                 GDN_LOADROW(bB, rB, i + 1);
;                 GDN_ROW(bA, rA, i);
;                 if (i + 2 < 64) GDN_LOADROW(bA, rA, i + 2);
;                 GDN_ROW(bB, rB, i + 1);
;             }
	v_mul_f32_dpp v120, v186, v4 quad_perm:[0,0,0,0] row_mask:0xf bank_mask:0xf
	v_fma_f32 v116, v181, v248, -v120
	v_permlane32_swap_b32_e32 v220, v221
	v_mul_f32_dpp v117, -v187, v5 quad_perm:[0,0,0,0] row_mask:0xf bank_mask:0xf
	v_mul_f32_dpp v118, -v186, v6 quad_perm:[1,1,1,1] row_mask:0xf bank_mask:0xf
	v_mfma_f32_32x32x2_f32 v[132:147], v227, v220, v[132:147]
	v_mul_f32_dpp v119, -v187, v12 quad_perm:[1,1,1,1] row_mask:0xf bank_mask:0xf
	ds_read_b64 v[166:167], v125 offset:8432
	v_fmac_f32_dpp v116, -v186, v7 quad_perm:[2,2,2,2] row_mask:0xf bank_mask:0xf
	v_fmac_f32_dpp v117, -v187, v13 quad_perm:[2,2,2,2] row_mask:0xf bank_mask:0xf
	v_fmac_f32_dpp v118, -v186, v14 quad_perm:[3,3,3,3] row_mask:0xf bank_mask:0xf
	ds_read_b64 v[168:169], v125 offset:8464
	v_fmac_f32_dpp v119, -v187, v15 quad_perm:[3,3,3,3] row_mask:0xf bank_mask:0xf
	v_fmac_f32_dpp v116, -v188, v16 quad_perm:[0,0,0,0] row_mask:0xf bank_mask:0xf
	v_fmac_f32_dpp v117, -v189, v17 quad_perm:[0,0,0,0] row_mask:0xf bank_mask:0xf
	ds_read_b64 v[170:171], v125 offset:8496
	v_fmac_f32_dpp v118, -v188, v19 quad_perm:[1,1,1,1] row_mask:0xf bank_mask:0xf
	v_fmac_f32_dpp v119, -v189, v20 quad_perm:[1,1,1,1] row_mask:0xf bank_mask:0xf
	v_fmac_f32_dpp v116, -v188, v21 quad_perm:[2,2,2,2] row_mask:0xf bank_mask:0xf
	ds_read_b64 v[84:85], v125 offset:8528
	v_fmac_f32_dpp v117, -v189, v22 quad_perm:[2,2,2,2] row_mask:0xf bank_mask:0xf
	v_fmac_f32_dpp v118, -v188, v23 quad_perm:[3,3,3,3] row_mask:0xf bank_mask:0xf
	v_fmac_f32_dpp v119, -v189, v24 quad_perm:[3,3,3,3] row_mask:0xf bank_mask:0xf
	ds_read_b32 v185, v124 offset:124
	v_fmac_f32_dpp v116, -v190, v25 quad_perm:[0,0,0,0] row_mask:0xf bank_mask:0xf
	v_fmac_f32_dpp v117, -v191, v27 quad_perm:[0,0,0,0] row_mask:0xf bank_mask:0xf
	v_fmac_f32_dpp v118, -v190, v28 quad_perm:[1,1,1,1] row_mask:0xf bank_mask:0xf
	v_mfma_f32_32x32x2_f32 v[148:163], v227, v221, v[148:163]
	ds_read_u16_d16_hi v251, v123 offset:8432
	v_fmac_f32_dpp v119, -v191, v29 quad_perm:[1,1,1,1] row_mask:0xf bank_mask:0xf
	v_fmac_f32_dpp v116, -v190, v30 quad_perm:[2,2,2,2] row_mask:0xf bank_mask:0xf
	v_fmac_f32_dpp v117, -v191, v31 quad_perm:[2,2,2,2] row_mask:0xf bank_mask:0xf
	v_fmac_f32_dpp v118, -v190, v32 quad_perm:[3,3,3,3] row_mask:0xf bank_mask:0xf
	v_fmac_f32_dpp v119, -v191, v33 quad_perm:[3,3,3,3] row_mask:0xf bank_mask:0xf
	v_fmac_f32_dpp v116, -v192, v34 quad_perm:[0,0,0,0] row_mask:0xf bank_mask:0xf
	v_fmac_f32_dpp v117, -v193, v35 quad_perm:[0,0,0,0] row_mask:0xf bank_mask:0xf
	v_fmac_f32_dpp v118, -v192, v36 quad_perm:[1,1,1,1] row_mask:0xf bank_mask:0xf
	v_fmac_f32_dpp v119, -v193, v37 quad_perm:[1,1,1,1] row_mask:0xf bank_mask:0xf
	v_add_f32_e32 v121, v117, v116
	v_add_f32_e32 v122, v118, v119
	v_add_f32_e32 v38, v122, v121
	s_waitcnt lgkmcnt(12)
	v_mul_f32_dpp v120, v194, v4 quad_perm:[0,0,0,0] row_mask:0xf bank_mask:0xf
	v_fma_f32 v116, v182, v249, -v120
	v_mul_f32_dpp v117, -v195, v5 quad_perm:[0,0,0,0] row_mask:0xf bank_mask:0xf
	v_mul_f32_dpp v118, -v194, v6 quad_perm:[1,1,1,1] row_mask:0xf bank_mask:0xf
	v_mul_f32_dpp v119, -v195, v12 quad_perm:[1,1,1,1] row_mask:0xf bank_mask:0xf
	v_fmac_f32_dpp v116, -v194, v7 quad_perm:[2,2,2,2] row_mask:0xf bank_mask:0xf
	v_fmac_f32_dpp v117, -v195, v13 quad_perm:[2,2,2,2] row_mask:0xf bank_mask:0xf
	v_fmac_f32_dpp v118, -v194, v14 quad_perm:[3,3,3,3] row_mask:0xf bank_mask:0xf
	v_fmac_f32_dpp v119, -v195, v15 quad_perm:[3,3,3,3] row_mask:0xf bank_mask:0xf
	v_fmac_f32_dpp v116, -v196, v16 quad_perm:[0,0,0,0] row_mask:0xf bank_mask:0xf
	v_fmac_f32_dpp v117, -v197, v17 quad_perm:[0,0,0,0] row_mask:0xf bank_mask:0xf
	v_fmac_f32_dpp v118, -v196, v19 quad_perm:[1,1,1,1] row_mask:0xf bank_mask:0xf
	v_fmac_f32_dpp v119, -v197, v20 quad_perm:[1,1,1,1] row_mask:0xf bank_mask:0xf
	v_fmac_f32_dpp v116, -v196, v21 quad_perm:[2,2,2,2] row_mask:0xf bank_mask:0xf
	v_fmac_f32_dpp v117, -v197, v22 quad_perm:[2,2,2,2] row_mask:0xf bank_mask:0xf
	v_fmac_f32_dpp v118, -v196, v23 quad_perm:[3,3,3,3] row_mask:0xf bank_mask:0xf
	v_fmac_f32_dpp v119, -v197, v24 quad_perm:[3,3,3,3] row_mask:0xf bank_mask:0xf
	v_fmac_f32_dpp v116, -v198, v25 quad_perm:[0,0,0,0] row_mask:0xf bank_mask:0xf
	v_fmac_f32_dpp v117, -v199, v27 quad_perm:[0,0,0,0] row_mask:0xf bank_mask:0xf
	v_fmac_f32_dpp v118, -v198, v28 quad_perm:[1,1,1,1] row_mask:0xf bank_mask:0xf
	v_fmac_f32_dpp v119, -v199, v29 quad_perm:[1,1,1,1] row_mask:0xf bank_mask:0xf
	v_fmac_f32_dpp v116, -v198, v30 quad_perm:[2,2,2,2] row_mask:0xf bank_mask:0xf
	v_fmac_f32_dpp v117, -v199, v31 quad_perm:[2,2,2,2] row_mask:0xf bank_mask:0xf
	v_fmac_f32_dpp v118, -v198, v32 quad_perm:[3,3,3,3] row_mask:0xf bank_mask:0xf
	v_fmac_f32_dpp v119, -v199, v33 quad_perm:[3,3,3,3] row_mask:0xf bank_mask:0xf
	v_fmac_f32_dpp v116, -v200, v34 quad_perm:[0,0,0,0] row_mask:0xf bank_mask:0xf
	v_fmac_f32_dpp v117, -v201, v35 quad_perm:[0,0,0,0] row_mask:0xf bank_mask:0xf
	v_fmac_f32_dpp v118, -v200, v36 quad_perm:[1,1,1,1] row_mask:0xf bank_mask:0xf
	v_fmac_f32_dpp v119, -v201, v37 quad_perm:[1,1,1,1] row_mask:0xf bank_mask:0xf
	v_fmac_f32_dpp v116, -v200, v38 quad_perm:[2,2,2,2] row_mask:0xf bank_mask:0xf
	v_add_f32_e32 v121, v117, v116
	v_add_f32_e32 v122, v118, v119
	v_add_f32_e32 v39, v122, v121
	v_mov_b32_e32 v128, v38
	v_mov_b32_e32 v129, v39
	s_waitcnt lgkmcnt(6)
; __device__ __forceinline__ float bf2f(bf16 v) { return __uint_as_float(((unsigned)v) << 16); }
; #define GDN_LOADROW(buf, rr_, i_) do { _Pragma("unroll") for (int j4 = 0; j4 < ((i_) + 3) / 4; ++j4) buf[j4] = *(const f32x4*)(Lm + (i_) * GP_LSTR + 4 * j4); rr_ = bf2f(*(const bf16*)(xsrc + (i_) * GP_STR * 2)) * scl[i_]; } while (0)
; template <int STRIP> __device__ __forceinline__ void ph_gdn_prep_fast(const bf16* __restrict__ proj, const float* __restrict__ small, const float* __restrict__ conv_w, const float* __restrict__ a_log, const float* __restrict__ dt_bias, ...
;     ...
;             f32x4 bA[16], bB[16]; float rA, rB = 0.f;
;             rA = bf2f(*(const bf16*)xsrc) * scl[0];
;     ...
; #pragma unroll
;             for (int i = 0; i < 64; i += 2) {
;                 GDN_LOADROW(bB, rB, i + 1);
;                 GDN_ROW(bA, rA, i);
;                 if (i + 2 < 64) GDN_LOADROW(bA, rA, i + 2);
;                 GDN_ROW(bB, rB, i + 1);
;             }
	v_mul_f32_dpp v120, v202, v4 quad_perm:[0,0,0,0] row_mask:0xf bank_mask:0xf
	v_fma_f32 v116, v183, v250, -v120
	v_permlane32_swap_b32_e32 v128, v129
	v_mul_f32_dpp v117, -v203, v5 quad_perm:[0,0,0,0] row_mask:0xf bank_mask:0xf
	v_mul_f32_dpp v118, -v202, v6 quad_perm:[1,1,1,1] row_mask:0xf bank_mask:0xf
	v_mfma_f32_32x32x2_f32 v[132:147], v228, v128, v[132:147]
	v_mul_f32_dpp v119, -v203, v12 quad_perm:[1,1,1,1] row_mask:0xf bank_mask:0xf
	v_fmac_f32_dpp v116, -v202, v7 quad_perm:[2,2,2,2] row_mask:0xf bank_mask:0xf
	v_fmac_f32_dpp v117, -v203, v13 quad_perm:[2,2,2,2] row_mask:0xf bank_mask:0xf
	v_fmac_f32_dpp v118, -v202, v14 quad_perm:[3,3,3,3] row_mask:0xf bank_mask:0xf
	v_fmac_f32_dpp v119, -v203, v15 quad_perm:[3,3,3,3] row_mask:0xf bank_mask:0xf
	v_fmac_f32_dpp v116, -v204, v16 quad_perm:[0,0,0,0] row_mask:0xf bank_mask:0xf
	v_fmac_f32_dpp v117, -v205, v17 quad_perm:[0,0,0,0] row_mask:0xf bank_mask:0xf
	v_fmac_f32_dpp v118, -v204, v19 quad_perm:[1,1,1,1] row_mask:0xf bank_mask:0xf
	v_fmac_f32_dpp v119, -v205, v20 quad_perm:[1,1,1,1] row_mask:0xf bank_mask:0xf
	v_fmac_f32_dpp v116, -v204, v21 quad_perm:[2,2,2,2] row_mask:0xf bank_mask:0xf
	v_fmac_f32_dpp v117, -v205, v22 quad_perm:[2,2,2,2] row_mask:0xf bank_mask:0xf
	v_fmac_f32_dpp v118, -v204, v23 quad_perm:[3,3,3,3] row_mask:0xf bank_mask:0xf
	v_fmac_f32_dpp v119, -v205, v24 quad_perm:[3,3,3,3] row_mask:0xf bank_mask:0xf
	v_fmac_f32_dpp v116, -v206, v25 quad_perm:[0,0,0,0] row_mask:0xf bank_mask:0xf
	v_fmac_f32_dpp v117, -v207, v27 quad_perm:[0,0,0,0] row_mask:0xf bank_mask:0xf
	v_fmac_f32_dpp v118, -v206, v28 quad_perm:[1,1,1,1] row_mask:0xf bank_mask:0xf
	v_mfma_f32_32x32x2_f32 v[148:163], v228, v129, v[148:163]
	v_fmac_f32_dpp v119, -v207, v29 quad_perm:[1,1,1,1] row_mask:0xf bank_mask:0xf
	v_fmac_f32_dpp v116, -v206, v30 quad_perm:[2,2,2,2] row_mask:0xf bank_mask:0xf
	v_fmac_f32_dpp v117, -v207, v31 quad_perm:[2,2,2,2] row_mask:0xf bank_mask:0xf
	v_fmac_f32_dpp v118, -v206, v32 quad_perm:[3,3,3,3] row_mask:0xf bank_mask:0xf
	v_fmac_f32_dpp v119, -v207, v33 quad_perm:[3,3,3,3] row_mask:0xf bank_mask:0xf
	v_fmac_f32_dpp v116, -v164, v34 quad_perm:[0,0,0,0] row_mask:0xf bank_mask:0xf
	v_fmac_f32_dpp v117, -v165, v35 quad_perm:[0,0,0,0] row_mask:0xf bank_mask:0xf
	v_fmac_f32_dpp v118, -v164, v36 quad_perm:[1,1,1,1] row_mask:0xf bank_mask:0xf
	v_fmac_f32_dpp v119, -v165, v37 quad_perm:[1,1,1,1] row_mask:0xf bank_mask:0xf
	v_fmac_f32_dpp v116, -v164, v38 quad_perm:[2,2,2,2] row_mask:0xf bank_mask:0xf
	v_fmac_f32_dpp v117, -v165, v39 quad_perm:[2,2,2,2] row_mask:0xf bank_mask:0xf
	v_add_f32_e32 v121, v117, v116
	v_add_f32_e32 v122, v118, v119
	v_add_f32_e32 v40, v122, v121
	s_waitcnt lgkmcnt(0)
	v_mul_f32_dpp v120, v166, v4 quad_perm:[0,0,0,0] row_mask:0xf bank_mask:0xf
	v_fma_f32 v116, v185, v251, -v120
	v_mul_f32_dpp v117, -v167, v5 quad_perm:[0,0,0,0] row_mask:0xf bank_mask:0xf
	v_mul_f32_dpp v118, -v166, v6 quad_perm:[1,1,1,1] row_mask:0xf bank_mask:0xf
	v_mul_f32_dpp v119, -v167, v12 quad_perm:[1,1,1,1] row_mask:0xf bank_mask:0xf
	v_fmac_f32_dpp v116, -v166, v7 quad_perm:[2,2,2,2] row_mask:0xf bank_mask:0xf
	v_fmac_f32_dpp v117, -v167, v13 quad_perm:[2,2,2,2] row_mask:0xf bank_mask:0xf
	v_fmac_f32_dpp v118, -v166, v14 quad_perm:[3,3,3,3] row_mask:0xf bank_mask:0xf
	v_fmac_f32_dpp v119, -v167, v15 quad_perm:[3,3,3,3] row_mask:0xf bank_mask:0xf
	v_fmac_f32_dpp v116, -v168, v16 quad_perm:[0,0,0,0] row_mask:0xf bank_mask:0xf
	v_fmac_f32_dpp v117, -v169, v17 quad_perm:[0,0,0,0] row_mask:0xf bank_mask:0xf
	v_fmac_f32_dpp v118, -v168, v19 quad_perm:[1,1,1,1] row_mask:0xf bank_mask:0xf
	v_fmac_f32_dpp v119, -v169, v20 quad_perm:[1,1,1,1] row_mask:0xf bank_mask:0xf
	v_fmac_f32_dpp v116, -v168, v21 quad_perm:[2,2,2,2] row_mask:0xf bank_mask:0xf
	v_fmac_f32_dpp v117, -v169, v22 quad_perm:[2,2,2,2] row_mask:0xf bank_mask:0xf
	v_fmac_f32_dpp v118, -v168, v23 quad_perm:[3,3,3,3] row_mask:0xf bank_mask:0xf
	v_fmac_f32_dpp v119, -v169, v24 quad_perm:[3,3,3,3] row_mask:0xf bank_mask:0xf
	v_fmac_f32_dpp v116, -v170, v25 quad_perm:[0,0,0,0] row_mask:0xf bank_mask:0xf
	v_fmac_f32_dpp v117, -v171, v27 quad_perm:[0,0,0,0] row_mask:0xf bank_mask:0xf
	v_fmac_f32_dpp v118, -v170, v28 quad_perm:[1,1,1,1] row_mask:0xf bank_mask:0xf
	v_fmac_f32_dpp v119, -v171, v29 quad_perm:[1,1,1,1] row_mask:0xf bank_mask:0xf
	v_fmac_f32_dpp v116, -v170, v30 quad_perm:[2,2,2,2] row_mask:0xf bank_mask:0xf
	v_fmac_f32_dpp v117, -v171, v31 quad_perm:[2,2,2,2] row_mask:0xf bank_mask:0xf
	v_fmac_f32_dpp v118, -v170, v32 quad_perm:[3,3,3,3] row_mask:0xf bank_mask:0xf
	v_fmac_f32_dpp v119, -v171, v33 quad_perm:[3,3,3,3] row_mask:0xf bank_mask:0xf
	v_fmac_f32_dpp v116, -v84, v34 quad_perm:[0,0,0,0] row_mask:0xf bank_mask:0xf
	v_fmac_f32_dpp v117, -v85, v35 quad_perm:[0,0,0,0] row_mask:0xf bank_mask:0xf
	v_fmac_f32_dpp v118, -v84, v36 quad_perm:[1,1,1,1] row_mask:0xf bank_mask:0xf
	v_fmac_f32_dpp v119, -v85, v37 quad_perm:[1,1,1,1] row_mask:0xf bank_mask:0xf
	v_fmac_f32_dpp v116, -v84, v38 quad_perm:[2,2,2,2] row_mask:0xf bank_mask:0xf
	v_fmac_f32_dpp v117, -v85, v39 quad_perm:[2,2,2,2] row_mask:0xf bank_mask:0xf
	v_fmac_f32_dpp v118, -v84, v40 quad_perm:[3,3,3,3] row_mask:0xf bank_mask:0xf
	v_add_f32_e32 v121, v117, v116
	v_add_f32_e32 v122, v118, v119
	v_add_f32_e32 v41, v122, v121
	v_mov_b32_e32 v220, v40
	v_mov_b32_e32 v221, v41
	s_nop 1
	v_permlane32_swap_b32_e32 v220, v221
	s_nop 1
	v_mfma_f32_32x32x2_f32 v[132:147], v229, v220, v[132:147]
	s_nop 1
	v_mfma_f32_32x32x2_f32 v[148:163], v229, v221, v[148:163]
	ds_read_b32 v208, v124 offset:128
	ds_read_u16_d16_hi v252, v123 offset:8704
	ds_read_b64 v[86:87], v125 offset:9104
	ds_read_b32 v209, v124 offset:132
	ds_read_u16_d16_hi v253, v123 offset:8976
	ds_read_b64 v[88:89], v125 offset:9376
	ds_read_b32 v210, v124 offset:136
	ds_read_u16_d16_hi v126, v123 offset:9248
	s_nop 7
	s_nop 7
	s_nop 3
	v_permlane32_swap_b32_e32 v132, v148
	v_permlane32_swap_b32_e32 v133, v149
	v_permlane32_swap_b32_e32 v134, v150
	v_permlane32_swap_b32_e32 v135, v151
	v_permlane32_swap_b32_e32 v136, v152
	v_permlane32_swap_b32_e32 v137, v153
	v_permlane32_swap_b32_e32 v138, v154
	v_permlane32_swap_b32_e32 v139, v155
	v_permlane32_swap_b32_e32 v140, v156
	v_permlane32_swap_b32_e32 v141, v157
	v_permlane32_swap_b32_e32 v142, v158
	v_permlane32_swap_b32_e32 v143, v159
	v_permlane32_swap_b32_e32 v144, v160
	v_permlane32_swap_b32_e32 v145, v161
	v_permlane32_swap_b32_e32 v146, v162
	v_permlane32_swap_b32_e32 v147, v163
	s_waitcnt lgkmcnt(6)
; __device__ __forceinline__ float bf2f(bf16 v) { return __uint_as_float(((unsigned)v) << 16); }
; #define GDN_LOADROW(buf, rr_, i_) do { _Pragma("unroll") for (int j4 = 0; j4 < ((i_) + 3) / 4; ++j4) buf[j4] = *(const f32x4*)(Lm + (i_) * GP_LSTR + 4 * j4); rr_ = bf2f(*(const bf16*)(xsrc + (i_) * GP_STR * 2)) * scl[i_]; } while (0)
; template <int STRIP> __device__ __forceinline__ void ph_gdn_prep_fast(const bf16* __restrict__ proj, const float* __restrict__ small, const float* __restrict__ conv_w, const float* __restrict__ a_log, const float* __restrict__ dt_bias, ...
;     ...
;             f32x4 bA[16], bB[16]; float rA, rB = 0.f;
;             rA = bf2f(*(const bf16*)xsrc) * scl[0];
;     ...
; #pragma unroll
;             for (int i = 0; i < 64; i += 2) {
;                 GDN_LOADROW(bB, rB, i + 1);
;                 GDN_ROW(bA, rA, i);
;                 if (i + 2 < 64) GDN_LOADROW(bA, rA, i + 2);
;                 GDN_ROW(bB, rB, i + 1);
;             }
	v_fma_f32 v116, v208, v252, -v132
	v_add_f32_e32 v42, 0, v116
	s_waitcnt lgkmcnt(3)
	v_fma_f32 v116, v209, v253, -v133
	v_fmac_f32_dpp v116, -v86, v42 quad_perm:[0,0,0,0] row_mask:0xf bank_mask:0xf
	v_add_f32_e32 v43, 0, v116
	s_waitcnt lgkmcnt(0)
	v_fma_f32 v116, v210, v126, -v134
	v_fmac_f32_dpp v116, -v88, v42 quad_perm:[0,0,0,0] row_mask:0xf bank_mask:0xf
	v_mul_f32_dpp v117, -v89, v43 quad_perm:[0,0,0,0] row_mask:0xf bank_mask:0xf
	ds_read_b64 v[90:91], v125 offset:9648
	v_add_f32_e32 v44, v117, v116
	ds_read_b32 v211, v124 offset:140
	ds_read_u16_d16_hi v127, v123 offset:9520
	s_waitcnt lgkmcnt(0)
	v_fma_f32 v116, v211, v127, -v135
	v_fmac_f32_dpp v116, -v90, v42 quad_perm:[0,0,0,0] row_mask:0xf bank_mask:0xf
	v_mul_f32_dpp v117, -v91, v43 quad_perm:[0,0,0,0] row_mask:0xf bank_mask:0xf
	v_mul_f32_dpp v118, -v90, v44 quad_perm:[1,1,1,1] row_mask:0xf bank_mask:0xf
	ds_read_b64 v[92:93], v125 offset:9920
	v_add_f32_e32 v121, v117, v116
	v_add_f32_e32 v45, v118, v121
	ds_read_b32 v212, v124 offset:144
	ds_read_u16_d16_hi v244, v123 offset:9792
	s_waitcnt lgkmcnt(0)
	v_fma_f32 v116, v212, v244, -v148
	v_fmac_f32_dpp v116, -v92, v42 quad_perm:[0,0,0,0] row_mask:0xf bank_mask:0xf
	v_mul_f32_dpp v117, -v93, v43 quad_perm:[0,0,0,0] row_mask:0xf bank_mask:0xf
	v_mul_f32_dpp v118, -v92, v44 quad_perm:[1,1,1,1] row_mask:0xf bank_mask:0xf
	ds_read_b64 v[186:187], v125 offset:10192
	v_mul_f32_dpp v119, -v93, v45 quad_perm:[1,1,1,1] row_mask:0xf bank_mask:0xf
	v_add_f32_e32 v121, v117, v116
	v_add_f32_e32 v122, v118, v119
	v_add_f32_e32 v46, v122, v121
	ds_read_b32 v213, v124 offset:148
	ds_read_u16_d16_hi v245, v123 offset:10064
	s_waitcnt lgkmcnt(0)
	v_fma_f32 v116, v213, v245, -v149
	v_fmac_f32_dpp v116, -v186, v42 quad_perm:[0,0,0,0] row_mask:0xf bank_mask:0xf
	v_mul_f32_dpp v117, -v187, v43 quad_perm:[0,0,0,0] row_mask:0xf bank_mask:0xf
	ds_read_b64 v[188:189], v125 offset:10464
	v_mul_f32_dpp v118, -v186, v44 quad_perm:[1,1,1,1] row_mask:0xf bank_mask:0xf
	v_mul_f32_dpp v119, -v187, v45 quad_perm:[1,1,1,1] row_mask:0xf bank_mask:0xf
	v_fmac_f32_dpp v116, -v186, v46 quad_perm:[2,2,2,2] row_mask:0xf bank_mask:0xf
	ds_read_b32 v214, v124 offset:152
	v_add_f32_e32 v121, v117, v116
	v_add_f32_e32 v122, v118, v119
	v_add_f32_e32 v47, v122, v121
	ds_read_u16_d16_hi v246, v123 offset:10336
	s_waitcnt lgkmcnt(0)
	v_fma_f32 v116, v214, v246, -v150
	v_fmac_f32_dpp v116, -v188, v42 quad_perm:[0,0,0,0] row_mask:0xf bank_mask:0xf
	v_mul_f32_dpp v117, -v189, v43 quad_perm:[0,0,0,0] row_mask:0xf bank_mask:0xf
	v_mul_f32_dpp v118, -v188, v44 quad_perm:[1,1,1,1] row_mask:0xf bank_mask:0xf
	ds_read_b64 v[190:191], v125 offset:10736
	v_mul_f32_dpp v119, -v189, v45 quad_perm:[1,1,1,1] row_mask:0xf bank_mask:0xf
	v_fmac_f32_dpp v116, -v188, v46 quad_perm:[2,2,2,2] row_mask:0xf bank_mask:0xf
	v_fmac_f32_dpp v117, -v189, v47 quad_perm:[2,2,2,2] row_mask:0xf bank_mask:0xf
	ds_read_b32 v215, v124 offset:156
	v_add_f32_e32 v121, v117, v116
	v_add_f32_e32 v122, v118, v119
	v_add_f32_e32 v48, v122, v121
	ds_read_u16_d16_hi v247, v123 offset:10608
	s_waitcnt lgkmcnt(0)
	v_fma_f32 v116, v215, v247, -v151
	v_fmac_f32_dpp v116, -v190, v42 quad_perm:[0,0,0,0] row_mask:0xf bank_mask:0xf
	v_mul_f32_dpp v117, -v191, v43 quad_perm:[0,0,0,0] row_mask:0xf bank_mask:0xf
	v_mul_f32_dpp v118, -v190, v44 quad_perm:[1,1,1,1] row_mask:0xf bank_mask:0xf
	ds_read_b64 v[192:193], v125 offset:11008
	v_mul_f32_dpp v119, -v191, v45 quad_perm:[1,1,1,1] row_mask:0xf bank_mask:0xf
	v_fmac_f32_dpp v116, -v190, v46 quad_perm:[2,2,2,2] row_mask:0xf bank_mask:0xf
	v_fmac_f32_dpp v117, -v191, v47 quad_perm:[2,2,2,2] row_mask:0xf bank_mask:0xf
	ds_read_b32 v216, v124 offset:160
	v_fmac_f32_dpp v118, -v190, v48 quad_perm:[3,3,3,3] row_mask:0xf bank_mask:0xf
	v_add_f32_e32 v121, v117, v116
	v_add_f32_e32 v122, v118, v119
	v_add_f32_e32 v49, v122, v121
	ds_read_u16_d16_hi v248, v123 offset:10880
	s_waitcnt lgkmcnt(0)
	v_fma_f32 v116, v216, v248, -v136
	v_fmac_f32_dpp v116, -v192, v42 quad_perm:[0,0,0,0] row_mask:0xf bank_mask:0xf
	v_mul_f32_dpp v117, -v193, v43 quad_perm:[0,0,0,0] row_mask:0xf bank_mask:0xf
	ds_read_b64 v[194:195], v125 offset:11280
	v_mul_f32_dpp v118, -v192, v44 quad_perm:[1,1,1,1] row_mask:0xf bank_mask:0xf
	v_mul_f32_dpp v119, -v193, v45 quad_perm:[1,1,1,1] row_mask:0xf bank_mask:0xf
	v_fmac_f32_dpp v116, -v192, v46 quad_perm:[2,2,2,2] row_mask:0xf bank_mask:0xf
	ds_read_b64 v[196:197], v125 offset:11312
	v_fmac_f32_dpp v117, -v193, v47 quad_perm:[2,2,2,2] row_mask:0xf bank_mask:0xf
	v_fmac_f32_dpp v118, -v192, v48 quad_perm:[3,3,3,3] row_mask:0xf bank_mask:0xf
	v_fmac_f32_dpp v119, -v193, v49 quad_perm:[3,3,3,3] row_mask:0xf bank_mask:0xf
	ds_read_b32 v217, v124 offset:164
	v_add_f32_e32 v121, v117, v116
	v_add_f32_e32 v122, v118, v119
	v_add_f32_e32 v50, v122, v121
	ds_read_u16_d16_hi v249, v123 offset:11152
	s_waitcnt lgkmcnt(0)
	v_fma_f32 v116, v217, v249, -v137
	v_fmac_f32_dpp v116, -v194, v42 quad_perm:[0,0,0,0] row_mask:0xf bank_mask:0xf
	v_mul_f32_dpp v117, -v195, v43 quad_perm:[0,0,0,0] row_mask:0xf bank_mask:0xf
	v_mul_f32_dpp v118, -v194, v44 quad_perm:[1,1,1,1] row_mask:0xf bank_mask:0xf
	ds_read_b64 v[198:199], v125 offset:11552
	v_mul_f32_dpp v119, -v195, v45 quad_perm:[1,1,1,1] row_mask:0xf bank_mask:0xf
	v_fmac_f32_dpp v116, -v194, v46 quad_perm:[2,2,2,2] row_mask:0xf bank_mask:0xf
	v_fmac_f32_dpp v117, -v195, v47 quad_perm:[2,2,2,2] row_mask:0xf bank_mask:0xf
	ds_read_b64 v[200:201], v125 offset:11584
	v_fmac_f32_dpp v118, -v194, v48 quad_perm:[3,3,3,3] row_mask:0xf bank_mask:0xf
	v_fmac_f32_dpp v119, -v195, v49 quad_perm:[3,3,3,3] row_mask:0xf bank_mask:0xf
	v_fmac_f32_dpp v116, -v196, v50 quad_perm:[0,0,0,0] row_mask:0xf bank_mask:0xf
	ds_read_b32 v218, v124 offset:168
	v_add_f32_e32 v121, v117, v116
	v_add_f32_e32 v122, v118, v119
	v_add_f32_e32 v51, v122, v121
	ds_read_u16_d16_hi v250, v123 offset:11424
	s_waitcnt lgkmcnt(0)
; __device__ __forceinline__ float bf2f(bf16 v) { return __uint_as_float(((unsigned)v) << 16); }
; #define GDN_LOADROW(buf, rr_, i_) do { _Pragma("unroll") for (int j4 = 0; j4 < ((i_) + 3) / 4; ++j4) buf[j4] = *(const f32x4*)(Lm + (i_) * GP_LSTR + 4 * j4); rr_ = bf2f(*(const bf16*)(xsrc + (i_) * GP_STR * 2)) * scl[i_]; } while (0)
; template <int STRIP> __device__ __forceinline__ void ph_gdn_prep_fast(const bf16* __restrict__ proj, const float* __restrict__ small, const float* __restrict__ conv_w, const float* __restrict__ a_log, const float* __restrict__ dt_bias, ...
;     ...
;             f32x4 bA[16], bB[16]; float rA, rB = 0.f;
;             rA = bf2f(*(const bf16*)xsrc) * scl[0];
;     ...
; #pragma unroll
;             for (int i = 0; i < 64; i += 2) {
;                 GDN_LOADROW(bB, rB, i + 1);
;                 GDN_ROW(bA, rA, i);
;                 if (i + 2 < 64) GDN_LOADROW(bA, rA, i + 2);
;                 GDN_ROW(bB, rB, i + 1);
;             }
	v_fma_f32 v116, v218, v250, -v138
	v_fmac_f32_dpp v116, -v198, v42 quad_perm:[0,0,0,0] row_mask:0xf bank_mask:0xf
	v_mul_f32_dpp v117, -v199, v43 quad_perm:[0,0,0,0] row_mask:0xf bank_mask:0xf
	v_mul_f32_dpp v118, -v198, v44 quad_perm:[1,1,1,1] row_mask:0xf bank_mask:0xf
	ds_read_b64 v[202:203], v125 offset:11824
	v_mul_f32_dpp v119, -v199, v45 quad_perm:[1,1,1,1] row_mask:0xf bank_mask:0xf
	v_fmac_f32_dpp v116, -v198, v46 quad_perm:[2,2,2,2] row_mask:0xf bank_mask:0xf
	v_fmac_f32_dpp v117, -v199, v47 quad_perm:[2,2,2,2] row_mask:0xf bank_mask:0xf
	ds_read_b64 v[204:205], v125 offset:11856
	v_fmac_f32_dpp v118, -v198, v48 quad_perm:[3,3,3,3] row_mask:0xf bank_mask:0xf
	v_fmac_f32_dpp v119, -v199, v49 quad_perm:[3,3,3,3] row_mask:0xf bank_mask:0xf
	v_fmac_f32_dpp v116, -v200, v50 quad_perm:[0,0,0,0] row_mask:0xf bank_mask:0xf
	ds_read_b32 v219, v124 offset:172
	v_fmac_f32_dpp v117, -v201, v51 quad_perm:[0,0,0,0] row_mask:0xf bank_mask:0xf
	v_add_f32_e32 v121, v117, v116
	v_add_f32_e32 v122, v118, v119
	v_add_f32_e32 v52, v122, v121
	ds_read_u16_d16_hi v251, v123 offset:11696
	s_waitcnt lgkmcnt(0)
	v_fma_f32 v116, v219, v251, -v139
	v_fmac_f32_dpp v116, -v202, v42 quad_perm:[0,0,0,0] row_mask:0xf bank_mask:0xf
	v_mul_f32_dpp v117, -v203, v43 quad_perm:[0,0,0,0] row_mask:0xf bank_mask:0xf
	ds_read_b64 v[206:207], v125 offset:12096
	v_mul_f32_dpp v118, -v202, v44 quad_perm:[1,1,1,1] row_mask:0xf bank_mask:0xf
	v_mul_f32_dpp v119, -v203, v45 quad_perm:[1,1,1,1] row_mask:0xf bank_mask:0xf
	v_fmac_f32_dpp v116, -v202, v46 quad_perm:[2,2,2,2] row_mask:0xf bank_mask:0xf
	ds_read_b64 v[164:165], v125 offset:12128
	v_fmac_f32_dpp v117, -v203, v47 quad_perm:[2,2,2,2] row_mask:0xf bank_mask:0xf
	v_fmac_f32_dpp v118, -v202, v48 quad_perm:[3,3,3,3] row_mask:0xf bank_mask:0xf
	v_fmac_f32_dpp v119, -v203, v49 quad_perm:[3,3,3,3] row_mask:0xf bank_mask:0xf
	ds_read_b32 v181, v124 offset:176
	v_fmac_f32_dpp v116, -v204, v50 quad_perm:[0,0,0,0] row_mask:0xf bank_mask:0xf
	v_fmac_f32_dpp v117, -v205, v51 quad_perm:[0,0,0,0] row_mask:0xf bank_mask:0xf
	v_fmac_f32_dpp v118, -v204, v52 quad_perm:[1,1,1,1] row_mask:0xf bank_mask:0xf
	ds_read_u16_d16_hi v252, v123 offset:11968
	v_add_f32_e32 v121, v117, v116
	v_add_f32_e32 v122, v118, v119
	v_add_f32_e32 v53, v122, v121
	s_waitcnt lgkmcnt(0)
	v_fma_f32 v116, v181, v252, -v152
	v_fmac_f32_dpp v116, -v206, v42 quad_perm:[0,0,0,0] row_mask:0xf bank_mask:0xf
	v_mul_f32_dpp v117, -v207, v43 quad_perm:[0,0,0,0] row_mask:0xf bank_mask:0xf
	v_mul_f32_dpp v118, -v206, v44 quad_perm:[1,1,1,1] row_mask:0xf bank_mask:0xf
	ds_read_b64 v[166:167], v125 offset:12368
	v_mul_f32_dpp v119, -v207, v45 quad_perm:[1,1,1,1] row_mask:0xf bank_mask:0xf
	v_fmac_f32_dpp v116, -v206, v46 quad_perm:[2,2,2,2] row_mask:0xf bank_mask:0xf
	v_fmac_f32_dpp v117, -v207, v47 quad_perm:[2,2,2,2] row_mask:0xf bank_mask:0xf
	ds_read_b64 v[168:169], v125 offset:12400
	v_fmac_f32_dpp v118, -v206, v48 quad_perm:[3,3,3,3] row_mask:0xf bank_mask:0xf
	v_fmac_f32_dpp v119, -v207, v49 quad_perm:[3,3,3,3] row_mask:0xf bank_mask:0xf
	v_fmac_f32_dpp v116, -v164, v50 quad_perm:[0,0,0,0] row_mask:0xf bank_mask:0xf
	ds_read_b32 v182, v124 offset:180
	v_fmac_f32_dpp v117, -v165, v51 quad_perm:[0,0,0,0] row_mask:0xf bank_mask:0xf
	v_fmac_f32_dpp v118, -v164, v52 quad_perm:[1,1,1,1] row_mask:0xf bank_mask:0xf
	v_fmac_f32_dpp v119, -v165, v53 quad_perm:[1,1,1,1] row_mask:0xf bank_mask:0xf
	ds_read_u16_d16_hi v253, v123 offset:12240
	v_add_f32_e32 v121, v117, v116
	v_add_f32_e32 v122, v118, v119
	v_add_f32_e32 v54, v122, v121
	s_waitcnt lgkmcnt(0)
	v_fma_f32 v116, v182, v253, -v153
	v_fmac_f32_dpp v116, -v166, v42 quad_perm:[0,0,0,0] row_mask:0xf bank_mask:0xf
	v_mul_f32_dpp v117, -v167, v43 quad_perm:[0,0,0,0] row_mask:0xf bank_mask:0xf
	v_mul_f32_dpp v118, -v166, v44 quad_perm:[1,1,1,1] row_mask:0xf bank_mask:0xf
	ds_read_b64 v[170:171], v125 offset:12640
	v_mul_f32_dpp v119, -v167, v45 quad_perm:[1,1,1,1] row_mask:0xf bank_mask:0xf
	v_fmac_f32_dpp v116, -v166, v46 quad_perm:[2,2,2,2] row_mask:0xf bank_mask:0xf
	v_fmac_f32_dpp v117, -v167, v47 quad_perm:[2,2,2,2] row_mask:0xf bank_mask:0xf
	ds_read_b64 v[84:85], v125 offset:12672
	v_fmac_f32_dpp v118, -v166, v48 quad_perm:[3,3,3,3] row_mask:0xf bank_mask:0xf
	v_fmac_f32_dpp v119, -v167, v49 quad_perm:[3,3,3,3] row_mask:0xf bank_mask:0xf
	v_fmac_f32_dpp v116, -v168, v50 quad_perm:[0,0,0,0] row_mask:0xf bank_mask:0xf
	ds_read_b32 v183, v124 offset:184
	v_fmac_f32_dpp v117, -v169, v51 quad_perm:[0,0,0,0] row_mask:0xf bank_mask:0xf
	v_fmac_f32_dpp v118, -v168, v52 quad_perm:[1,1,1,1] row_mask:0xf bank_mask:0xf
	v_fmac_f32_dpp v119, -v169, v53 quad_perm:[1,1,1,1] row_mask:0xf bank_mask:0xf
	ds_read_u16_d16_hi v126, v123 offset:12512
	v_fmac_f32_dpp v116, -v168, v54 quad_perm:[2,2,2,2] row_mask:0xf bank_mask:0xf
	v_add_f32_e32 v121, v117, v116
	v_add_f32_e32 v122, v118, v119
	v_add_f32_e32 v55, v122, v121
	s_waitcnt lgkmcnt(0)
; __device__ __forceinline__ float bf2f(bf16 v) { return __uint_as_float(((unsigned)v) << 16); }
; #define GDN_LOADROW(buf, rr_, i_) do { _Pragma("unroll") for (int j4 = 0; j4 < ((i_) + 3) / 4; ++j4) buf[j4] = *(const f32x4*)(Lm + (i_) * GP_LSTR + 4 * j4); rr_ = bf2f(*(const bf16*)(xsrc + (i_) * GP_STR * 2)) * scl[i_]; } while (0)
; template <int STRIP> __device__ __forceinline__ void ph_gdn_prep_fast(const bf16* __restrict__ proj, const float* __restrict__ small, const float* __restrict__ conv_w, const float* __restrict__ a_log, const float* __restrict__ dt_bias, ...
;     ...
;             f32x4 bA[16], bB[16]; float rA, rB = 0.f;
;             rA = bf2f(*(const bf16*)xsrc) * scl[0];
;     ...
; #pragma unroll
;             for (int i = 0; i < 64; i += 2) {
;                 GDN_LOADROW(bB, rB, i + 1);
;                 GDN_ROW(bA, rA, i);
;                 if (i + 2 < 64) GDN_LOADROW(bA, rA, i + 2);
;                 GDN_ROW(bB, rB, i + 1);
;             }
	v_fma_f32 v116, v183, v126, -v154
	v_fmac_f32_dpp v116, -v170, v42 quad_perm:[0,0,0,0] row_mask:0xf bank_mask:0xf
	v_mul_f32_dpp v117, -v171, v43 quad_perm:[0,0,0,0] row_mask:0xf bank_mask:0xf
	ds_read_b64 v[172:173], v125 offset:12912
	v_mul_f32_dpp v118, -v170, v44 quad_perm:[1,1,1,1] row_mask:0xf bank_mask:0xf
	v_mul_f32_dpp v119, -v171, v45 quad_perm:[1,1,1,1] row_mask:0xf bank_mask:0xf
	v_fmac_f32_dpp v116, -v170, v46 quad_perm:[2,2,2,2] row_mask:0xf bank_mask:0xf
	ds_read_b64 v[174:175], v125 offset:12944
	v_fmac_f32_dpp v117, -v171, v47 quad_perm:[2,2,2,2] row_mask:0xf bank_mask:0xf
	v_fmac_f32_dpp v118, -v170, v48 quad_perm:[3,3,3,3] row_mask:0xf bank_mask:0xf
	v_fmac_f32_dpp v119, -v171, v49 quad_perm:[3,3,3,3] row_mask:0xf bank_mask:0xf
	ds_read_b32 v185, v124 offset:188
	v_fmac_f32_dpp v116, -v84, v50 quad_perm:[0,0,0,0] row_mask:0xf bank_mask:0xf
	v_fmac_f32_dpp v117, -v85, v51 quad_perm:[0,0,0,0] row_mask:0xf bank_mask:0xf
	v_fmac_f32_dpp v118, -v84, v52 quad_perm:[1,1,1,1] row_mask:0xf bank_mask:0xf
	ds_read_u16_d16_hi v127, v123 offset:12784
	v_fmac_f32_dpp v119, -v85, v53 quad_perm:[1,1,1,1] row_mask:0xf bank_mask:0xf
	v_fmac_f32_dpp v116, -v84, v54 quad_perm:[2,2,2,2] row_mask:0xf bank_mask:0xf
	v_fmac_f32_dpp v117, -v85, v55 quad_perm:[2,2,2,2] row_mask:0xf bank_mask:0xf
	ds_read_b64 v[176:177], v125 offset:13184
	v_add_f32_e32 v121, v117, v116
	v_add_f32_e32 v122, v118, v119
	v_add_f32_e32 v56, v122, v121
	s_waitcnt lgkmcnt(1)
	v_fma_f32 v116, v185, v127, -v155
	v_fmac_f32_dpp v116, -v172, v42 quad_perm:[0,0,0,0] row_mask:0xf bank_mask:0xf
	v_mul_f32_dpp v117, -v173, v43 quad_perm:[0,0,0,0] row_mask:0xf bank_mask:0xf
	v_mul_f32_dpp v118, -v172, v44 quad_perm:[1,1,1,1] row_mask:0xf bank_mask:0xf
	ds_read_b64 v[178:179], v125 offset:13216
	v_mul_f32_dpp v119, -v173, v45 quad_perm:[1,1,1,1] row_mask:0xf bank_mask:0xf
	v_fmac_f32_dpp v116, -v172, v46 quad_perm:[2,2,2,2] row_mask:0xf bank_mask:0xf
	v_fmac_f32_dpp v117, -v173, v47 quad_perm:[2,2,2,2] row_mask:0xf bank_mask:0xf
	ds_read_b32 v208, v124 offset:192
	v_fmac_f32_dpp v118, -v172, v48 quad_perm:[3,3,3,3] row_mask:0xf bank_mask:0xf
	v_fmac_f32_dpp v119, -v173, v49 quad_perm:[3,3,3,3] row_mask:0xf bank_mask:0xf
	v_fmac_f32_dpp v116, -v174, v50 quad_perm:[0,0,0,0] row_mask:0xf bank_mask:0xf
	ds_read_u16_d16_hi v244, v123 offset:13056
	v_fmac_f32_dpp v117, -v175, v51 quad_perm:[0,0,0,0] row_mask:0xf bank_mask:0xf
	v_fmac_f32_dpp v118, -v174, v52 quad_perm:[1,1,1,1] row_mask:0xf bank_mask:0xf
	v_fmac_f32_dpp v119, -v175, v53 quad_perm:[1,1,1,1] row_mask:0xf bank_mask:0xf
	ds_read_b64 v[222:223], v125 offset:13456
	v_fmac_f32_dpp v116, -v174, v54 quad_perm:[2,2,2,2] row_mask:0xf bank_mask:0xf
	v_fmac_f32_dpp v117, -v175, v55 quad_perm:[2,2,2,2] row_mask:0xf bank_mask:0xf
	v_fmac_f32_dpp v118, -v174, v56 quad_perm:[3,3,3,3] row_mask:0xf bank_mask:0xf
	ds_read_b64 v[224:225], v125 offset:13488
	v_add_f32_e32 v121, v117, v116
	v_add_f32_e32 v122, v118, v119
	v_add_f32_e32 v57, v122, v121
	s_waitcnt lgkmcnt(2)
	v_fma_f32 v116, v208, v244, -v140
	v_fmac_f32_dpp v116, -v176, v42 quad_perm:[0,0,0,0] row_mask:0xf bank_mask:0xf
	v_mul_f32_dpp v117, -v177, v43 quad_perm:[0,0,0,0] row_mask:0xf bank_mask:0xf
	v_mul_f32_dpp v118, -v176, v44 quad_perm:[1,1,1,1] row_mask:0xf bank_mask:0xf
	ds_read_b64 v[226:227], v125 offset:13520
	v_mul_f32_dpp v119, -v177, v45 quad_perm:[1,1,1,1] row_mask:0xf bank_mask:0xf
	v_fmac_f32_dpp v116, -v176, v46 quad_perm:[2,2,2,2] row_mask:0xf bank_mask:0xf
	v_fmac_f32_dpp v117, -v177, v47 quad_perm:[2,2,2,2] row_mask:0xf bank_mask:0xf
	ds_read_b32 v209, v124 offset:196
	v_fmac_f32_dpp v118, -v176, v48 quad_perm:[3,3,3,3] row_mask:0xf bank_mask:0xf
	v_fmac_f32_dpp v119, -v177, v49 quad_perm:[3,3,3,3] row_mask:0xf bank_mask:0xf
	v_fmac_f32_dpp v116, -v178, v50 quad_perm:[0,0,0,0] row_mask:0xf bank_mask:0xf
	ds_read_u16_d16_hi v245, v123 offset:13328
	v_fmac_f32_dpp v117, -v179, v51 quad_perm:[0,0,0,0] row_mask:0xf bank_mask:0xf
	v_fmac_f32_dpp v118, -v178, v52 quad_perm:[1,1,1,1] row_mask:0xf bank_mask:0xf
	v_fmac_f32_dpp v119, -v179, v53 quad_perm:[1,1,1,1] row_mask:0xf bank_mask:0xf
	ds_read_b64 v[228:229], v125 offset:13728
	v_fmac_f32_dpp v116, -v178, v54 quad_perm:[2,2,2,2] row_mask:0xf bank_mask:0xf
	v_fmac_f32_dpp v117, -v179, v55 quad_perm:[2,2,2,2] row_mask:0xf bank_mask:0xf
	v_fmac_f32_dpp v118, -v178, v56 quad_perm:[3,3,3,3] row_mask:0xf bank_mask:0xf
	ds_read_b64 v[86:87], v125 offset:13760
	v_fmac_f32_dpp v119, -v179, v57 quad_perm:[3,3,3,3] row_mask:0xf bank_mask:0xf
	v_add_f32_e32 v121, v117, v116
	v_add_f32_e32 v122, v118, v119
	v_add_f32_e32 v58, v122, v121
	s_waitcnt lgkmcnt(2)
	v_fma_f32 v116, v209, v245, -v141
	v_fmac_f32_dpp v116, -v222, v42 quad_perm:[0,0,0,0] row_mask:0xf bank_mask:0xf
	v_mul_f32_dpp v117, -v223, v43 quad_perm:[0,0,0,0] row_mask:0xf bank_mask:0xf
	ds_read_b64 v[88:89], v125 offset:13792
	v_mul_f32_dpp v118, -v222, v44 quad_perm:[1,1,1,1] row_mask:0xf bank_mask:0xf
	v_mul_f32_dpp v119, -v223, v45 quad_perm:[1,1,1,1] row_mask:0xf bank_mask:0xf
	v_fmac_f32_dpp v116, -v222, v46 quad_perm:[2,2,2,2] row_mask:0xf bank_mask:0xf
	ds_read_b32 v210, v124 offset:200
	v_fmac_f32_dpp v117, -v223, v47 quad_perm:[2,2,2,2] row_mask:0xf bank_mask:0xf
	v_fmac_f32_dpp v118, -v222, v48 quad_perm:[3,3,3,3] row_mask:0xf bank_mask:0xf
	v_fmac_f32_dpp v119, -v223, v49 quad_perm:[3,3,3,3] row_mask:0xf bank_mask:0xf
	ds_read_u16_d16_hi v246, v123 offset:13600
	v_fmac_f32_dpp v116, -v224, v50 quad_perm:[0,0,0,0] row_mask:0xf bank_mask:0xf
	v_fmac_f32_dpp v117, -v225, v51 quad_perm:[0,0,0,0] row_mask:0xf bank_mask:0xf
	v_fmac_f32_dpp v118, -v224, v52 quad_perm:[1,1,1,1] row_mask:0xf bank_mask:0xf
	ds_read_b64 v[90:91], v125 offset:14000
	v_fmac_f32_dpp v119, -v225, v53 quad_perm:[1,1,1,1] row_mask:0xf bank_mask:0xf
	v_fmac_f32_dpp v116, -v224, v54 quad_perm:[2,2,2,2] row_mask:0xf bank_mask:0xf
	v_fmac_f32_dpp v117, -v225, v55 quad_perm:[2,2,2,2] row_mask:0xf bank_mask:0xf
	ds_read_b64 v[92:93], v125 offset:14032
	v_fmac_f32_dpp v118, -v224, v56 quad_perm:[3,3,3,3] row_mask:0xf bank_mask:0xf
	v_fmac_f32_dpp v119, -v225, v57 quad_perm:[3,3,3,3] row_mask:0xf bank_mask:0xf
	v_fmac_f32_dpp v116, -v226, v58 quad_perm:[0,0,0,0] row_mask:0xf bank_mask:0xf
	ds_read_b64 v[186:187], v125 offset:14064
	v_add_f32_e32 v121, v117, v116
	v_add_f32_e32 v122, v118, v119
	v_add_f32_e32 v59, v122, v121
	s_waitcnt lgkmcnt(3)
; __device__ __forceinline__ float bf2f(bf16 v) { return __uint_as_float(((unsigned)v) << 16); }
; #define GDN_LOADROW(buf, rr_, i_) do { _Pragma("unroll") for (int j4 = 0; j4 < ((i_) + 3) / 4; ++j4) buf[j4] = *(const f32x4*)(Lm + (i_) * GP_LSTR + 4 * j4); rr_ = bf2f(*(const bf16*)(xsrc + (i_) * GP_STR * 2)) * scl[i_]; } while (0)
; template <int STRIP> __device__ __forceinline__ void ph_gdn_prep_fast(const bf16* __restrict__ proj, const float* __restrict__ small, const float* __restrict__ conv_w, const float* __restrict__ a_log, const float* __restrict__ dt_bias, ...
;     ...
;             f32x4 bA[16], bB[16]; float rA, rB = 0.f;
;             rA = bf2f(*(const bf16*)xsrc) * scl[0];
;     ...
; #pragma unroll
;             for (int i = 0; i < 64; i += 2) {
;                 GDN_LOADROW(bB, rB, i + 1);
;                 GDN_ROW(bA, rA, i);
;                 if (i + 2 < 64) GDN_LOADROW(bA, rA, i + 2);
;                 GDN_ROW(bB, rB, i + 1);
;             }
	v_fma_f32 v116, v210, v246, -v142
	v_fmac_f32_dpp v116, -v228, v42 quad_perm:[0,0,0,0] row_mask:0xf bank_mask:0xf
	v_mul_f32_dpp v117, -v229, v43 quad_perm:[0,0,0,0] row_mask:0xf bank_mask:0xf
	v_mul_f32_dpp v118, -v228, v44 quad_perm:[1,1,1,1] row_mask:0xf bank_mask:0xf
	ds_read_b32 v211, v124 offset:204
	v_mul_f32_dpp v119, -v229, v45 quad_perm:[1,1,1,1] row_mask:0xf bank_mask:0xf
	v_fmac_f32_dpp v116, -v228, v46 quad_perm:[2,2,2,2] row_mask:0xf bank_mask:0xf
	v_fmac_f32_dpp v117, -v229, v47 quad_perm:[2,2,2,2] row_mask:0xf bank_mask:0xf
	ds_read_u16_d16_hi v247, v123 offset:13872
	v_fmac_f32_dpp v118, -v228, v48 quad_perm:[3,3,3,3] row_mask:0xf bank_mask:0xf
	v_fmac_f32_dpp v119, -v229, v49 quad_perm:[3,3,3,3] row_mask:0xf bank_mask:0xf
	v_fmac_f32_dpp v116, -v86, v50 quad_perm:[0,0,0,0] row_mask:0xf bank_mask:0xf
	ds_read_b64 v[188:189], v125 offset:14272
	v_fmac_f32_dpp v117, -v87, v51 quad_perm:[0,0,0,0] row_mask:0xf bank_mask:0xf
	v_fmac_f32_dpp v118, -v86, v52 quad_perm:[1,1,1,1] row_mask:0xf bank_mask:0xf
	v_fmac_f32_dpp v119, -v87, v53 quad_perm:[1,1,1,1] row_mask:0xf bank_mask:0xf
	ds_read_b64 v[190:191], v125 offset:14304
	v_fmac_f32_dpp v116, -v86, v54 quad_perm:[2,2,2,2] row_mask:0xf bank_mask:0xf
	v_fmac_f32_dpp v117, -v87, v55 quad_perm:[2,2,2,2] row_mask:0xf bank_mask:0xf
	v_fmac_f32_dpp v118, -v86, v56 quad_perm:[3,3,3,3] row_mask:0xf bank_mask:0xf
	ds_read_b64 v[192:193], v125 offset:14336
	v_fmac_f32_dpp v119, -v87, v57 quad_perm:[3,3,3,3] row_mask:0xf bank_mask:0xf
	v_fmac_f32_dpp v116, -v88, v58 quad_perm:[0,0,0,0] row_mask:0xf bank_mask:0xf
	v_fmac_f32_dpp v117, -v89, v59 quad_perm:[0,0,0,0] row_mask:0xf bank_mask:0xf
	ds_read_b32 v212, v124 offset:208
	v_add_f32_e32 v121, v117, v116
	v_add_f32_e32 v122, v118, v119
	v_add_f32_e32 v60, v122, v121
	s_waitcnt lgkmcnt(4)
	v_fma_f32 v116, v211, v247, -v143
	v_fmac_f32_dpp v116, -v90, v42 quad_perm:[0,0,0,0] row_mask:0xf bank_mask:0xf
	v_mul_f32_dpp v117, -v91, v43 quad_perm:[0,0,0,0] row_mask:0xf bank_mask:0xf
	v_mul_f32_dpp v118, -v90, v44 quad_perm:[1,1,1,1] row_mask:0xf bank_mask:0xf
	ds_read_u16_d16_hi v248, v123 offset:14144
	v_mul_f32_dpp v119, -v91, v45 quad_perm:[1,1,1,1] row_mask:0xf bank_mask:0xf
	v_fmac_f32_dpp v116, -v90, v46 quad_perm:[2,2,2,2] row_mask:0xf bank_mask:0xf
	v_fmac_f32_dpp v117, -v91, v47 quad_perm:[2,2,2,2] row_mask:0xf bank_mask:0xf
	ds_read_b64 v[194:195], v125 offset:14544
	v_fmac_f32_dpp v118, -v90, v48 quad_perm:[3,3,3,3] row_mask:0xf bank_mask:0xf
	v_fmac_f32_dpp v119, -v91, v49 quad_perm:[3,3,3,3] row_mask:0xf bank_mask:0xf
	v_fmac_f32_dpp v116, -v92, v50 quad_perm:[0,0,0,0] row_mask:0xf bank_mask:0xf
	ds_read_b64 v[196:197], v125 offset:14576
	v_fmac_f32_dpp v117, -v93, v51 quad_perm:[0,0,0,0] row_mask:0xf bank_mask:0xf
	v_fmac_f32_dpp v118, -v92, v52 quad_perm:[1,1,1,1] row_mask:0xf bank_mask:0xf
	v_fmac_f32_dpp v119, -v93, v53 quad_perm:[1,1,1,1] row_mask:0xf bank_mask:0xf
	ds_read_b64 v[198:199], v125 offset:14608
	v_fmac_f32_dpp v116, -v92, v54 quad_perm:[2,2,2,2] row_mask:0xf bank_mask:0xf
	v_fmac_f32_dpp v117, -v93, v55 quad_perm:[2,2,2,2] row_mask:0xf bank_mask:0xf
	v_fmac_f32_dpp v118, -v92, v56 quad_perm:[3,3,3,3] row_mask:0xf bank_mask:0xf
	ds_read_b32 v213, v124 offset:212
	v_fmac_f32_dpp v119, -v93, v57 quad_perm:[3,3,3,3] row_mask:0xf bank_mask:0xf
	v_fmac_f32_dpp v116, -v186, v58 quad_perm:[0,0,0,0] row_mask:0xf bank_mask:0xf
	v_fmac_f32_dpp v117, -v187, v59 quad_perm:[0,0,0,0] row_mask:0xf bank_mask:0xf
	ds_read_u16_d16_hi v249, v123 offset:14416
	v_fmac_f32_dpp v118, -v186, v60 quad_perm:[1,1,1,1] row_mask:0xf bank_mask:0xf
	v_add_f32_e32 v121, v117, v116
	v_add_f32_e32 v122, v118, v119
	v_add_f32_e32 v61, v122, v121
	s_waitcnt lgkmcnt(5)
	v_fma_f32 v116, v212, v248, -v156
	v_fmac_f32_dpp v116, -v188, v42 quad_perm:[0,0,0,0] row_mask:0xf bank_mask:0xf
	v_mul_f32_dpp v117, -v189, v43 quad_perm:[0,0,0,0] row_mask:0xf bank_mask:0xf
	ds_read_b64 v[200:201], v125 offset:14816
	v_mul_f32_dpp v118, -v188, v44 quad_perm:[1,1,1,1] row_mask:0xf bank_mask:0xf
	v_mul_f32_dpp v119, -v189, v45 quad_perm:[1,1,1,1] row_mask:0xf bank_mask:0xf
	v_fmac_f32_dpp v116, -v188, v46 quad_perm:[2,2,2,2] row_mask:0xf bank_mask:0xf
	ds_read_b64 v[202:203], v125 offset:14848
	v_fmac_f32_dpp v117, -v189, v47 quad_perm:[2,2,2,2] row_mask:0xf bank_mask:0xf
	v_fmac_f32_dpp v118, -v188, v48 quad_perm:[3,3,3,3] row_mask:0xf bank_mask:0xf
	v_fmac_f32_dpp v119, -v189, v49 quad_perm:[3,3,3,3] row_mask:0xf bank_mask:0xf
	ds_read_b64 v[204:205], v125 offset:14880
	v_fmac_f32_dpp v116, -v190, v50 quad_perm:[0,0,0,0] row_mask:0xf bank_mask:0xf
	v_fmac_f32_dpp v117, -v191, v51 quad_perm:[0,0,0,0] row_mask:0xf bank_mask:0xf
	v_fmac_f32_dpp v118, -v190, v52 quad_perm:[1,1,1,1] row_mask:0xf bank_mask:0xf
	ds_read_b32 v214, v124 offset:216
	v_fmac_f32_dpp v119, -v191, v53 quad_perm:[1,1,1,1] row_mask:0xf bank_mask:0xf
	v_fmac_f32_dpp v116, -v190, v54 quad_perm:[2,2,2,2] row_mask:0xf bank_mask:0xf
	v_fmac_f32_dpp v117, -v191, v55 quad_perm:[2,2,2,2] row_mask:0xf bank_mask:0xf
	ds_read_u16_d16_hi v250, v123 offset:14688
	v_fmac_f32_dpp v118, -v190, v56 quad_perm:[3,3,3,3] row_mask:0xf bank_mask:0xf
	v_fmac_f32_dpp v119, -v191, v57 quad_perm:[3,3,3,3] row_mask:0xf bank_mask:0xf
	v_fmac_f32_dpp v116, -v192, v58 quad_perm:[0,0,0,0] row_mask:0xf bank_mask:0xf
	ds_read_b64 v[206:207], v125 offset:15088
	v_fmac_f32_dpp v117, -v193, v59 quad_perm:[0,0,0,0] row_mask:0xf bank_mask:0xf
	v_fmac_f32_dpp v118, -v192, v60 quad_perm:[1,1,1,1] row_mask:0xf bank_mask:0xf
	v_fmac_f32_dpp v119, -v193, v61 quad_perm:[1,1,1,1] row_mask:0xf bank_mask:0xf
	ds_read_b64 v[164:165], v125 offset:15120
	v_add_f32_e32 v121, v117, v116
	v_add_f32_e32 v122, v118, v119
	v_add_f32_e32 v62, v122, v121
	s_waitcnt lgkmcnt(7)
; __device__ __forceinline__ float bf2f(bf16 v) { return __uint_as_float(((unsigned)v) << 16); }
; #define GDN_LOADROW(buf, rr_, i_) do { _Pragma("unroll") for (int j4 = 0; j4 < ((i_) + 3) / 4; ++j4) buf[j4] = *(const f32x4*)(Lm + (i_) * GP_LSTR + 4 * j4); rr_ = bf2f(*(const bf16*)(xsrc + (i_) * GP_STR * 2)) * scl[i_]; } while (0)
; template <int STRIP> __device__ __forceinline__ void ph_gdn_prep_fast(const bf16* __restrict__ proj, const float* __restrict__ small, const float* __restrict__ conv_w, const float* __restrict__ a_log, const float* __restrict__ dt_bias, ...
;     ...
;             f32x4 bA[16], bB[16]; float rA, rB = 0.f;
;             rA = bf2f(*(const bf16*)xsrc) * scl[0];
;     ...
; #pragma unroll
;             for (int i = 0; i < 64; i += 2) {
;                 GDN_LOADROW(bB, rB, i + 1);
;                 GDN_ROW(bA, rA, i);
;                 if (i + 2 < 64) GDN_LOADROW(bA, rA, i + 2);
;                 GDN_ROW(bB, rB, i + 1);
;             }
	v_fma_f32 v116, v213, v249, -v157
	v_fmac_f32_dpp v116, -v194, v42 quad_perm:[0,0,0,0] row_mask:0xf bank_mask:0xf
	v_mul_f32_dpp v117, -v195, v43 quad_perm:[0,0,0,0] row_mask:0xf bank_mask:0xf
	v_mul_f32_dpp v118, -v194, v44 quad_perm:[1,1,1,1] row_mask:0xf bank_mask:0xf
	ds_read_b64 v[166:167], v125 offset:15152
	v_mul_f32_dpp v119, -v195, v45 quad_perm:[1,1,1,1] row_mask:0xf bank_mask:0xf
	v_fmac_f32_dpp v116, -v194, v46 quad_perm:[2,2,2,2] row_mask:0xf bank_mask:0xf
	v_fmac_f32_dpp v117, -v195, v47 quad_perm:[2,2,2,2] row_mask:0xf bank_mask:0xf
	ds_read_b32 v215, v124 offset:220
	v_fmac_f32_dpp v118, -v194, v48 quad_perm:[3,3,3,3] row_mask:0xf bank_mask:0xf
	v_fmac_f32_dpp v119, -v195, v49 quad_perm:[3,3,3,3] row_mask:0xf bank_mask:0xf
	v_fmac_f32_dpp v116, -v196, v50 quad_perm:[0,0,0,0] row_mask:0xf bank_mask:0xf
	ds_read_u16_d16_hi v251, v123 offset:14960
	v_fmac_f32_dpp v117, -v197, v51 quad_perm:[0,0,0,0] row_mask:0xf bank_mask:0xf
	v_fmac_f32_dpp v118, -v196, v52 quad_perm:[1,1,1,1] row_mask:0xf bank_mask:0xf
	v_fmac_f32_dpp v119, -v197, v53 quad_perm:[1,1,1,1] row_mask:0xf bank_mask:0xf
	ds_read_b64 v[168:169], v125 offset:15360
	v_fmac_f32_dpp v116, -v196, v54 quad_perm:[2,2,2,2] row_mask:0xf bank_mask:0xf
	v_fmac_f32_dpp v117, -v197, v55 quad_perm:[2,2,2,2] row_mask:0xf bank_mask:0xf
	v_fmac_f32_dpp v118, -v196, v56 quad_perm:[3,3,3,3] row_mask:0xf bank_mask:0xf
	ds_read_b64 v[170:171], v125 offset:15392
	v_fmac_f32_dpp v119, -v197, v57 quad_perm:[3,3,3,3] row_mask:0xf bank_mask:0xf
	v_fmac_f32_dpp v116, -v198, v58 quad_perm:[0,0,0,0] row_mask:0xf bank_mask:0xf
	v_fmac_f32_dpp v117, -v199, v59 quad_perm:[0,0,0,0] row_mask:0xf bank_mask:0xf
	ds_read_b64 v[84:85], v125 offset:15424
	v_fmac_f32_dpp v118, -v198, v60 quad_perm:[1,1,1,1] row_mask:0xf bank_mask:0xf
	v_fmac_f32_dpp v119, -v199, v61 quad_perm:[1,1,1,1] row_mask:0xf bank_mask:0xf
	v_fmac_f32_dpp v116, -v198, v62 quad_perm:[2,2,2,2] row_mask:0xf bank_mask:0xf
	ds_read_b32 v216, v124 offset:224
	v_add_f32_e32 v121, v117, v116
	v_add_f32_e32 v122, v118, v119
	v_add_f32_e32 v63, v122, v121
	s_waitcnt lgkmcnt(9)
	v_fma_f32 v116, v214, v250, -v158
	v_fmac_f32_dpp v116, -v200, v42 quad_perm:[0,0,0,0] row_mask:0xf bank_mask:0xf
	v_mul_f32_dpp v117, -v201, v43 quad_perm:[0,0,0,0] row_mask:0xf bank_mask:0xf
	v_mul_f32_dpp v118, -v200, v44 quad_perm:[1,1,1,1] row_mask:0xf bank_mask:0xf
	ds_read_u16_d16_hi v252, v123 offset:15232
	v_mul_f32_dpp v119, -v201, v45 quad_perm:[1,1,1,1] row_mask:0xf bank_mask:0xf
	v_fmac_f32_dpp v116, -v200, v46 quad_perm:[2,2,2,2] row_mask:0xf bank_mask:0xf
	v_fmac_f32_dpp v117, -v201, v47 quad_perm:[2,2,2,2] row_mask:0xf bank_mask:0xf
	ds_read_b64 v[172:173], v125 offset:15632
	v_fmac_f32_dpp v118, -v200, v48 quad_perm:[3,3,3,3] row_mask:0xf bank_mask:0xf
	v_fmac_f32_dpp v119, -v201, v49 quad_perm:[3,3,3,3] row_mask:0xf bank_mask:0xf
	v_fmac_f32_dpp v116, -v202, v50 quad_perm:[0,0,0,0] row_mask:0xf bank_mask:0xf
	ds_read_b64 v[174:175], v125 offset:15664
	v_fmac_f32_dpp v117, -v203, v51 quad_perm:[0,0,0,0] row_mask:0xf bank_mask:0xf
	v_fmac_f32_dpp v118, -v202, v52 quad_perm:[1,1,1,1] row_mask:0xf bank_mask:0xf
	v_fmac_f32_dpp v119, -v203, v53 quad_perm:[1,1,1,1] row_mask:0xf bank_mask:0xf
	ds_read_b64 v[176:177], v125 offset:15696
	v_fmac_f32_dpp v116, -v202, v54 quad_perm:[2,2,2,2] row_mask:0xf bank_mask:0xf
	v_fmac_f32_dpp v117, -v203, v55 quad_perm:[2,2,2,2] row_mask:0xf bank_mask:0xf
	v_fmac_f32_dpp v118, -v202, v56 quad_perm:[3,3,3,3] row_mask:0xf bank_mask:0xf
	ds_read_b64 v[178:179], v125 offset:15728
	v_fmac_f32_dpp v119, -v203, v57 quad_perm:[3,3,3,3] row_mask:0xf bank_mask:0xf
	v_fmac_f32_dpp v116, -v204, v58 quad_perm:[0,0,0,0] row_mask:0xf bank_mask:0xf
	v_fmac_f32_dpp v117, -v205, v59 quad_perm:[0,0,0,0] row_mask:0xf bank_mask:0xf
	ds_read_b32 v217, v124 offset:228
	v_fmac_f32_dpp v118, -v204, v60 quad_perm:[1,1,1,1] row_mask:0xf bank_mask:0xf
	v_fmac_f32_dpp v119, -v205, v61 quad_perm:[1,1,1,1] row_mask:0xf bank_mask:0xf
	v_fmac_f32_dpp v116, -v204, v62 quad_perm:[2,2,2,2] row_mask:0xf bank_mask:0xf
	ds_read_u16_d16_hi v253, v123 offset:15504
	v_fmac_f32_dpp v117, -v205, v63 quad_perm:[2,2,2,2] row_mask:0xf bank_mask:0xf
	v_add_f32_e32 v121, v117, v116
	v_add_f32_e32 v122, v118, v119
	v_add_f32_e32 v64, v122, v121
	s_waitcnt lgkmcnt(11)
	v_fma_f32 v116, v215, v251, -v159
	v_fmac_f32_dpp v116, -v206, v42 quad_perm:[0,0,0,0] row_mask:0xf bank_mask:0xf
	v_mul_f32_dpp v117, -v207, v43 quad_perm:[0,0,0,0] row_mask:0xf bank_mask:0xf
	ds_read_b64 v[222:223], v125 offset:15904
	v_mul_f32_dpp v118, -v206, v44 quad_perm:[1,1,1,1] row_mask:0xf bank_mask:0xf
	v_mul_f32_dpp v119, -v207, v45 quad_perm:[1,1,1,1] row_mask:0xf bank_mask:0xf
	v_fmac_f32_dpp v116, -v206, v46 quad_perm:[2,2,2,2] row_mask:0xf bank_mask:0xf
	ds_read_b64 v[224:225], v125 offset:15936
	v_fmac_f32_dpp v117, -v207, v47 quad_perm:[2,2,2,2] row_mask:0xf bank_mask:0xf
	v_fmac_f32_dpp v118, -v206, v48 quad_perm:[3,3,3,3] row_mask:0xf bank_mask:0xf
	v_fmac_f32_dpp v119, -v207, v49 quad_perm:[3,3,3,3] row_mask:0xf bank_mask:0xf
	ds_read_b64 v[226:227], v125 offset:15968
	v_fmac_f32_dpp v116, -v164, v50 quad_perm:[0,0,0,0] row_mask:0xf bank_mask:0xf
	v_fmac_f32_dpp v117, -v165, v51 quad_perm:[0,0,0,0] row_mask:0xf bank_mask:0xf
	v_fmac_f32_dpp v118, -v164, v52 quad_perm:[1,1,1,1] row_mask:0xf bank_mask:0xf
	ds_read_b64 v[228:229], v125 offset:16000
	v_fmac_f32_dpp v119, -v165, v53 quad_perm:[1,1,1,1] row_mask:0xf bank_mask:0xf
	v_fmac_f32_dpp v116, -v164, v54 quad_perm:[2,2,2,2] row_mask:0xf bank_mask:0xf
	v_fmac_f32_dpp v117, -v165, v55 quad_perm:[2,2,2,2] row_mask:0xf bank_mask:0xf
	ds_read_b32 v218, v124 offset:232
	v_fmac_f32_dpp v118, -v164, v56 quad_perm:[3,3,3,3] row_mask:0xf bank_mask:0xf
	v_fmac_f32_dpp v119, -v165, v57 quad_perm:[3,3,3,3] row_mask:0xf bank_mask:0xf
	v_fmac_f32_dpp v116, -v166, v58 quad_perm:[0,0,0,0] row_mask:0xf bank_mask:0xf
	ds_read_u16_d16_hi v126, v123 offset:15776
	v_fmac_f32_dpp v117, -v167, v59 quad_perm:[0,0,0,0] row_mask:0xf bank_mask:0xf
	v_fmac_f32_dpp v118, -v166, v60 quad_perm:[1,1,1,1] row_mask:0xf bank_mask:0xf
	v_fmac_f32_dpp v119, -v167, v61 quad_perm:[1,1,1,1] row_mask:0xf bank_mask:0xf
	v_fmac_f32_dpp v116, -v166, v62 quad_perm:[2,2,2,2] row_mask:0xf bank_mask:0xf
	v_fmac_f32_dpp v117, -v167, v63 quad_perm:[2,2,2,2] row_mask:0xf bank_mask:0xf
	v_fmac_f32_dpp v118, -v166, v64 quad_perm:[3,3,3,3] row_mask:0xf bank_mask:0xf
	v_add_f32_e32 v121, v117, v116
	v_add_f32_e32 v122, v118, v119
	v_add_f32_e32 v65, v122, v121
	s_waitcnt lgkmcnt(12)
; __device__ __forceinline__ float bf2f(bf16 v) { return __uint_as_float(((unsigned)v) << 16); }
; #define GDN_LOADROW(buf, rr_, i_) do { _Pragma("unroll") for (int j4 = 0; j4 < ((i_) + 3) / 4; ++j4) buf[j4] = *(const f32x4*)(Lm + (i_) * GP_LSTR + 4 * j4); rr_ = bf2f(*(const bf16*)(xsrc + (i_) * GP_STR * 2)) * scl[i_]; } while (0)
; template <int STRIP> __device__ __forceinline__ void ph_gdn_prep_fast(const bf16* __restrict__ proj, const float* __restrict__ small, const float* __restrict__ conv_w, const float* __restrict__ a_log, const float* __restrict__ dt_bias, ...
;     ...
;             f32x4 bA[16], bB[16]; float rA, rB = 0.f;
;             rA = bf2f(*(const bf16*)xsrc) * scl[0];
;     ...
; #pragma unroll
;             for (int i = 0; i < 64; i += 2) {
;                 GDN_LOADROW(bB, rB, i + 1);
;                 GDN_ROW(bA, rA, i);
;                 if (i + 2 < 64) GDN_LOADROW(bA, rA, i + 2);
;                 GDN_ROW(bB, rB, i + 1);
;             }
	v_fma_f32 v116, v216, v252, -v144
	v_fmac_f32_dpp v116, -v168, v42 quad_perm:[0,0,0,0] row_mask:0xf bank_mask:0xf
	v_mul_f32_dpp v117, -v169, v43 quad_perm:[0,0,0,0] row_mask:0xf bank_mask:0xf
	v_mul_f32_dpp v118, -v168, v44 quad_perm:[1,1,1,1] row_mask:0xf bank_mask:0xf
	ds_read_b64 v[86:87], v125 offset:16176
	v_mul_f32_dpp v119, -v169, v45 quad_perm:[1,1,1,1] row_mask:0xf bank_mask:0xf
	v_fmac_f32_dpp v116, -v168, v46 quad_perm:[2,2,2,2] row_mask:0xf bank_mask:0xf
	v_fmac_f32_dpp v117, -v169, v47 quad_perm:[2,2,2,2] row_mask:0xf bank_mask:0xf
	ds_read_b64 v[88:89], v125 offset:16208
	v_fmac_f32_dpp v118, -v168, v48 quad_perm:[3,3,3,3] row_mask:0xf bank_mask:0xf
	v_fmac_f32_dpp v119, -v169, v49 quad_perm:[3,3,3,3] row_mask:0xf bank_mask:0xf
	v_fmac_f32_dpp v116, -v170, v50 quad_perm:[0,0,0,0] row_mask:0xf bank_mask:0xf
	ds_read_b64 v[90:91], v125 offset:16240
	v_fmac_f32_dpp v117, -v171, v51 quad_perm:[0,0,0,0] row_mask:0xf bank_mask:0xf
	v_fmac_f32_dpp v118, -v170, v52 quad_perm:[1,1,1,1] row_mask:0xf bank_mask:0xf
	v_fmac_f32_dpp v119, -v171, v53 quad_perm:[1,1,1,1] row_mask:0xf bank_mask:0xf
	ds_read_b64 v[92:93], v125 offset:16272
	v_fmac_f32_dpp v116, -v170, v54 quad_perm:[2,2,2,2] row_mask:0xf bank_mask:0xf
	v_fmac_f32_dpp v117, -v171, v55 quad_perm:[2,2,2,2] row_mask:0xf bank_mask:0xf
	v_fmac_f32_dpp v118, -v170, v56 quad_perm:[3,3,3,3] row_mask:0xf bank_mask:0xf
	ds_read_b32 v219, v124 offset:236
	v_fmac_f32_dpp v119, -v171, v57 quad_perm:[3,3,3,3] row_mask:0xf bank_mask:0xf
	v_fmac_f32_dpp v116, -v84, v58 quad_perm:[0,0,0,0] row_mask:0xf bank_mask:0xf
	v_fmac_f32_dpp v117, -v85, v59 quad_perm:[0,0,0,0] row_mask:0xf bank_mask:0xf
	ds_read_u16_d16_hi v127, v123 offset:16048
	v_fmac_f32_dpp v118, -v84, v60 quad_perm:[1,1,1,1] row_mask:0xf bank_mask:0xf
	v_fmac_f32_dpp v119, -v85, v61 quad_perm:[1,1,1,1] row_mask:0xf bank_mask:0xf
	v_fmac_f32_dpp v116, -v84, v62 quad_perm:[2,2,2,2] row_mask:0xf bank_mask:0xf
	v_fmac_f32_dpp v117, -v85, v63 quad_perm:[2,2,2,2] row_mask:0xf bank_mask:0xf
	v_fmac_f32_dpp v118, -v84, v64 quad_perm:[3,3,3,3] row_mask:0xf bank_mask:0xf
	v_fmac_f32_dpp v119, -v85, v65 quad_perm:[3,3,3,3] row_mask:0xf bank_mask:0xf
	v_add_f32_e32 v121, v117, v116
	v_add_f32_e32 v122, v118, v119
	v_add_f32_e32 v66, v122, v121
	s_waitcnt lgkmcnt(12)
	v_fma_f32 v116, v217, v253, -v145
	v_fmac_f32_dpp v116, -v172, v42 quad_perm:[0,0,0,0] row_mask:0xf bank_mask:0xf
	v_mul_f32_dpp v117, -v173, v43 quad_perm:[0,0,0,0] row_mask:0xf bank_mask:0xf
	v_mul_f32_dpp v118, -v172, v44 quad_perm:[1,1,1,1] row_mask:0xf bank_mask:0xf
	ds_read_b64 v[186:187], v125 offset:16448
	v_mul_f32_dpp v119, -v173, v45 quad_perm:[1,1,1,1] row_mask:0xf bank_mask:0xf
	v_fmac_f32_dpp v116, -v172, v46 quad_perm:[2,2,2,2] row_mask:0xf bank_mask:0xf
	v_fmac_f32_dpp v117, -v173, v47 quad_perm:[2,2,2,2] row_mask:0xf bank_mask:0xf
	ds_read_b64 v[188:189], v125 offset:16480
	v_fmac_f32_dpp v118, -v172, v48 quad_perm:[3,3,3,3] row_mask:0xf bank_mask:0xf
	v_fmac_f32_dpp v119, -v173, v49 quad_perm:[3,3,3,3] row_mask:0xf bank_mask:0xf
	v_fmac_f32_dpp v116, -v174, v50 quad_perm:[0,0,0,0] row_mask:0xf bank_mask:0xf
	ds_read_b64 v[190:191], v125 offset:16512
	v_fmac_f32_dpp v117, -v175, v51 quad_perm:[0,0,0,0] row_mask:0xf bank_mask:0xf
	v_fmac_f32_dpp v118, -v174, v52 quad_perm:[1,1,1,1] row_mask:0xf bank_mask:0xf
	v_fmac_f32_dpp v119, -v175, v53 quad_perm:[1,1,1,1] row_mask:0xf bank_mask:0xf
	ds_read_b64 v[192:193], v125 offset:16544
	v_fmac_f32_dpp v116, -v174, v54 quad_perm:[2,2,2,2] row_mask:0xf bank_mask:0xf
	v_fmac_f32_dpp v117, -v175, v55 quad_perm:[2,2,2,2] row_mask:0xf bank_mask:0xf
	v_fmac_f32_dpp v118, -v174, v56 quad_perm:[3,3,3,3] row_mask:0xf bank_mask:0xf
	ds_read_b32 v181, v124 offset:240
	v_fmac_f32_dpp v119, -v175, v57 quad_perm:[3,3,3,3] row_mask:0xf bank_mask:0xf
	v_fmac_f32_dpp v116, -v176, v58 quad_perm:[0,0,0,0] row_mask:0xf bank_mask:0xf
	v_fmac_f32_dpp v117, -v177, v59 quad_perm:[0,0,0,0] row_mask:0xf bank_mask:0xf
	ds_read_u16_d16_hi v244, v123 offset:16320
	v_fmac_f32_dpp v118, -v176, v60 quad_perm:[1,1,1,1] row_mask:0xf bank_mask:0xf
	v_fmac_f32_dpp v119, -v177, v61 quad_perm:[1,1,1,1] row_mask:0xf bank_mask:0xf
	v_fmac_f32_dpp v116, -v176, v62 quad_perm:[2,2,2,2] row_mask:0xf bank_mask:0xf
	v_fmac_f32_dpp v117, -v177, v63 quad_perm:[2,2,2,2] row_mask:0xf bank_mask:0xf
	v_fmac_f32_dpp v118, -v176, v64 quad_perm:[3,3,3,3] row_mask:0xf bank_mask:0xf
	v_fmac_f32_dpp v119, -v177, v65 quad_perm:[3,3,3,3] row_mask:0xf bank_mask:0xf
	v_fmac_f32_dpp v116, -v178, v66 quad_perm:[0,0,0,0] row_mask:0xf bank_mask:0xf
	v_add_f32_e32 v121, v117, v116
	v_add_f32_e32 v122, v118, v119
	v_add_f32_e32 v67, v122, v121
	s_waitcnt lgkmcnt(12)
; __device__ __forceinline__ float bf2f(bf16 v) { return __uint_as_float(((unsigned)v) << 16); }
; #define GDN_LOADROW(buf, rr_, i_) do { _Pragma("unroll") for (int j4 = 0; j4 < ((i_) + 3) / 4; ++j4) buf[j4] = *(const f32x4*)(Lm + (i_) * GP_LSTR + 4 * j4); rr_ = bf2f(*(const bf16*)(xsrc + (i_) * GP_STR * 2)) * scl[i_]; } while (0)
; template <int STRIP> __device__ __forceinline__ void ph_gdn_prep_fast(const bf16* __restrict__ proj, const float* __restrict__ small, const float* __restrict__ conv_w, const float* __restrict__ a_log, const float* __restrict__ dt_bias, ...
;     ...
;             f32x4 bA[16], bB[16]; float rA, rB = 0.f;
;             rA = bf2f(*(const bf16*)xsrc) * scl[0];
;     ...
; #pragma unroll
;             for (int i = 0; i < 64; i += 2) {
;                 GDN_LOADROW(bB, rB, i + 1);
;                 GDN_ROW(bA, rA, i);
;                 if (i + 2 < 64) GDN_LOADROW(bA, rA, i + 2);
;                 GDN_ROW(bB, rB, i + 1);
;             }
	v_fma_f32 v116, v218, v126, -v146
	v_fmac_f32_dpp v116, -v222, v42 quad_perm:[0,0,0,0] row_mask:0xf bank_mask:0xf
	v_mul_f32_dpp v117, -v223, v43 quad_perm:[0,0,0,0] row_mask:0xf bank_mask:0xf
	ds_read_b64 v[194:195], v125 offset:16720
	v_mul_f32_dpp v118, -v222, v44 quad_perm:[1,1,1,1] row_mask:0xf bank_mask:0xf
	v_mul_f32_dpp v119, -v223, v45 quad_perm:[1,1,1,1] row_mask:0xf bank_mask:0xf
	v_fmac_f32_dpp v116, -v222, v46 quad_perm:[2,2,2,2] row_mask:0xf bank_mask:0xf
	ds_read_b64 v[196:197], v125 offset:16752
	v_fmac_f32_dpp v117, -v223, v47 quad_perm:[2,2,2,2] row_mask:0xf bank_mask:0xf
	v_fmac_f32_dpp v118, -v222, v48 quad_perm:[3,3,3,3] row_mask:0xf bank_mask:0xf
	v_fmac_f32_dpp v119, -v223, v49 quad_perm:[3,3,3,3] row_mask:0xf bank_mask:0xf
	ds_read_b64 v[198:199], v125 offset:16784
	v_fmac_f32_dpp v116, -v224, v50 quad_perm:[0,0,0,0] row_mask:0xf bank_mask:0xf
	v_fmac_f32_dpp v117, -v225, v51 quad_perm:[0,0,0,0] row_mask:0xf bank_mask:0xf
	v_fmac_f32_dpp v118, -v224, v52 quad_perm:[1,1,1,1] row_mask:0xf bank_mask:0xf
	ds_read_b64 v[200:201], v125 offset:16816
	v_fmac_f32_dpp v119, -v225, v53 quad_perm:[1,1,1,1] row_mask:0xf bank_mask:0xf
	v_fmac_f32_dpp v116, -v224, v54 quad_perm:[2,2,2,2] row_mask:0xf bank_mask:0xf
	v_fmac_f32_dpp v117, -v225, v55 quad_perm:[2,2,2,2] row_mask:0xf bank_mask:0xf
	ds_read_b32 v182, v124 offset:244
	v_fmac_f32_dpp v118, -v224, v56 quad_perm:[3,3,3,3] row_mask:0xf bank_mask:0xf
	v_fmac_f32_dpp v119, -v225, v57 quad_perm:[3,3,3,3] row_mask:0xf bank_mask:0xf
	v_fmac_f32_dpp v116, -v226, v58 quad_perm:[0,0,0,0] row_mask:0xf bank_mask:0xf
	ds_read_u16_d16_hi v245, v123 offset:16592
	v_fmac_f32_dpp v117, -v227, v59 quad_perm:[0,0,0,0] row_mask:0xf bank_mask:0xf
	v_fmac_f32_dpp v118, -v226, v60 quad_perm:[1,1,1,1] row_mask:0xf bank_mask:0xf
	v_fmac_f32_dpp v119, -v227, v61 quad_perm:[1,1,1,1] row_mask:0xf bank_mask:0xf
	v_fmac_f32_dpp v116, -v226, v62 quad_perm:[2,2,2,2] row_mask:0xf bank_mask:0xf
	v_fmac_f32_dpp v117, -v227, v63 quad_perm:[2,2,2,2] row_mask:0xf bank_mask:0xf
	v_fmac_f32_dpp v118, -v226, v64 quad_perm:[3,3,3,3] row_mask:0xf bank_mask:0xf
	v_fmac_f32_dpp v119, -v227, v65 quad_perm:[3,3,3,3] row_mask:0xf bank_mask:0xf
	v_fmac_f32_dpp v116, -v228, v66 quad_perm:[0,0,0,0] row_mask:0xf bank_mask:0xf
	v_fmac_f32_dpp v117, -v229, v67 quad_perm:[0,0,0,0] row_mask:0xf bank_mask:0xf
	v_add_f32_e32 v121, v117, v116
	v_add_f32_e32 v122, v118, v119
	v_add_f32_e32 v68, v122, v121
	s_waitcnt lgkmcnt(12)
	v_fma_f32 v116, v219, v127, -v147
	v_fmac_f32_dpp v116, -v86, v42 quad_perm:[0,0,0,0] row_mask:0xf bank_mask:0xf
	v_mul_f32_dpp v117, -v87, v43 quad_perm:[0,0,0,0] row_mask:0xf bank_mask:0xf
	v_mul_f32_dpp v118, -v86, v44 quad_perm:[1,1,1,1] row_mask:0xf bank_mask:0xf
	ds_read_b64 v[202:203], v125 offset:16992
	v_mul_f32_dpp v119, -v87, v45 quad_perm:[1,1,1,1] row_mask:0xf bank_mask:0xf
	v_fmac_f32_dpp v116, -v86, v46 quad_perm:[2,2,2,2] row_mask:0xf bank_mask:0xf
	v_fmac_f32_dpp v117, -v87, v47 quad_perm:[2,2,2,2] row_mask:0xf bank_mask:0xf
	ds_read_b64 v[204:205], v125 offset:17024
	v_fmac_f32_dpp v118, -v86, v48 quad_perm:[3,3,3,3] row_mask:0xf bank_mask:0xf
	v_fmac_f32_dpp v119, -v87, v49 quad_perm:[3,3,3,3] row_mask:0xf bank_mask:0xf
	v_fmac_f32_dpp v116, -v88, v50 quad_perm:[0,0,0,0] row_mask:0xf bank_mask:0xf
	ds_read_b64 v[206:207], v125 offset:17056
	v_fmac_f32_dpp v117, -v89, v51 quad_perm:[0,0,0,0] row_mask:0xf bank_mask:0xf
	v_fmac_f32_dpp v118, -v88, v52 quad_perm:[1,1,1,1] row_mask:0xf bank_mask:0xf
	v_fmac_f32_dpp v119, -v89, v53 quad_perm:[1,1,1,1] row_mask:0xf bank_mask:0xf
	ds_read_b64 v[164:165], v125 offset:17088
	v_fmac_f32_dpp v116, -v88, v54 quad_perm:[2,2,2,2] row_mask:0xf bank_mask:0xf
	v_fmac_f32_dpp v117, -v89, v55 quad_perm:[2,2,2,2] row_mask:0xf bank_mask:0xf
	v_fmac_f32_dpp v118, -v88, v56 quad_perm:[3,3,3,3] row_mask:0xf bank_mask:0xf
	ds_read_b32 v183, v124 offset:248
	v_fmac_f32_dpp v119, -v89, v57 quad_perm:[3,3,3,3] row_mask:0xf bank_mask:0xf
	v_fmac_f32_dpp v116, -v90, v58 quad_perm:[0,0,0,0] row_mask:0xf bank_mask:0xf
	v_fmac_f32_dpp v117, -v91, v59 quad_perm:[0,0,0,0] row_mask:0xf bank_mask:0xf
	ds_read_u16_d16_hi v246, v123 offset:16864
	v_fmac_f32_dpp v118, -v90, v60 quad_perm:[1,1,1,1] row_mask:0xf bank_mask:0xf
	v_fmac_f32_dpp v119, -v91, v61 quad_perm:[1,1,1,1] row_mask:0xf bank_mask:0xf
	v_fmac_f32_dpp v116, -v90, v62 quad_perm:[2,2,2,2] row_mask:0xf bank_mask:0xf
	v_fmac_f32_dpp v117, -v91, v63 quad_perm:[2,2,2,2] row_mask:0xf bank_mask:0xf
	v_fmac_f32_dpp v118, -v90, v64 quad_perm:[3,3,3,3] row_mask:0xf bank_mask:0xf
	v_fmac_f32_dpp v119, -v91, v65 quad_perm:[3,3,3,3] row_mask:0xf bank_mask:0xf
	v_fmac_f32_dpp v116, -v92, v66 quad_perm:[0,0,0,0] row_mask:0xf bank_mask:0xf
	v_fmac_f32_dpp v117, -v93, v67 quad_perm:[0,0,0,0] row_mask:0xf bank_mask:0xf
	v_fmac_f32_dpp v118, -v92, v68 quad_perm:[1,1,1,1] row_mask:0xf bank_mask:0xf
	v_add_f32_e32 v121, v117, v116
	v_add_f32_e32 v122, v118, v119
	v_add_f32_e32 v69, v122, v121
	s_waitcnt lgkmcnt(12)
; __device__ __forceinline__ float bf2f(bf16 v) { return __uint_as_float(((unsigned)v) << 16); }
; #define GDN_LOADROW(buf, rr_, i_) do { _Pragma("unroll") for (int j4 = 0; j4 < ((i_) + 3) / 4; ++j4) buf[j4] = *(const f32x4*)(Lm + (i_) * GP_LSTR + 4 * j4); rr_ = bf2f(*(const bf16*)(xsrc + (i_) * GP_STR * 2)) * scl[i_]; } while (0)
; template <int STRIP> __device__ __forceinline__ void ph_gdn_prep_fast(const bf16* __restrict__ proj, const float* __restrict__ small, const float* __restrict__ conv_w, const float* __restrict__ a_log, const float* __restrict__ dt_bias, ...
;     ...
;             f32x4 bA[16], bB[16]; float rA, rB = 0.f;
;             rA = bf2f(*(const bf16*)xsrc) * scl[0];
;     ...
; #pragma unroll
;             for (int i = 0; i < 64; i += 2) {
;                 GDN_LOADROW(bB, rB, i + 1);
;                 GDN_ROW(bA, rA, i);
;                 if (i + 2 < 64) GDN_LOADROW(bA, rA, i + 2);
;                 GDN_ROW(bB, rB, i + 1);
;             }
	v_fma_f32 v116, v181, v244, -v160
	v_fmac_f32_dpp v116, -v186, v42 quad_perm:[0,0,0,0] row_mask:0xf bank_mask:0xf
	v_mul_f32_dpp v117, -v187, v43 quad_perm:[0,0,0,0] row_mask:0xf bank_mask:0xf
	v_mul_f32_dpp v118, -v186, v44 quad_perm:[1,1,1,1] row_mask:0xf bank_mask:0xf
	ds_read_b64 v[166:167], v125 offset:17264
	v_mul_f32_dpp v119, -v187, v45 quad_perm:[1,1,1,1] row_mask:0xf bank_mask:0xf
	v_fmac_f32_dpp v116, -v186, v46 quad_perm:[2,2,2,2] row_mask:0xf bank_mask:0xf
	v_fmac_f32_dpp v117, -v187, v47 quad_perm:[2,2,2,2] row_mask:0xf bank_mask:0xf
	ds_read_b64 v[168:169], v125 offset:17296
	v_fmac_f32_dpp v118, -v186, v48 quad_perm:[3,3,3,3] row_mask:0xf bank_mask:0xf
	v_fmac_f32_dpp v119, -v187, v49 quad_perm:[3,3,3,3] row_mask:0xf bank_mask:0xf
	v_fmac_f32_dpp v116, -v188, v50 quad_perm:[0,0,0,0] row_mask:0xf bank_mask:0xf
	ds_read_b64 v[170:171], v125 offset:17328
	v_fmac_f32_dpp v117, -v189, v51 quad_perm:[0,0,0,0] row_mask:0xf bank_mask:0xf
	v_fmac_f32_dpp v118, -v188, v52 quad_perm:[1,1,1,1] row_mask:0xf bank_mask:0xf
	v_fmac_f32_dpp v119, -v189, v53 quad_perm:[1,1,1,1] row_mask:0xf bank_mask:0xf
	ds_read_b64 v[84:85], v125 offset:17360
	v_fmac_f32_dpp v116, -v188, v54 quad_perm:[2,2,2,2] row_mask:0xf bank_mask:0xf
	v_fmac_f32_dpp v117, -v189, v55 quad_perm:[2,2,2,2] row_mask:0xf bank_mask:0xf
	v_fmac_f32_dpp v118, -v188, v56 quad_perm:[3,3,3,3] row_mask:0xf bank_mask:0xf
	ds_read_b32 v185, v124 offset:252
	v_fmac_f32_dpp v119, -v189, v57 quad_perm:[3,3,3,3] row_mask:0xf bank_mask:0xf
	v_fmac_f32_dpp v116, -v190, v58 quad_perm:[0,0,0,0] row_mask:0xf bank_mask:0xf
	v_fmac_f32_dpp v117, -v191, v59 quad_perm:[0,0,0,0] row_mask:0xf bank_mask:0xf
	ds_read_u16_d16_hi v247, v123 offset:17136
	v_fmac_f32_dpp v118, -v190, v60 quad_perm:[1,1,1,1] row_mask:0xf bank_mask:0xf
	v_fmac_f32_dpp v119, -v191, v61 quad_perm:[1,1,1,1] row_mask:0xf bank_mask:0xf
	v_fmac_f32_dpp v116, -v190, v62 quad_perm:[2,2,2,2] row_mask:0xf bank_mask:0xf
	v_fmac_f32_dpp v117, -v191, v63 quad_perm:[2,2,2,2] row_mask:0xf bank_mask:0xf
	v_fmac_f32_dpp v118, -v190, v64 quad_perm:[3,3,3,3] row_mask:0xf bank_mask:0xf
	v_fmac_f32_dpp v119, -v191, v65 quad_perm:[3,3,3,3] row_mask:0xf bank_mask:0xf
	v_fmac_f32_dpp v116, -v192, v66 quad_perm:[0,0,0,0] row_mask:0xf bank_mask:0xf
	v_fmac_f32_dpp v117, -v193, v67 quad_perm:[0,0,0,0] row_mask:0xf bank_mask:0xf
	v_fmac_f32_dpp v118, -v192, v68 quad_perm:[1,1,1,1] row_mask:0xf bank_mask:0xf
	v_fmac_f32_dpp v119, -v193, v69 quad_perm:[1,1,1,1] row_mask:0xf bank_mask:0xf
	v_add_f32_e32 v121, v117, v116
	v_add_f32_e32 v122, v118, v119
	v_add_f32_e32 v70, v122, v121
	s_waitcnt lgkmcnt(12)
	v_fma_f32 v116, v182, v245, -v161
	v_fmac_f32_dpp v116, -v194, v42 quad_perm:[0,0,0,0] row_mask:0xf bank_mask:0xf
	v_mul_f32_dpp v117, -v195, v43 quad_perm:[0,0,0,0] row_mask:0xf bank_mask:0xf
	v_mul_f32_dpp v118, -v194, v44 quad_perm:[1,1,1,1] row_mask:0xf bank_mask:0xf
	v_mul_f32_dpp v119, -v195, v45 quad_perm:[1,1,1,1] row_mask:0xf bank_mask:0xf
	v_fmac_f32_dpp v116, -v194, v46 quad_perm:[2,2,2,2] row_mask:0xf bank_mask:0xf
	v_fmac_f32_dpp v117, -v195, v47 quad_perm:[2,2,2,2] row_mask:0xf bank_mask:0xf
	v_fmac_f32_dpp v118, -v194, v48 quad_perm:[3,3,3,3] row_mask:0xf bank_mask:0xf
	v_fmac_f32_dpp v119, -v195, v49 quad_perm:[3,3,3,3] row_mask:0xf bank_mask:0xf
	v_fmac_f32_dpp v116, -v196, v50 quad_perm:[0,0,0,0] row_mask:0xf bank_mask:0xf
	v_fmac_f32_dpp v117, -v197, v51 quad_perm:[0,0,0,0] row_mask:0xf bank_mask:0xf
	v_fmac_f32_dpp v118, -v196, v52 quad_perm:[1,1,1,1] row_mask:0xf bank_mask:0xf
	v_fmac_f32_dpp v119, -v197, v53 quad_perm:[1,1,1,1] row_mask:0xf bank_mask:0xf
	v_fmac_f32_dpp v116, -v196, v54 quad_perm:[2,2,2,2] row_mask:0xf bank_mask:0xf
	v_fmac_f32_dpp v117, -v197, v55 quad_perm:[2,2,2,2] row_mask:0xf bank_mask:0xf
	v_fmac_f32_dpp v118, -v196, v56 quad_perm:[3,3,3,3] row_mask:0xf bank_mask:0xf
	v_fmac_f32_dpp v119, -v197, v57 quad_perm:[3,3,3,3] row_mask:0xf bank_mask:0xf
	v_fmac_f32_dpp v116, -v198, v58 quad_perm:[0,0,0,0] row_mask:0xf bank_mask:0xf
	v_fmac_f32_dpp v117, -v199, v59 quad_perm:[0,0,0,0] row_mask:0xf bank_mask:0xf
	v_fmac_f32_dpp v118, -v198, v60 quad_perm:[1,1,1,1] row_mask:0xf bank_mask:0xf
	v_fmac_f32_dpp v119, -v199, v61 quad_perm:[1,1,1,1] row_mask:0xf bank_mask:0xf
	v_fmac_f32_dpp v116, -v198, v62 quad_perm:[2,2,2,2] row_mask:0xf bank_mask:0xf
	v_fmac_f32_dpp v117, -v199, v63 quad_perm:[2,2,2,2] row_mask:0xf bank_mask:0xf
	v_fmac_f32_dpp v118, -v198, v64 quad_perm:[3,3,3,3] row_mask:0xf bank_mask:0xf
	v_fmac_f32_dpp v119, -v199, v65 quad_perm:[3,3,3,3] row_mask:0xf bank_mask:0xf
	v_fmac_f32_dpp v116, -v200, v66 quad_perm:[0,0,0,0] row_mask:0xf bank_mask:0xf
	v_fmac_f32_dpp v117, -v201, v67 quad_perm:[0,0,0,0] row_mask:0xf bank_mask:0xf
	v_fmac_f32_dpp v118, -v200, v68 quad_perm:[1,1,1,1] row_mask:0xf bank_mask:0xf
	v_fmac_f32_dpp v119, -v201, v69 quad_perm:[1,1,1,1] row_mask:0xf bank_mask:0xf
	v_fmac_f32_dpp v116, -v200, v70 quad_perm:[2,2,2,2] row_mask:0xf bank_mask:0xf
	v_add_f32_e32 v121, v117, v116
	v_add_f32_e32 v122, v118, v119
	v_add_f32_e32 v71, v122, v121
	s_waitcnt lgkmcnt(6)
; __device__ __forceinline__ float bf2f(bf16 v) { return __uint_as_float(((unsigned)v) << 16); }
; #define GDN_LOADROW(buf, rr_, i_) do { _Pragma("unroll") for (int j4 = 0; j4 < ((i_) + 3) / 4; ++j4) buf[j4] = *(const f32x4*)(Lm + (i_) * GP_LSTR + 4 * j4); rr_ = bf2f(*(const bf16*)(xsrc + (i_) * GP_STR * 2)) * scl[i_]; } while (0)
; template <int STRIP> __device__ __forceinline__ void ph_gdn_prep_fast(const bf16* __restrict__ proj, const float* __restrict__ small, const float* __restrict__ conv_w, const float* __restrict__ a_log, const float* __restrict__ dt_bias, ...
;     ...
;             f32x4 bA[16], bB[16]; float rA, rB = 0.f;
;             rA = bf2f(*(const bf16*)xsrc) * scl[0];
;     ...
; #pragma unroll
;             for (int i = 0; i < 64; i += 2) {
;                 GDN_LOADROW(bB, rB, i + 1);
;                 GDN_ROW(bA, rA, i);
;                 if (i + 2 < 64) GDN_LOADROW(bA, rA, i + 2);
;                 GDN_ROW(bB, rB, i + 1);
;             }
;     ...
;             if (STRIP == 3) { if (U[63] == 12345.678f) EGL[ci] = U[5]; } else
;             if (!isw) { const int v = cc >> 4, c15 = cc & 15; bf16* dst = UF + ((size_t)ci * 8 + v) * 64 * 16;
	v_fma_f32 v116, v183, v246, -v162
	v_fmac_f32_dpp v116, -v202, v42 quad_perm:[0,0,0,0] row_mask:0xf bank_mask:0xf
	v_mul_f32_dpp v117, -v203, v43 quad_perm:[0,0,0,0] row_mask:0xf bank_mask:0xf
	v_mul_f32_dpp v118, -v202, v44 quad_perm:[1,1,1,1] row_mask:0xf bank_mask:0xf
	v_mul_f32_dpp v119, -v203, v45 quad_perm:[1,1,1,1] row_mask:0xf bank_mask:0xf
	v_fmac_f32_dpp v116, -v202, v46 quad_perm:[2,2,2,2] row_mask:0xf bank_mask:0xf
	v_fmac_f32_dpp v117, -v203, v47 quad_perm:[2,2,2,2] row_mask:0xf bank_mask:0xf
	v_fmac_f32_dpp v118, -v202, v48 quad_perm:[3,3,3,3] row_mask:0xf bank_mask:0xf
	v_fmac_f32_dpp v119, -v203, v49 quad_perm:[3,3,3,3] row_mask:0xf bank_mask:0xf
	v_fmac_f32_dpp v116, -v204, v50 quad_perm:[0,0,0,0] row_mask:0xf bank_mask:0xf
	v_fmac_f32_dpp v117, -v205, v51 quad_perm:[0,0,0,0] row_mask:0xf bank_mask:0xf
	v_fmac_f32_dpp v118, -v204, v52 quad_perm:[1,1,1,1] row_mask:0xf bank_mask:0xf
	v_fmac_f32_dpp v119, -v205, v53 quad_perm:[1,1,1,1] row_mask:0xf bank_mask:0xf
	v_fmac_f32_dpp v116, -v204, v54 quad_perm:[2,2,2,2] row_mask:0xf bank_mask:0xf
	v_fmac_f32_dpp v117, -v205, v55 quad_perm:[2,2,2,2] row_mask:0xf bank_mask:0xf
	v_fmac_f32_dpp v118, -v204, v56 quad_perm:[3,3,3,3] row_mask:0xf bank_mask:0xf
	v_fmac_f32_dpp v119, -v205, v57 quad_perm:[3,3,3,3] row_mask:0xf bank_mask:0xf
	v_fmac_f32_dpp v116, -v206, v58 quad_perm:[0,0,0,0] row_mask:0xf bank_mask:0xf
	v_fmac_f32_dpp v117, -v207, v59 quad_perm:[0,0,0,0] row_mask:0xf bank_mask:0xf
	v_fmac_f32_dpp v118, -v206, v60 quad_perm:[1,1,1,1] row_mask:0xf bank_mask:0xf
	v_fmac_f32_dpp v119, -v207, v61 quad_perm:[1,1,1,1] row_mask:0xf bank_mask:0xf
	v_fmac_f32_dpp v116, -v206, v62 quad_perm:[2,2,2,2] row_mask:0xf bank_mask:0xf
	v_fmac_f32_dpp v117, -v207, v63 quad_perm:[2,2,2,2] row_mask:0xf bank_mask:0xf
	v_fmac_f32_dpp v118, -v206, v64 quad_perm:[3,3,3,3] row_mask:0xf bank_mask:0xf
	v_fmac_f32_dpp v119, -v207, v65 quad_perm:[3,3,3,3] row_mask:0xf bank_mask:0xf
	v_fmac_f32_dpp v116, -v164, v66 quad_perm:[0,0,0,0] row_mask:0xf bank_mask:0xf
	v_fmac_f32_dpp v117, -v165, v67 quad_perm:[0,0,0,0] row_mask:0xf bank_mask:0xf
	v_fmac_f32_dpp v118, -v164, v68 quad_perm:[1,1,1,1] row_mask:0xf bank_mask:0xf
	v_fmac_f32_dpp v119, -v165, v69 quad_perm:[1,1,1,1] row_mask:0xf bank_mask:0xf
	v_fmac_f32_dpp v116, -v164, v70 quad_perm:[2,2,2,2] row_mask:0xf bank_mask:0xf
	v_fmac_f32_dpp v117, -v165, v71 quad_perm:[2,2,2,2] row_mask:0xf bank_mask:0xf
	v_add_f32_e32 v121, v117, v116
	v_add_f32_e32 v122, v118, v119
	v_add_f32_e32 v26, v122, v121
	s_waitcnt lgkmcnt(0)
	v_fma_f32 v116, v185, v247, -v163
	v_fmac_f32_dpp v116, -v166, v42 quad_perm:[0,0,0,0] row_mask:0xf bank_mask:0xf
	v_mul_f32_dpp v117, -v167, v43 quad_perm:[0,0,0,0] row_mask:0xf bank_mask:0xf
	v_mul_f32_dpp v118, -v166, v44 quad_perm:[1,1,1,1] row_mask:0xf bank_mask:0xf
	v_mul_f32_dpp v119, -v167, v45 quad_perm:[1,1,1,1] row_mask:0xf bank_mask:0xf
	v_fmac_f32_dpp v116, -v166, v46 quad_perm:[2,2,2,2] row_mask:0xf bank_mask:0xf
	v_fmac_f32_dpp v117, -v167, v47 quad_perm:[2,2,2,2] row_mask:0xf bank_mask:0xf
	v_fmac_f32_dpp v118, -v166, v48 quad_perm:[3,3,3,3] row_mask:0xf bank_mask:0xf
	v_fmac_f32_dpp v119, -v167, v49 quad_perm:[3,3,3,3] row_mask:0xf bank_mask:0xf
	v_fmac_f32_dpp v116, -v168, v50 quad_perm:[0,0,0,0] row_mask:0xf bank_mask:0xf
	v_fmac_f32_dpp v117, -v169, v51 quad_perm:[0,0,0,0] row_mask:0xf bank_mask:0xf
	v_fmac_f32_dpp v118, -v168, v52 quad_perm:[1,1,1,1] row_mask:0xf bank_mask:0xf
	v_fmac_f32_dpp v119, -v169, v53 quad_perm:[1,1,1,1] row_mask:0xf bank_mask:0xf
	v_fmac_f32_dpp v116, -v168, v54 quad_perm:[2,2,2,2] row_mask:0xf bank_mask:0xf
	v_fmac_f32_dpp v117, -v169, v55 quad_perm:[2,2,2,2] row_mask:0xf bank_mask:0xf
	v_fmac_f32_dpp v118, -v168, v56 quad_perm:[3,3,3,3] row_mask:0xf bank_mask:0xf
	v_fmac_f32_dpp v119, -v169, v57 quad_perm:[3,3,3,3] row_mask:0xf bank_mask:0xf
	v_fmac_f32_dpp v116, -v170, v58 quad_perm:[0,0,0,0] row_mask:0xf bank_mask:0xf
	v_fmac_f32_dpp v117, -v171, v59 quad_perm:[0,0,0,0] row_mask:0xf bank_mask:0xf
	v_fmac_f32_dpp v118, -v170, v60 quad_perm:[1,1,1,1] row_mask:0xf bank_mask:0xf
	v_fmac_f32_dpp v119, -v171, v61 quad_perm:[1,1,1,1] row_mask:0xf bank_mask:0xf
	v_fmac_f32_dpp v116, -v170, v62 quad_perm:[2,2,2,2] row_mask:0xf bank_mask:0xf
	v_fmac_f32_dpp v117, -v171, v63 quad_perm:[2,2,2,2] row_mask:0xf bank_mask:0xf
	v_fmac_f32_dpp v118, -v170, v64 quad_perm:[3,3,3,3] row_mask:0xf bank_mask:0xf
	v_fmac_f32_dpp v119, -v171, v65 quad_perm:[3,3,3,3] row_mask:0xf bank_mask:0xf
	v_fmac_f32_dpp v116, -v84, v66 quad_perm:[0,0,0,0] row_mask:0xf bank_mask:0xf
	v_fmac_f32_dpp v117, -v85, v67 quad_perm:[0,0,0,0] row_mask:0xf bank_mask:0xf
	v_fmac_f32_dpp v118, -v84, v68 quad_perm:[1,1,1,1] row_mask:0xf bank_mask:0xf
	v_fmac_f32_dpp v119, -v85, v69 quad_perm:[1,1,1,1] row_mask:0xf bank_mask:0xf
	v_fmac_f32_dpp v116, -v84, v70 quad_perm:[2,2,2,2] row_mask:0xf bank_mask:0xf
	v_fmac_f32_dpp v117, -v85, v71 quad_perm:[2,2,2,2] row_mask:0xf bank_mask:0xf
	v_fmac_f32_dpp v118, -v84, v26 quad_perm:[3,3,3,3] row_mask:0xf bank_mask:0xf
	v_add_f32_e32 v121, v117, v116
	v_add_f32_e32 v122, v118, v119
	v_add_f32_e32 v72, v122, v121
	v_add_u32_e32 v8, v79, v8
	v_ashrrev_i32_e32 v9, 31, v8
	v_lshlrev_b64 v[8:9], 14, v[8:9]
	v_lshlrev_b32_e32 v73, 4, v78
	s_and_saveexec_b64 s[0:1], vcc
	s_xor_b64 s[0:1], exec, s[0:1]
	s_cbranch_execz .LBB0_1305
; __device__ __forceinline__ bf16 f2bf(float f) { return (bf16)(pk2(f, 0.f) & 0xffffu); }
; __device__ __forceinline__ int gperm(int x) { return (x & ~31) | ((x & 12) << 1) | ((x & 16) >> 2) | (x & 3); }
; template <int STRIP> __device__ __forceinline__ void ph_gdn_prep_fast(const bf16* __restrict__ proj, const float* __restrict__ small, const float* __restrict__ conv_w, const float* __restrict__ a_log, const float* __restrict__ dt_bias, ...
;     ...
;             else { bf16* dst = WP + (size_t)ci * 64 * 128 + gperm(cc);
; #pragma unroll
;                 for (int i = 0; i < 64; ++i) __builtin_nontemporal_store(f2bf(U[i]), dst + i * 128); }
	v_and_b32_e32 v2, 24, v18
	v_lshrrev_b32_e32 v18, 2, v78
	v_and_b32_e32 v18, 4, v18
	v_and_b32_e32 v73, 0x63, v78
	v_or3_b32 v2, v18, v73, v2
	v_lshl_add_u64 v[74:75], s[34:35], 0, v[8:9]
	v_lshlrev_b32_e32 v2, 1, v2
	v_lshl_add_u64 v[74:75], v[74:75], 0, v[2:3]
	v_cvt_pk_bf16_f32 v2, v4, s0
	global_store_short v[74:75], v2, off nt
	v_cvt_pk_bf16_f32 v2, v5, s0
	global_store_short v[74:75], v2, off offset:256 nt
	v_cvt_pk_bf16_f32 v2, v6, s0
	global_store_short v[74:75], v2, off offset:512 nt
	v_cvt_pk_bf16_f32 v2, v12, s0
	global_store_short v[74:75], v2, off offset:768 nt
	v_cvt_pk_bf16_f32 v2, v7, s0
	global_store_short v[74:75], v2, off offset:1024 nt
	v_cvt_pk_bf16_f32 v2, v13, s0
	global_store_short v[74:75], v2, off offset:1280 nt
	v_cvt_pk_bf16_f32 v2, v14, s0
	global_store_short v[74:75], v2, off offset:1536 nt
	v_cvt_pk_bf16_f32 v2, v15, s0
	global_store_short v[74:75], v2, off offset:1792 nt
	v_cvt_pk_bf16_f32 v2, v16, s0
	global_store_short v[74:75], v2, off offset:2048 nt
	v_cvt_pk_bf16_f32 v2, v17, s0
	global_store_short v[74:75], v2, off offset:2304 nt
	v_cvt_pk_bf16_f32 v2, v19, s0
	global_store_short v[74:75], v2, off offset:2560 nt
	v_cvt_pk_bf16_f32 v2, v20, s0
	global_store_short v[74:75], v2, off offset:2816 nt
	v_cvt_pk_bf16_f32 v2, v21, s0
	global_store_short v[74:75], v2, off offset:3072 nt
	v_cvt_pk_bf16_f32 v2, v22, s0
	v_add_co_u32_e32 v4, vcc, s79, v74
	global_store_short v[74:75], v2, off offset:3328 nt
	v_cvt_pk_bf16_f32 v2, v23, s0
	v_addc_co_u32_e32 v5, vcc, 0, v75, vcc
	global_store_short v[74:75], v2, off offset:3584 nt
	v_cvt_pk_bf16_f32 v2, v24, s0
	v_add_co_u32_e32 v6, vcc, s76, v74
	global_store_short v[74:75], v2, off offset:3840 nt
	v_cvt_pk_bf16_f32 v2, v25, s0
	v_addc_co_u32_e32 v7, vcc, 0, v75, vcc
	global_store_short v[6:7], v2, off offset:-4096 nt
	v_cvt_pk_bf16_f32 v2, v27, s0
	global_store_short v[4:5], v2, off offset:256 nt
	v_cvt_pk_bf16_f32 v2, v28, s0
	global_store_short v[4:5], v2, off offset:512 nt
	v_cvt_pk_bf16_f32 v2, v29, s0
	global_store_short v[4:5], v2, off offset:768 nt
	v_cvt_pk_bf16_f32 v2, v30, s0
	global_store_short v[4:5], v2, off offset:1024 nt
	v_cvt_pk_bf16_f32 v2, v31, s0
	global_store_short v[4:5], v2, off offset:1280 nt
	v_cvt_pk_bf16_f32 v2, v32, s0
	global_store_short v[4:5], v2, off offset:1536 nt
	v_cvt_pk_bf16_f32 v2, v33, s0
	global_store_short v[4:5], v2, off offset:1792 nt
	v_cvt_pk_bf16_f32 v2, v34, s0
	global_store_short v[4:5], v2, off offset:2048 nt
	v_cvt_pk_bf16_f32 v2, v35, s0
	global_store_short v[4:5], v2, off offset:2304 nt
	v_cvt_pk_bf16_f32 v2, v36, s0
	global_store_short v[4:5], v2, off offset:2560 nt
	v_cvt_pk_bf16_f32 v2, v37, s0
	global_store_short v[4:5], v2, off offset:2816 nt
	v_cvt_pk_bf16_f32 v2, v38, s0
	global_store_short v[4:5], v2, off offset:3072 nt
	v_cvt_pk_bf16_f32 v2, v39, s0
	global_store_short v[4:5], v2, off offset:3328 nt
	v_cvt_pk_bf16_f32 v2, v40, s0
	global_store_short v[4:5], v2, off offset:3584 nt
	v_cvt_pk_bf16_f32 v2, v41, s0
	global_store_short v[4:5], v2, off offset:3840 nt
	v_cvt_pk_bf16_f32 v2, v42, s0
	global_store_short v[6:7], v2, off nt
	v_cvt_pk_bf16_f32 v2, v43, s0
	global_store_short v[6:7], v2, off offset:256 nt
	v_cvt_pk_bf16_f32 v2, v44, s0
	global_store_short v[6:7], v2, off offset:512 nt
	v_cvt_pk_bf16_f32 v2, v45, s0
	global_store_short v[6:7], v2, off offset:768 nt
	v_cvt_pk_bf16_f32 v2, v46, s0
	global_store_short v[6:7], v2, off offset:1024 nt
	v_cvt_pk_bf16_f32 v2, v47, s0
	global_store_short v[6:7], v2, off offset:1280 nt
	v_cvt_pk_bf16_f32 v2, v48, s0
	global_store_short v[6:7], v2, off offset:1536 nt
	v_cvt_pk_bf16_f32 v2, v49, s0
	global_store_short v[6:7], v2, off offset:1792 nt
	v_cvt_pk_bf16_f32 v2, v50, s0
	global_store_short v[6:7], v2, off offset:2048 nt
	v_cvt_pk_bf16_f32 v2, v51, s0
	global_store_short v[6:7], v2, off offset:2304 nt
	v_cvt_pk_bf16_f32 v2, v52, s0
	global_store_short v[6:7], v2, off offset:2560 nt
	v_cvt_pk_bf16_f32 v2, v53, s0
	global_store_short v[6:7], v2, off offset:2816 nt
	v_cvt_pk_bf16_f32 v2, v54, s0
	global_store_short v[6:7], v2, off offset:3072 nt
	v_cvt_pk_bf16_f32 v2, v55, s0
	global_store_short v[6:7], v2, off offset:3328 nt
	v_cvt_pk_bf16_f32 v2, v56, s0
	s_movk_i32 s2, 0x3000
	global_store_short v[6:7], v2, off offset:3584 nt
	v_cvt_pk_bf16_f32 v2, v57, s0
	v_add_co_u32_e32 v4, vcc, s2, v74
	global_store_short v[6:7], v2, off offset:3840 nt
	v_cvt_pk_bf16_f32 v2, v58, s0
	v_addc_co_u32_e32 v5, vcc, 0, v75, vcc
	global_store_short v[4:5], v2, off nt
	v_cvt_pk_bf16_f32 v2, v59, s0
	global_store_short v[4:5], v2, off offset:256 nt
	v_cvt_pk_bf16_f32 v2, v60, s0
	global_store_short v[4:5], v2, off offset:512 nt
	v_cvt_pk_bf16_f32 v2, v61, s0
	global_store_short v[4:5], v2, off offset:768 nt
	v_cvt_pk_bf16_f32 v2, v62, s0
	global_store_short v[4:5], v2, off offset:1024 nt
	v_cvt_pk_bf16_f32 v2, v63, s0
	global_store_short v[4:5], v2, off offset:1280 nt
	v_cvt_pk_bf16_f32 v2, v64, s0
	global_store_short v[4:5], v2, off offset:1536 nt
	v_cvt_pk_bf16_f32 v2, v65, s0
	global_store_short v[4:5], v2, off offset:1792 nt
	v_cvt_pk_bf16_f32 v2, v66, s0
	global_store_short v[4:5], v2, off offset:2048 nt
	v_cvt_pk_bf16_f32 v2, v67, s0
	global_store_short v[4:5], v2, off offset:2304 nt
	v_cvt_pk_bf16_f32 v2, v68, s0
	global_store_short v[4:5], v2, off offset:2560 nt
	v_cvt_pk_bf16_f32 v2, v69, s0
	global_store_short v[4:5], v2, off offset:2816 nt
	v_cvt_pk_bf16_f32 v2, v70, s0
	global_store_short v[4:5], v2, off offset:3072 nt
	v_cvt_pk_bf16_f32 v2, v71, s0
	global_store_short v[4:5], v2, off offset:3328 nt
	v_cvt_pk_bf16_f32 v2, v26, s0
	global_store_short v[4:5], v2, off offset:3584 nt
	v_cvt_pk_bf16_f32 v2, v72, s0
	global_store_short v[4:5], v2, off offset:3840 nt
	v_lshlrev_b32_e32 v73, 4, v78
